# k25_pv4
# speedup vs baseline: 1.0056x; 1.0014x over previous
; DI void phase_peer_b(const Params& p, int layer, const float* gnext, bool last) {
;     ...
;   for (size_t row = (size_t)blockIdx.x * 4 + wave; row < (size_t)T; row += (size_t)gridDim.x * 4) {
;     const int i0 = ibuf[row * 128 + lane], i1 = ibuf[row * 128 + 64 + lane];
;     const float w0 = wbuf[row * 128 + lane], w1 = wbuf[row * 128 + 64 + lane];
;     float acc[16];
; #pragma unroll
;     for (int i = 0; i < 16; ++i) acc[i] = 0.f;
; #pragma unroll 1
;     for (int bt = 0; bt < 8; ++bt) {
;       u32x4 vr[16];
; #pragma unroll
;       for (int j = 0; j < 16; ++j) {
;         const int e = bt * 16 + j;
;         const int eidx = __builtin_amdgcn_readlane(e < 64 ? i0 : i1, e & 63);
;         vr[j] = *(const u32x4*)(EV + (size_t)eidx * DM + lane * 16);
;       }
; #pragma unroll
;       for (int j = 0; j < 16; ++j) {
;         const int e = bt * 16 + j;
;         const float wj = __int_as_float(__builtin_amdgcn_readlane(__float_as_int(e < 64 ? w0 : w1), e & 63));
; #pragma unroll
;         for (int w = 0; w < 4; ++w) {
;           const f32x2 lo = __builtin_amdgcn_cvt_pk_f32_fp8((int)vr[j][w], false);
;           const f32x2 hi = __builtin_amdgcn_cvt_pk_f32_fp8((int)vr[j][w], true);
;           acc[4 * w] += wj * lo[0]; acc[4 * w + 1] += wj * lo[1]; acc[4 * w + 2] += wj * hi[0]; acc[4 * w + 3] += wj * hi[1];
;         }
.LBB0_501:
	s_or_b64 exec, exec, s[10:11]
	s_add_u32 s58, s68, 0x294a0800
	s_addc_u32 s59, s69, 0
	s_mov_b32 s3, 0
	v_mov_b32_e32 v181, 0
	s_add_u32 s60, s68, 0x2b4b0800
	v_lshl_add_u64 v[192:193], s[2:3], 2, v[180:181]
	s_mov_b64 s[10:11], 0x10080
	s_addc_u32 s61, s69, 0
	v_cmp_gt_u64_e64 s[10:11], s[10:11], v[192:193]
	v_lshlrev_b32_e32 v196, 6, v176
	s_barrier
	s_mov_b64 exec, -1
	v_mbcnt_lo_u32_b32 v165, -1, 0
	v_mbcnt_hi_u32_b32 v165, -1, v165
	v_and_b32_e32 v160, 7, v165
	v_lshlrev_b32_e32 v167, 6, v160
	v_lshlrev_b32_e32 v160, 4, v160
	v_lshrrev_b32_e32 v166, 3, v165
	s_and_b32 s24, s95, 7
	s_lshr_b32 s22, s95, 3
	s_lshr_b32 s23, s70, 3
	s_cmp_ge_u32 s22, s23
	s_cbranch_scc1 .Lpv0_end
	s_lshl_b32 s22, s22, 2
	s_add_u32 s22, s22, s94
	s_lshl_b32 s23, s23, 2
	s_lshl_b32 s25, s24, 21
	s_add_u32 s25, s25, 0x190c0000
	s_add_u32 s14, s68, s25
	s_addc_u32 s15, s69, 0
	s_add_u32 s16, s68, 0x2b4b0800
	s_addc_u32 s17, s69, 0
	s_add_u32 s18, s68, 0x294a0800
	s_addc_u32 s19, s69, 0
	s_lshl_b32 s25, s24, 9
	s_add_u32 s20, s68, s25
	s_addc_u32 s21, s69, 0
	s_mul_i32 s25, s94, 8448
	v_lshrrev_b32_e32 v162, 5, v165
	v_mul_u32_u24_e32 v162, 528, v162
	v_and_b32_e32 v161, 31, v165
	v_lshl_add_u32 v162, v161, 4, v162
	v_add_u32_e32 v162, s25, v162
	v_mul_u32_u24_e32 v163, 528, v166
	v_add_u32_e32 v163, s25, v163
	v_lshlrev_b32_e32 v168, 4, v165
	s_cmpk_ge_u32 s22, 0x2010
	s_cbranch_scc1 .Lpv0_end
	s_lshl_b32 s24, s22, 12
	v_add_u32_e32 v172, s24, v168
	global_load_dwordx4 v[200:203], v172, s[16:17]
	global_load_dwordx4 v[204:207], v172, s[16:17] offset:1024
	global_load_dwordx4 v[208:211], v172, s[16:17] offset:2048
	global_load_dwordx4 v[246:249], v172, s[16:17] offset:3072
	s_waitcnt vmcnt(0)
	ds_write_b128 v162, v[200:203]
	ds_write_b128 v162, v[204:207] offset:1056
	ds_write_b128 v162, v[208:211] offset:2112
	ds_write_b128 v162, v[246:249] offset:3168
	s_waitcnt lgkmcnt(0)
	ds_read_b128 v[16:19], v163
	ds_read_b128 v[20:23], v163 offset:16
	ds_read_b128 v[24:27], v163 offset:32
	ds_read_b128 v[28:31], v163 offset:48
	ds_read_b128 v[32:35], v163 offset:64
	ds_read_b128 v[36:39], v163 offset:80
	ds_read_b128 v[40:43], v163 offset:96
	ds_read_b128 v[44:47], v163 offset:112
	global_load_dwordx4 v[48:51], v172, s[18:19]
	global_load_dwordx4 v[52:55], v172, s[18:19] offset:1024
	global_load_dwordx4 v[56:59], v172, s[18:19] offset:2048
	global_load_dwordx4 v[60:63], v172, s[18:19] offset:3072
	s_waitcnt lgkmcnt(0)
	v_lshl_add_u32 v161, v16, 7, v160
	global_load_dwordx4 v[80:83], v161, s[14:15]
	v_lshl_add_u32 v161, v17, 7, v160
	global_load_dwordx4 v[84:87], v161, s[14:15]
	v_lshl_add_u32 v161, v18, 7, v160
	global_load_dwordx4 v[88:91], v161, s[14:15]
	v_lshl_add_u32 v161, v19, 7, v160
	global_load_dwordx4 v[92:95], v161, s[14:15]
	v_lshl_add_u32 v161, v20, 7, v160
	global_load_dwordx4 v[96:99], v161, s[14:15]
	v_lshl_add_u32 v161, v21, 7, v160
	global_load_dwordx4 v[100:103], v161, s[14:15]
	v_lshl_add_u32 v161, v22, 7, v160
	global_load_dwordx4 v[104:107], v161, s[14:15]
	v_lshl_add_u32 v161, v23, 7, v160
	global_load_dwordx4 v[108:111], v161, s[14:15]
	v_lshl_add_u32 v161, v24, 7, v160
	global_load_dwordx4 v[112:115], v161, s[14:15]
	v_lshl_add_u32 v161, v25, 7, v160
	global_load_dwordx4 v[116:119], v161, s[14:15]
	v_lshl_add_u32 v161, v26, 7, v160
	global_load_dwordx4 v[120:123], v161, s[14:15]
	v_lshl_add_u32 v161, v27, 7, v160
	global_load_dwordx4 v[124:127], v161, s[14:15]
	v_lshl_add_u32 v161, v28, 7, v160
	global_load_dwordx4 v[128:131], v161, s[14:15]
	v_lshl_add_u32 v161, v29, 7, v160
	global_load_dwordx4 v[132:135], v161, s[14:15]
	v_lshl_add_u32 v161, v30, 7, v160
	global_load_dwordx4 v[136:139], v161, s[14:15]
	v_lshl_add_u32 v161, v31, 7, v160
	global_load_dwordx4 v[140:143], v161, s[14:15]
.Lpv0_item:
	v_mov_b32_e32 v164, s22
	v_lshl_add_u32 v164, v164, 3, v166
	v_lshl_add_u32 v164, v164, 12, v167
	v_mov_b32_e32 v0, 0
	v_mov_b32_e32 v1, 0
	v_mov_b32_e32 v2, 0
	v_mov_b32_e32 v3, 0
	v_mov_b32_e32 v4, 0
	v_mov_b32_e32 v5, 0
	v_mov_b32_e32 v6, 0
	v_mov_b32_e32 v7, 0
	v_mov_b32_e32 v8, 0
	v_mov_b32_e32 v9, 0
	v_mov_b32_e32 v10, 0
	v_mov_b32_e32 v11, 0
	v_mov_b32_e32 v12, 0
	v_mov_b32_e32 v13, 0
	v_mov_b32_e32 v14, 0
	v_mov_b32_e32 v15, 0
	s_waitcnt vmcnt(16)
	ds_write_b128 v162, v[48:51] offset:4224
	ds_write_b128 v162, v[52:55] offset:5280
	ds_write_b128 v162, v[56:59] offset:6336
	ds_write_b128 v162, v[60:63] offset:7392
	s_waitcnt lgkmcnt(0)
	ds_read_b128 v[48:51], v163 offset:4224
	ds_read_b128 v[52:55], v163 offset:4240
	ds_read_b128 v[56:59], v163 offset:4256
	ds_read_b128 v[60:63], v163 offset:4272
	ds_read_b128 v[16:19], v163 offset:128
	ds_read_b128 v[20:23], v163 offset:144
	ds_read_b128 v[24:27], v163 offset:160
	ds_read_b128 v[28:31], v163 offset:176
	ds_read_b128 v[64:67], v163 offset:4288
	ds_read_b128 v[68:71], v163 offset:4304
	ds_read_b128 v[72:75], v163 offset:4320
	ds_read_b128 v[76:79], v163 offset:4336
	s_waitcnt lgkmcnt(0)
	s_waitcnt vmcnt(15)
	v_cvt_pk_f32_fp8_e32 v[144:145], v80
	v_cvt_pk_f32_fp8_sdwa v[146:147], v80 src0_sel:WORD_1
	v_cvt_pk_f32_fp8_e32 v[148:149], v81
	v_cvt_pk_f32_fp8_sdwa v[150:151], v81 src0_sel:WORD_1
	v_cvt_pk_f32_fp8_e32 v[152:153], v82
	v_cvt_pk_f32_fp8_sdwa v[154:155], v82 src0_sel:WORD_1
	v_cvt_pk_f32_fp8_e32 v[156:157], v83
	v_cvt_pk_f32_fp8_sdwa v[158:159], v83 src0_sel:WORD_1
	v_fmac_f32_e32 v0, v48, v144
	v_fmac_f32_e32 v1, v48, v145
	v_fmac_f32_e32 v2, v48, v146
	v_fmac_f32_e32 v3, v48, v147
	v_fmac_f32_e32 v4, v48, v148
	v_fmac_f32_e32 v5, v48, v149
	v_fmac_f32_e32 v6, v48, v150
	v_fmac_f32_e32 v7, v48, v151
	v_fmac_f32_e32 v8, v48, v152
	v_fmac_f32_e32 v9, v48, v153
	v_fmac_f32_e32 v10, v48, v154
	v_fmac_f32_e32 v11, v48, v155
	v_fmac_f32_e32 v12, v48, v156
	v_fmac_f32_e32 v13, v48, v157
	v_fmac_f32_e32 v14, v48, v158
	v_fmac_f32_e32 v15, v48, v159
	v_lshl_add_u32 v161, v32, 7, v160
	global_load_dwordx4 v[80:83], v161, s[14:15]
	s_waitcnt vmcnt(15)
; DI void phase_peer_b(const Params& p, int layer, const float* gnext, bool last) {
;     ...
;       for (int j = 0; j < 16; ++j) {
;         const int e = bt * 16 + j;
;         const int eidx = __builtin_amdgcn_readlane(e < 64 ? i0 : i1, e & 63);
;         vr[j] = *(const u32x4*)(EV + (size_t)eidx * DM + lane * 16);
;       }
; #pragma unroll
;       for (int j = 0; j < 16; ++j) {
;         const int e = bt * 16 + j;
;         const float wj = __int_as_float(__builtin_amdgcn_readlane(__float_as_int(e < 64 ? w0 : w1), e & 63));
; #pragma unroll
;         for (int w = 0; w < 4; ++w) {
;           const f32x2 lo = __builtin_amdgcn_cvt_pk_f32_fp8((int)vr[j][w], false);
;           const f32x2 hi = __builtin_amdgcn_cvt_pk_f32_fp8((int)vr[j][w], true);
;           acc[4 * w] += wj * lo[0]; acc[4 * w + 1] += wj * lo[1]; acc[4 * w + 2] += wj * hi[0]; acc[4 * w + 3] += wj * hi[1];
;         }
	v_cvt_pk_f32_fp8_e32 v[144:145], v84
	v_cvt_pk_f32_fp8_sdwa v[146:147], v84 src0_sel:WORD_1
	v_cvt_pk_f32_fp8_e32 v[148:149], v85
	v_cvt_pk_f32_fp8_sdwa v[150:151], v85 src0_sel:WORD_1
	v_cvt_pk_f32_fp8_e32 v[152:153], v86
	v_cvt_pk_f32_fp8_sdwa v[154:155], v86 src0_sel:WORD_1
	v_cvt_pk_f32_fp8_e32 v[156:157], v87
	v_cvt_pk_f32_fp8_sdwa v[158:159], v87 src0_sel:WORD_1
	v_fmac_f32_e32 v0, v49, v144
	v_fmac_f32_e32 v1, v49, v145
	v_fmac_f32_e32 v2, v49, v146
	v_fmac_f32_e32 v3, v49, v147
	v_fmac_f32_e32 v4, v49, v148
	v_fmac_f32_e32 v5, v49, v149
	v_fmac_f32_e32 v6, v49, v150
	v_fmac_f32_e32 v7, v49, v151
	v_fmac_f32_e32 v8, v49, v152
	v_fmac_f32_e32 v9, v49, v153
	v_fmac_f32_e32 v10, v49, v154
	v_fmac_f32_e32 v11, v49, v155
	v_fmac_f32_e32 v12, v49, v156
	v_fmac_f32_e32 v13, v49, v157
	v_fmac_f32_e32 v14, v49, v158
	v_fmac_f32_e32 v15, v49, v159
	v_lshl_add_u32 v161, v33, 7, v160
	global_load_dwordx4 v[84:87], v161, s[14:15]
	s_waitcnt vmcnt(15)
	v_cvt_pk_f32_fp8_e32 v[144:145], v88
	v_cvt_pk_f32_fp8_sdwa v[146:147], v88 src0_sel:WORD_1
	v_cvt_pk_f32_fp8_e32 v[148:149], v89
	v_cvt_pk_f32_fp8_sdwa v[150:151], v89 src0_sel:WORD_1
	v_cvt_pk_f32_fp8_e32 v[152:153], v90
	v_cvt_pk_f32_fp8_sdwa v[154:155], v90 src0_sel:WORD_1
	v_cvt_pk_f32_fp8_e32 v[156:157], v91
	v_cvt_pk_f32_fp8_sdwa v[158:159], v91 src0_sel:WORD_1
	v_fmac_f32_e32 v0, v50, v144
	v_fmac_f32_e32 v1, v50, v145
	v_fmac_f32_e32 v2, v50, v146
	v_fmac_f32_e32 v3, v50, v147
	v_fmac_f32_e32 v4, v50, v148
	v_fmac_f32_e32 v5, v50, v149
	v_fmac_f32_e32 v6, v50, v150
	v_fmac_f32_e32 v7, v50, v151
	v_fmac_f32_e32 v8, v50, v152
	v_fmac_f32_e32 v9, v50, v153
	v_fmac_f32_e32 v10, v50, v154
	v_fmac_f32_e32 v11, v50, v155
	v_fmac_f32_e32 v12, v50, v156
	v_fmac_f32_e32 v13, v50, v157
	v_fmac_f32_e32 v14, v50, v158
	v_fmac_f32_e32 v15, v50, v159
	v_lshl_add_u32 v161, v34, 7, v160
	global_load_dwordx4 v[88:91], v161, s[14:15]
	s_waitcnt vmcnt(15)
	v_cvt_pk_f32_fp8_e32 v[144:145], v92
	v_cvt_pk_f32_fp8_sdwa v[146:147], v92 src0_sel:WORD_1
	v_cvt_pk_f32_fp8_e32 v[148:149], v93
	v_cvt_pk_f32_fp8_sdwa v[150:151], v93 src0_sel:WORD_1
	v_cvt_pk_f32_fp8_e32 v[152:153], v94
	v_cvt_pk_f32_fp8_sdwa v[154:155], v94 src0_sel:WORD_1
	v_cvt_pk_f32_fp8_e32 v[156:157], v95
	v_cvt_pk_f32_fp8_sdwa v[158:159], v95 src0_sel:WORD_1
	v_fmac_f32_e32 v0, v51, v144
	v_fmac_f32_e32 v1, v51, v145
	v_fmac_f32_e32 v2, v51, v146
	v_fmac_f32_e32 v3, v51, v147
	v_fmac_f32_e32 v4, v51, v148
	v_fmac_f32_e32 v5, v51, v149
	v_fmac_f32_e32 v6, v51, v150
	v_fmac_f32_e32 v7, v51, v151
	v_fmac_f32_e32 v8, v51, v152
	v_fmac_f32_e32 v9, v51, v153
	v_fmac_f32_e32 v10, v51, v154
	v_fmac_f32_e32 v11, v51, v155
	v_fmac_f32_e32 v12, v51, v156
	v_fmac_f32_e32 v13, v51, v157
	v_fmac_f32_e32 v14, v51, v158
	v_fmac_f32_e32 v15, v51, v159
	v_lshl_add_u32 v161, v35, 7, v160
	global_load_dwordx4 v[92:95], v161, s[14:15]
	s_waitcnt vmcnt(15)
	v_cvt_pk_f32_fp8_e32 v[144:145], v96
	v_cvt_pk_f32_fp8_sdwa v[146:147], v96 src0_sel:WORD_1
	v_cvt_pk_f32_fp8_e32 v[148:149], v97
	v_cvt_pk_f32_fp8_sdwa v[150:151], v97 src0_sel:WORD_1
	v_cvt_pk_f32_fp8_e32 v[152:153], v98
	v_cvt_pk_f32_fp8_sdwa v[154:155], v98 src0_sel:WORD_1
	v_cvt_pk_f32_fp8_e32 v[156:157], v99
	v_cvt_pk_f32_fp8_sdwa v[158:159], v99 src0_sel:WORD_1
	v_fmac_f32_e32 v0, v52, v144
	v_fmac_f32_e32 v1, v52, v145
	v_fmac_f32_e32 v2, v52, v146
	v_fmac_f32_e32 v3, v52, v147
	v_fmac_f32_e32 v4, v52, v148
	v_fmac_f32_e32 v5, v52, v149
	v_fmac_f32_e32 v6, v52, v150
	v_fmac_f32_e32 v7, v52, v151
	v_fmac_f32_e32 v8, v52, v152
	v_fmac_f32_e32 v9, v52, v153
	v_fmac_f32_e32 v10, v52, v154
	v_fmac_f32_e32 v11, v52, v155
	v_fmac_f32_e32 v12, v52, v156
	v_fmac_f32_e32 v13, v52, v157
	v_fmac_f32_e32 v14, v52, v158
	v_fmac_f32_e32 v15, v52, v159
	v_lshl_add_u32 v161, v36, 7, v160
	global_load_dwordx4 v[96:99], v161, s[14:15]
	s_waitcnt vmcnt(15)
	v_cvt_pk_f32_fp8_e32 v[144:145], v100
	v_cvt_pk_f32_fp8_sdwa v[146:147], v100 src0_sel:WORD_1
	v_cvt_pk_f32_fp8_e32 v[148:149], v101
	v_cvt_pk_f32_fp8_sdwa v[150:151], v101 src0_sel:WORD_1
	v_cvt_pk_f32_fp8_e32 v[152:153], v102
	v_cvt_pk_f32_fp8_sdwa v[154:155], v102 src0_sel:WORD_1
	v_cvt_pk_f32_fp8_e32 v[156:157], v103
	v_cvt_pk_f32_fp8_sdwa v[158:159], v103 src0_sel:WORD_1
	v_fmac_f32_e32 v0, v53, v144
	v_fmac_f32_e32 v1, v53, v145
	v_fmac_f32_e32 v2, v53, v146
	v_fmac_f32_e32 v3, v53, v147
	v_fmac_f32_e32 v4, v53, v148
	v_fmac_f32_e32 v5, v53, v149
	v_fmac_f32_e32 v6, v53, v150
	v_fmac_f32_e32 v7, v53, v151
	v_fmac_f32_e32 v8, v53, v152
	v_fmac_f32_e32 v9, v53, v153
	v_fmac_f32_e32 v10, v53, v154
	v_fmac_f32_e32 v11, v53, v155
	v_fmac_f32_e32 v12, v53, v156
	v_fmac_f32_e32 v13, v53, v157
	v_fmac_f32_e32 v14, v53, v158
	v_fmac_f32_e32 v15, v53, v159
	v_lshl_add_u32 v161, v37, 7, v160
	global_load_dwordx4 v[100:103], v161, s[14:15]
	s_waitcnt vmcnt(15)
	v_cvt_pk_f32_fp8_e32 v[144:145], v104
	v_cvt_pk_f32_fp8_sdwa v[146:147], v104 src0_sel:WORD_1
	v_cvt_pk_f32_fp8_e32 v[148:149], v105
	v_cvt_pk_f32_fp8_sdwa v[150:151], v105 src0_sel:WORD_1
	v_cvt_pk_f32_fp8_e32 v[152:153], v106
	v_cvt_pk_f32_fp8_sdwa v[154:155], v106 src0_sel:WORD_1
	v_cvt_pk_f32_fp8_e32 v[156:157], v107
	v_cvt_pk_f32_fp8_sdwa v[158:159], v107 src0_sel:WORD_1
	v_fmac_f32_e32 v0, v54, v144
	v_fmac_f32_e32 v1, v54, v145
	v_fmac_f32_e32 v2, v54, v146
	v_fmac_f32_e32 v3, v54, v147
	v_fmac_f32_e32 v4, v54, v148
	v_fmac_f32_e32 v5, v54, v149
	v_fmac_f32_e32 v6, v54, v150
	v_fmac_f32_e32 v7, v54, v151
	v_fmac_f32_e32 v8, v54, v152
	v_fmac_f32_e32 v9, v54, v153
	v_fmac_f32_e32 v10, v54, v154
	v_fmac_f32_e32 v11, v54, v155
	v_fmac_f32_e32 v12, v54, v156
	v_fmac_f32_e32 v13, v54, v157
	v_fmac_f32_e32 v14, v54, v158
	v_fmac_f32_e32 v15, v54, v159
	v_lshl_add_u32 v161, v38, 7, v160
	global_load_dwordx4 v[104:107], v161, s[14:15]
	s_waitcnt vmcnt(15)
; DI void phase_peer_b(const Params& p, int layer, const float* gnext, bool last) {
;     ...
;       for (int j = 0; j < 16; ++j) {
;         const int e = bt * 16 + j;
;         const int eidx = __builtin_amdgcn_readlane(e < 64 ? i0 : i1, e & 63);
;         vr[j] = *(const u32x4*)(EV + (size_t)eidx * DM + lane * 16);
;       }
; #pragma unroll
;       for (int j = 0; j < 16; ++j) {
;         const int e = bt * 16 + j;
;         const float wj = __int_as_float(__builtin_amdgcn_readlane(__float_as_int(e < 64 ? w0 : w1), e & 63));
; #pragma unroll
;         for (int w = 0; w < 4; ++w) {
;           const f32x2 lo = __builtin_amdgcn_cvt_pk_f32_fp8((int)vr[j][w], false);
;           const f32x2 hi = __builtin_amdgcn_cvt_pk_f32_fp8((int)vr[j][w], true);
;           acc[4 * w] += wj * lo[0]; acc[4 * w + 1] += wj * lo[1]; acc[4 * w + 2] += wj * hi[0]; acc[4 * w + 3] += wj * hi[1];
;         }
	v_cvt_pk_f32_fp8_e32 v[144:145], v108
	v_cvt_pk_f32_fp8_sdwa v[146:147], v108 src0_sel:WORD_1
	v_cvt_pk_f32_fp8_e32 v[148:149], v109
	v_cvt_pk_f32_fp8_sdwa v[150:151], v109 src0_sel:WORD_1
	v_cvt_pk_f32_fp8_e32 v[152:153], v110
	v_cvt_pk_f32_fp8_sdwa v[154:155], v110 src0_sel:WORD_1
	v_cvt_pk_f32_fp8_e32 v[156:157], v111
	v_cvt_pk_f32_fp8_sdwa v[158:159], v111 src0_sel:WORD_1
	v_fmac_f32_e32 v0, v55, v144
	v_fmac_f32_e32 v1, v55, v145
	v_fmac_f32_e32 v2, v55, v146
	v_fmac_f32_e32 v3, v55, v147
	v_fmac_f32_e32 v4, v55, v148
	v_fmac_f32_e32 v5, v55, v149
	v_fmac_f32_e32 v6, v55, v150
	v_fmac_f32_e32 v7, v55, v151
	v_fmac_f32_e32 v8, v55, v152
	v_fmac_f32_e32 v9, v55, v153
	v_fmac_f32_e32 v10, v55, v154
	v_fmac_f32_e32 v11, v55, v155
	v_fmac_f32_e32 v12, v55, v156
	v_fmac_f32_e32 v13, v55, v157
	v_fmac_f32_e32 v14, v55, v158
	v_fmac_f32_e32 v15, v55, v159
	v_lshl_add_u32 v161, v39, 7, v160
	global_load_dwordx4 v[108:111], v161, s[14:15]
	s_waitcnt vmcnt(15)
	v_cvt_pk_f32_fp8_e32 v[144:145], v112
	v_cvt_pk_f32_fp8_sdwa v[146:147], v112 src0_sel:WORD_1
	v_cvt_pk_f32_fp8_e32 v[148:149], v113
	v_cvt_pk_f32_fp8_sdwa v[150:151], v113 src0_sel:WORD_1
	v_cvt_pk_f32_fp8_e32 v[152:153], v114
	v_cvt_pk_f32_fp8_sdwa v[154:155], v114 src0_sel:WORD_1
	v_cvt_pk_f32_fp8_e32 v[156:157], v115
	v_cvt_pk_f32_fp8_sdwa v[158:159], v115 src0_sel:WORD_1
	v_fmac_f32_e32 v0, v56, v144
	v_fmac_f32_e32 v1, v56, v145
	v_fmac_f32_e32 v2, v56, v146
	v_fmac_f32_e32 v3, v56, v147
	v_fmac_f32_e32 v4, v56, v148
	v_fmac_f32_e32 v5, v56, v149
	v_fmac_f32_e32 v6, v56, v150
	v_fmac_f32_e32 v7, v56, v151
	v_fmac_f32_e32 v8, v56, v152
	v_fmac_f32_e32 v9, v56, v153
	v_fmac_f32_e32 v10, v56, v154
	v_fmac_f32_e32 v11, v56, v155
	v_fmac_f32_e32 v12, v56, v156
	v_fmac_f32_e32 v13, v56, v157
	v_fmac_f32_e32 v14, v56, v158
	v_fmac_f32_e32 v15, v56, v159
	v_lshl_add_u32 v161, v40, 7, v160
	global_load_dwordx4 v[112:115], v161, s[14:15]
	s_waitcnt vmcnt(15)
	v_cvt_pk_f32_fp8_e32 v[144:145], v116
	v_cvt_pk_f32_fp8_sdwa v[146:147], v116 src0_sel:WORD_1
	v_cvt_pk_f32_fp8_e32 v[148:149], v117
	v_cvt_pk_f32_fp8_sdwa v[150:151], v117 src0_sel:WORD_1
	v_cvt_pk_f32_fp8_e32 v[152:153], v118
	v_cvt_pk_f32_fp8_sdwa v[154:155], v118 src0_sel:WORD_1
	v_cvt_pk_f32_fp8_e32 v[156:157], v119
	v_cvt_pk_f32_fp8_sdwa v[158:159], v119 src0_sel:WORD_1
	v_fmac_f32_e32 v0, v57, v144
	v_fmac_f32_e32 v1, v57, v145
	v_fmac_f32_e32 v2, v57, v146
	v_fmac_f32_e32 v3, v57, v147
	v_fmac_f32_e32 v4, v57, v148
	v_fmac_f32_e32 v5, v57, v149
	v_fmac_f32_e32 v6, v57, v150
	v_fmac_f32_e32 v7, v57, v151
	v_fmac_f32_e32 v8, v57, v152
	v_fmac_f32_e32 v9, v57, v153
	v_fmac_f32_e32 v10, v57, v154
	v_fmac_f32_e32 v11, v57, v155
	v_fmac_f32_e32 v12, v57, v156
	v_fmac_f32_e32 v13, v57, v157
	v_fmac_f32_e32 v14, v57, v158
	v_fmac_f32_e32 v15, v57, v159
	v_lshl_add_u32 v161, v41, 7, v160
	global_load_dwordx4 v[116:119], v161, s[14:15]
	s_waitcnt vmcnt(15)
	v_cvt_pk_f32_fp8_e32 v[144:145], v120
	v_cvt_pk_f32_fp8_sdwa v[146:147], v120 src0_sel:WORD_1
	v_cvt_pk_f32_fp8_e32 v[148:149], v121
	v_cvt_pk_f32_fp8_sdwa v[150:151], v121 src0_sel:WORD_1
	v_cvt_pk_f32_fp8_e32 v[152:153], v122
	v_cvt_pk_f32_fp8_sdwa v[154:155], v122 src0_sel:WORD_1
	v_cvt_pk_f32_fp8_e32 v[156:157], v123
	v_cvt_pk_f32_fp8_sdwa v[158:159], v123 src0_sel:WORD_1
	v_fmac_f32_e32 v0, v58, v144
	v_fmac_f32_e32 v1, v58, v145
	v_fmac_f32_e32 v2, v58, v146
	v_fmac_f32_e32 v3, v58, v147
	v_fmac_f32_e32 v4, v58, v148
	v_fmac_f32_e32 v5, v58, v149
	v_fmac_f32_e32 v6, v58, v150
	v_fmac_f32_e32 v7, v58, v151
	v_fmac_f32_e32 v8, v58, v152
	v_fmac_f32_e32 v9, v58, v153
	v_fmac_f32_e32 v10, v58, v154
	v_fmac_f32_e32 v11, v58, v155
	v_fmac_f32_e32 v12, v58, v156
	v_fmac_f32_e32 v13, v58, v157
	v_fmac_f32_e32 v14, v58, v158
	v_fmac_f32_e32 v15, v58, v159
	v_lshl_add_u32 v161, v42, 7, v160
	global_load_dwordx4 v[120:123], v161, s[14:15]
	s_waitcnt vmcnt(15)
	v_cvt_pk_f32_fp8_e32 v[144:145], v124
	v_cvt_pk_f32_fp8_sdwa v[146:147], v124 src0_sel:WORD_1
	v_cvt_pk_f32_fp8_e32 v[148:149], v125
	v_cvt_pk_f32_fp8_sdwa v[150:151], v125 src0_sel:WORD_1
	v_cvt_pk_f32_fp8_e32 v[152:153], v126
	v_cvt_pk_f32_fp8_sdwa v[154:155], v126 src0_sel:WORD_1
	v_cvt_pk_f32_fp8_e32 v[156:157], v127
	v_cvt_pk_f32_fp8_sdwa v[158:159], v127 src0_sel:WORD_1
	v_fmac_f32_e32 v0, v59, v144
	v_fmac_f32_e32 v1, v59, v145
	v_fmac_f32_e32 v2, v59, v146
	v_fmac_f32_e32 v3, v59, v147
	v_fmac_f32_e32 v4, v59, v148
	v_fmac_f32_e32 v5, v59, v149
	v_fmac_f32_e32 v6, v59, v150
	v_fmac_f32_e32 v7, v59, v151
	v_fmac_f32_e32 v8, v59, v152
	v_fmac_f32_e32 v9, v59, v153
	v_fmac_f32_e32 v10, v59, v154
	v_fmac_f32_e32 v11, v59, v155
	v_fmac_f32_e32 v12, v59, v156
	v_fmac_f32_e32 v13, v59, v157
	v_fmac_f32_e32 v14, v59, v158
	v_fmac_f32_e32 v15, v59, v159
	v_lshl_add_u32 v161, v43, 7, v160
	global_load_dwordx4 v[124:127], v161, s[14:15]
	s_waitcnt vmcnt(15)
	v_cvt_pk_f32_fp8_e32 v[144:145], v128
	v_cvt_pk_f32_fp8_sdwa v[146:147], v128 src0_sel:WORD_1
	v_cvt_pk_f32_fp8_e32 v[148:149], v129
	v_cvt_pk_f32_fp8_sdwa v[150:151], v129 src0_sel:WORD_1
	v_cvt_pk_f32_fp8_e32 v[152:153], v130
	v_cvt_pk_f32_fp8_sdwa v[154:155], v130 src0_sel:WORD_1
	v_cvt_pk_f32_fp8_e32 v[156:157], v131
	v_cvt_pk_f32_fp8_sdwa v[158:159], v131 src0_sel:WORD_1
	v_fmac_f32_e32 v0, v60, v144
	v_fmac_f32_e32 v1, v60, v145
	v_fmac_f32_e32 v2, v60, v146
	v_fmac_f32_e32 v3, v60, v147
	v_fmac_f32_e32 v4, v60, v148
	v_fmac_f32_e32 v5, v60, v149
	v_fmac_f32_e32 v6, v60, v150
	v_fmac_f32_e32 v7, v60, v151
	v_fmac_f32_e32 v8, v60, v152
	v_fmac_f32_e32 v9, v60, v153
	v_fmac_f32_e32 v10, v60, v154
	v_fmac_f32_e32 v11, v60, v155
	v_fmac_f32_e32 v12, v60, v156
	v_fmac_f32_e32 v13, v60, v157
	v_fmac_f32_e32 v14, v60, v158
	v_fmac_f32_e32 v15, v60, v159
	v_lshl_add_u32 v161, v44, 7, v160
	global_load_dwordx4 v[128:131], v161, s[14:15]
	s_waitcnt vmcnt(15)
; DI void phase_peer_b(const Params& p, int layer, const float* gnext, bool last) {
;     ...
;       u32x4 vr[16];
; #pragma unroll
;       for (int j = 0; j < 16; ++j) {
;         const int e = bt * 16 + j;
;         const int eidx = __builtin_amdgcn_readlane(e < 64 ? i0 : i1, e & 63);
;         vr[j] = *(const u32x4*)(EV + (size_t)eidx * DM + lane * 16);
;       }
; #pragma unroll
;       for (int j = 0; j < 16; ++j) {
;         const int e = bt * 16 + j;
;         const float wj = __int_as_float(__builtin_amdgcn_readlane(__float_as_int(e < 64 ? w0 : w1), e & 63));
; #pragma unroll
;         for (int w = 0; w < 4; ++w) {
;           const f32x2 lo = __builtin_amdgcn_cvt_pk_f32_fp8((int)vr[j][w], false);
;           const f32x2 hi = __builtin_amdgcn_cvt_pk_f32_fp8((int)vr[j][w], true);
;           acc[4 * w] += wj * lo[0]; acc[4 * w + 1] += wj * lo[1]; acc[4 * w + 2] += wj * hi[0]; acc[4 * w + 3] += wj * hi[1];
;         }
	v_cvt_pk_f32_fp8_e32 v[144:145], v132
	v_cvt_pk_f32_fp8_sdwa v[146:147], v132 src0_sel:WORD_1
	v_cvt_pk_f32_fp8_e32 v[148:149], v133
	v_cvt_pk_f32_fp8_sdwa v[150:151], v133 src0_sel:WORD_1
	v_cvt_pk_f32_fp8_e32 v[152:153], v134
	v_cvt_pk_f32_fp8_sdwa v[154:155], v134 src0_sel:WORD_1
	v_cvt_pk_f32_fp8_e32 v[156:157], v135
	v_cvt_pk_f32_fp8_sdwa v[158:159], v135 src0_sel:WORD_1
	v_fmac_f32_e32 v0, v61, v144
	v_fmac_f32_e32 v1, v61, v145
	v_fmac_f32_e32 v2, v61, v146
	v_fmac_f32_e32 v3, v61, v147
	v_fmac_f32_e32 v4, v61, v148
	v_fmac_f32_e32 v5, v61, v149
	v_fmac_f32_e32 v6, v61, v150
	v_fmac_f32_e32 v7, v61, v151
	v_fmac_f32_e32 v8, v61, v152
	v_fmac_f32_e32 v9, v61, v153
	v_fmac_f32_e32 v10, v61, v154
	v_fmac_f32_e32 v11, v61, v155
	v_fmac_f32_e32 v12, v61, v156
	v_fmac_f32_e32 v13, v61, v157
	v_fmac_f32_e32 v14, v61, v158
	v_fmac_f32_e32 v15, v61, v159
	v_lshl_add_u32 v161, v45, 7, v160
	global_load_dwordx4 v[132:135], v161, s[14:15]
	s_waitcnt vmcnt(15)
	v_cvt_pk_f32_fp8_e32 v[144:145], v136
	v_cvt_pk_f32_fp8_sdwa v[146:147], v136 src0_sel:WORD_1
	v_cvt_pk_f32_fp8_e32 v[148:149], v137
	v_cvt_pk_f32_fp8_sdwa v[150:151], v137 src0_sel:WORD_1
	v_cvt_pk_f32_fp8_e32 v[152:153], v138
	v_cvt_pk_f32_fp8_sdwa v[154:155], v138 src0_sel:WORD_1
	v_cvt_pk_f32_fp8_e32 v[156:157], v139
	v_cvt_pk_f32_fp8_sdwa v[158:159], v139 src0_sel:WORD_1
	v_fmac_f32_e32 v0, v62, v144
	v_fmac_f32_e32 v1, v62, v145
	v_fmac_f32_e32 v2, v62, v146
	v_fmac_f32_e32 v3, v62, v147
	v_fmac_f32_e32 v4, v62, v148
	v_fmac_f32_e32 v5, v62, v149
	v_fmac_f32_e32 v6, v62, v150
	v_fmac_f32_e32 v7, v62, v151
	v_fmac_f32_e32 v8, v62, v152
	v_fmac_f32_e32 v9, v62, v153
	v_fmac_f32_e32 v10, v62, v154
	v_fmac_f32_e32 v11, v62, v155
	v_fmac_f32_e32 v12, v62, v156
	v_fmac_f32_e32 v13, v62, v157
	v_fmac_f32_e32 v14, v62, v158
	v_fmac_f32_e32 v15, v62, v159
	v_lshl_add_u32 v161, v46, 7, v160
	global_load_dwordx4 v[136:139], v161, s[14:15]
	s_waitcnt vmcnt(15)
	v_cvt_pk_f32_fp8_e32 v[144:145], v140
	v_cvt_pk_f32_fp8_sdwa v[146:147], v140 src0_sel:WORD_1
	v_cvt_pk_f32_fp8_e32 v[148:149], v141
	v_cvt_pk_f32_fp8_sdwa v[150:151], v141 src0_sel:WORD_1
	v_cvt_pk_f32_fp8_e32 v[152:153], v142
	v_cvt_pk_f32_fp8_sdwa v[154:155], v142 src0_sel:WORD_1
	v_cvt_pk_f32_fp8_e32 v[156:157], v143
	v_cvt_pk_f32_fp8_sdwa v[158:159], v143 src0_sel:WORD_1
	v_fmac_f32_e32 v0, v63, v144
	v_fmac_f32_e32 v1, v63, v145
	v_fmac_f32_e32 v2, v63, v146
	v_fmac_f32_e32 v3, v63, v147
	v_fmac_f32_e32 v4, v63, v148
	v_fmac_f32_e32 v5, v63, v149
	v_fmac_f32_e32 v6, v63, v150
	v_fmac_f32_e32 v7, v63, v151
	v_fmac_f32_e32 v8, v63, v152
	v_fmac_f32_e32 v9, v63, v153
	v_fmac_f32_e32 v10, v63, v154
	v_fmac_f32_e32 v11, v63, v155
	v_fmac_f32_e32 v12, v63, v156
	v_fmac_f32_e32 v13, v63, v157
	v_fmac_f32_e32 v14, v63, v158
	v_fmac_f32_e32 v15, v63, v159
	v_lshl_add_u32 v161, v47, 7, v160
	global_load_dwordx4 v[140:143], v161, s[14:15]
	ds_read_b128 v[32:35], v163 offset:192
	ds_read_b128 v[36:39], v163 offset:208
	ds_read_b128 v[40:43], v163 offset:224
	ds_read_b128 v[44:47], v163 offset:240
	ds_read_b128 v[48:51], v163 offset:4352
	ds_read_b128 v[52:55], v163 offset:4368
	ds_read_b128 v[56:59], v163 offset:4384
	ds_read_b128 v[60:63], v163 offset:4400
	s_waitcnt vmcnt(15)
	v_cvt_pk_f32_fp8_e32 v[144:145], v80
	v_cvt_pk_f32_fp8_sdwa v[146:147], v80 src0_sel:WORD_1
	v_cvt_pk_f32_fp8_e32 v[148:149], v81
	v_cvt_pk_f32_fp8_sdwa v[150:151], v81 src0_sel:WORD_1
	v_cvt_pk_f32_fp8_e32 v[152:153], v82
	v_cvt_pk_f32_fp8_sdwa v[154:155], v82 src0_sel:WORD_1
	v_cvt_pk_f32_fp8_e32 v[156:157], v83
	v_cvt_pk_f32_fp8_sdwa v[158:159], v83 src0_sel:WORD_1
	v_fmac_f32_e32 v0, v64, v144
	v_fmac_f32_e32 v1, v64, v145
	v_fmac_f32_e32 v2, v64, v146
	v_fmac_f32_e32 v3, v64, v147
	v_fmac_f32_e32 v4, v64, v148
	v_fmac_f32_e32 v5, v64, v149
	v_fmac_f32_e32 v6, v64, v150
	v_fmac_f32_e32 v7, v64, v151
	v_fmac_f32_e32 v8, v64, v152
	v_fmac_f32_e32 v9, v64, v153
	v_fmac_f32_e32 v10, v64, v154
	v_fmac_f32_e32 v11, v64, v155
	v_fmac_f32_e32 v12, v64, v156
	v_fmac_f32_e32 v13, v64, v157
	v_fmac_f32_e32 v14, v64, v158
	v_fmac_f32_e32 v15, v64, v159
	v_lshl_add_u32 v161, v16, 7, v160
	global_load_dwordx4 v[80:83], v161, s[14:15]
	s_waitcnt vmcnt(15)
	v_cvt_pk_f32_fp8_e32 v[144:145], v84
	v_cvt_pk_f32_fp8_sdwa v[146:147], v84 src0_sel:WORD_1
	v_cvt_pk_f32_fp8_e32 v[148:149], v85
	v_cvt_pk_f32_fp8_sdwa v[150:151], v85 src0_sel:WORD_1
	v_cvt_pk_f32_fp8_e32 v[152:153], v86
	v_cvt_pk_f32_fp8_sdwa v[154:155], v86 src0_sel:WORD_1
	v_cvt_pk_f32_fp8_e32 v[156:157], v87
	v_cvt_pk_f32_fp8_sdwa v[158:159], v87 src0_sel:WORD_1
	v_fmac_f32_e32 v0, v65, v144
	v_fmac_f32_e32 v1, v65, v145
	v_fmac_f32_e32 v2, v65, v146
	v_fmac_f32_e32 v3, v65, v147
	v_fmac_f32_e32 v4, v65, v148
	v_fmac_f32_e32 v5, v65, v149
	v_fmac_f32_e32 v6, v65, v150
	v_fmac_f32_e32 v7, v65, v151
	v_fmac_f32_e32 v8, v65, v152
	v_fmac_f32_e32 v9, v65, v153
	v_fmac_f32_e32 v10, v65, v154
	v_fmac_f32_e32 v11, v65, v155
	v_fmac_f32_e32 v12, v65, v156
	v_fmac_f32_e32 v13, v65, v157
	v_fmac_f32_e32 v14, v65, v158
	v_fmac_f32_e32 v15, v65, v159
	v_lshl_add_u32 v161, v17, 7, v160
	global_load_dwordx4 v[84:87], v161, s[14:15]
	s_waitcnt vmcnt(15)
	v_cvt_pk_f32_fp8_e32 v[144:145], v88
	v_cvt_pk_f32_fp8_sdwa v[146:147], v88 src0_sel:WORD_1
	v_cvt_pk_f32_fp8_e32 v[148:149], v89
	v_cvt_pk_f32_fp8_sdwa v[150:151], v89 src0_sel:WORD_1
	v_cvt_pk_f32_fp8_e32 v[152:153], v90
	v_cvt_pk_f32_fp8_sdwa v[154:155], v90 src0_sel:WORD_1
	v_cvt_pk_f32_fp8_e32 v[156:157], v91
	v_cvt_pk_f32_fp8_sdwa v[158:159], v91 src0_sel:WORD_1
	v_fmac_f32_e32 v0, v66, v144
	v_fmac_f32_e32 v1, v66, v145
	v_fmac_f32_e32 v2, v66, v146
	v_fmac_f32_e32 v3, v66, v147
	v_fmac_f32_e32 v4, v66, v148
	v_fmac_f32_e32 v5, v66, v149
	v_fmac_f32_e32 v6, v66, v150
	v_fmac_f32_e32 v7, v66, v151
	v_fmac_f32_e32 v8, v66, v152
	v_fmac_f32_e32 v9, v66, v153
	v_fmac_f32_e32 v10, v66, v154
	v_fmac_f32_e32 v11, v66, v155
	v_fmac_f32_e32 v12, v66, v156
	v_fmac_f32_e32 v13, v66, v157
	v_fmac_f32_e32 v14, v66, v158
	v_fmac_f32_e32 v15, v66, v159
	v_lshl_add_u32 v161, v18, 7, v160
	global_load_dwordx4 v[88:91], v161, s[14:15]
	s_waitcnt vmcnt(15)
; DI void phase_peer_b(const Params& p, int layer, const float* gnext, bool last) {
;     ...
;       for (int j = 0; j < 16; ++j) {
;         const int e = bt * 16 + j;
;         const int eidx = __builtin_amdgcn_readlane(e < 64 ? i0 : i1, e & 63);
;         vr[j] = *(const u32x4*)(EV + (size_t)eidx * DM + lane * 16);
;       }
; #pragma unroll
;       for (int j = 0; j < 16; ++j) {
;         const int e = bt * 16 + j;
;         const float wj = __int_as_float(__builtin_amdgcn_readlane(__float_as_int(e < 64 ? w0 : w1), e & 63));
; #pragma unroll
;         for (int w = 0; w < 4; ++w) {
;           const f32x2 lo = __builtin_amdgcn_cvt_pk_f32_fp8((int)vr[j][w], false);
;           const f32x2 hi = __builtin_amdgcn_cvt_pk_f32_fp8((int)vr[j][w], true);
;           acc[4 * w] += wj * lo[0]; acc[4 * w + 1] += wj * lo[1]; acc[4 * w + 2] += wj * hi[0]; acc[4 * w + 3] += wj * hi[1];
;         }
	v_cvt_pk_f32_fp8_e32 v[144:145], v92
	v_cvt_pk_f32_fp8_sdwa v[146:147], v92 src0_sel:WORD_1
	v_cvt_pk_f32_fp8_e32 v[148:149], v93
	v_cvt_pk_f32_fp8_sdwa v[150:151], v93 src0_sel:WORD_1
	v_cvt_pk_f32_fp8_e32 v[152:153], v94
	v_cvt_pk_f32_fp8_sdwa v[154:155], v94 src0_sel:WORD_1
	v_cvt_pk_f32_fp8_e32 v[156:157], v95
	v_cvt_pk_f32_fp8_sdwa v[158:159], v95 src0_sel:WORD_1
	v_fmac_f32_e32 v0, v67, v144
	v_fmac_f32_e32 v1, v67, v145
	v_fmac_f32_e32 v2, v67, v146
	v_fmac_f32_e32 v3, v67, v147
	v_fmac_f32_e32 v4, v67, v148
	v_fmac_f32_e32 v5, v67, v149
	v_fmac_f32_e32 v6, v67, v150
	v_fmac_f32_e32 v7, v67, v151
	v_fmac_f32_e32 v8, v67, v152
	v_fmac_f32_e32 v9, v67, v153
	v_fmac_f32_e32 v10, v67, v154
	v_fmac_f32_e32 v11, v67, v155
	v_fmac_f32_e32 v12, v67, v156
	v_fmac_f32_e32 v13, v67, v157
	v_fmac_f32_e32 v14, v67, v158
	v_fmac_f32_e32 v15, v67, v159
	v_lshl_add_u32 v161, v19, 7, v160
	global_load_dwordx4 v[92:95], v161, s[14:15]
	s_waitcnt vmcnt(15)
	v_cvt_pk_f32_fp8_e32 v[144:145], v96
	v_cvt_pk_f32_fp8_sdwa v[146:147], v96 src0_sel:WORD_1
	v_cvt_pk_f32_fp8_e32 v[148:149], v97
	v_cvt_pk_f32_fp8_sdwa v[150:151], v97 src0_sel:WORD_1
	v_cvt_pk_f32_fp8_e32 v[152:153], v98
	v_cvt_pk_f32_fp8_sdwa v[154:155], v98 src0_sel:WORD_1
	v_cvt_pk_f32_fp8_e32 v[156:157], v99
	v_cvt_pk_f32_fp8_sdwa v[158:159], v99 src0_sel:WORD_1
	v_fmac_f32_e32 v0, v68, v144
	v_fmac_f32_e32 v1, v68, v145
	v_fmac_f32_e32 v2, v68, v146
	v_fmac_f32_e32 v3, v68, v147
	v_fmac_f32_e32 v4, v68, v148
	v_fmac_f32_e32 v5, v68, v149
	v_fmac_f32_e32 v6, v68, v150
	v_fmac_f32_e32 v7, v68, v151
	v_fmac_f32_e32 v8, v68, v152
	v_fmac_f32_e32 v9, v68, v153
	v_fmac_f32_e32 v10, v68, v154
	v_fmac_f32_e32 v11, v68, v155
	v_fmac_f32_e32 v12, v68, v156
	v_fmac_f32_e32 v13, v68, v157
	v_fmac_f32_e32 v14, v68, v158
	v_fmac_f32_e32 v15, v68, v159
	v_lshl_add_u32 v161, v20, 7, v160
	global_load_dwordx4 v[96:99], v161, s[14:15]
	s_waitcnt vmcnt(15)
	v_cvt_pk_f32_fp8_e32 v[144:145], v100
	v_cvt_pk_f32_fp8_sdwa v[146:147], v100 src0_sel:WORD_1
	v_cvt_pk_f32_fp8_e32 v[148:149], v101
	v_cvt_pk_f32_fp8_sdwa v[150:151], v101 src0_sel:WORD_1
	v_cvt_pk_f32_fp8_e32 v[152:153], v102
	v_cvt_pk_f32_fp8_sdwa v[154:155], v102 src0_sel:WORD_1
	v_cvt_pk_f32_fp8_e32 v[156:157], v103
	v_cvt_pk_f32_fp8_sdwa v[158:159], v103 src0_sel:WORD_1
	v_fmac_f32_e32 v0, v69, v144
	v_fmac_f32_e32 v1, v69, v145
	v_fmac_f32_e32 v2, v69, v146
	v_fmac_f32_e32 v3, v69, v147
	v_fmac_f32_e32 v4, v69, v148
	v_fmac_f32_e32 v5, v69, v149
	v_fmac_f32_e32 v6, v69, v150
	v_fmac_f32_e32 v7, v69, v151
	v_fmac_f32_e32 v8, v69, v152
	v_fmac_f32_e32 v9, v69, v153
	v_fmac_f32_e32 v10, v69, v154
	v_fmac_f32_e32 v11, v69, v155
	v_fmac_f32_e32 v12, v69, v156
	v_fmac_f32_e32 v13, v69, v157
	v_fmac_f32_e32 v14, v69, v158
	v_fmac_f32_e32 v15, v69, v159
	v_lshl_add_u32 v161, v21, 7, v160
	global_load_dwordx4 v[100:103], v161, s[14:15]
	s_waitcnt vmcnt(15)
	v_cvt_pk_f32_fp8_e32 v[144:145], v104
	v_cvt_pk_f32_fp8_sdwa v[146:147], v104 src0_sel:WORD_1
	v_cvt_pk_f32_fp8_e32 v[148:149], v105
	v_cvt_pk_f32_fp8_sdwa v[150:151], v105 src0_sel:WORD_1
	v_cvt_pk_f32_fp8_e32 v[152:153], v106
	v_cvt_pk_f32_fp8_sdwa v[154:155], v106 src0_sel:WORD_1
	v_cvt_pk_f32_fp8_e32 v[156:157], v107
	v_cvt_pk_f32_fp8_sdwa v[158:159], v107 src0_sel:WORD_1
	v_fmac_f32_e32 v0, v70, v144
	v_fmac_f32_e32 v1, v70, v145
	v_fmac_f32_e32 v2, v70, v146
	v_fmac_f32_e32 v3, v70, v147
	v_fmac_f32_e32 v4, v70, v148
	v_fmac_f32_e32 v5, v70, v149
	v_fmac_f32_e32 v6, v70, v150
	v_fmac_f32_e32 v7, v70, v151
	v_fmac_f32_e32 v8, v70, v152
	v_fmac_f32_e32 v9, v70, v153
	v_fmac_f32_e32 v10, v70, v154
	v_fmac_f32_e32 v11, v70, v155
	v_fmac_f32_e32 v12, v70, v156
	v_fmac_f32_e32 v13, v70, v157
	v_fmac_f32_e32 v14, v70, v158
	v_fmac_f32_e32 v15, v70, v159
	v_lshl_add_u32 v161, v22, 7, v160
	global_load_dwordx4 v[104:107], v161, s[14:15]
	s_waitcnt vmcnt(15)
	v_cvt_pk_f32_fp8_e32 v[144:145], v108
	v_cvt_pk_f32_fp8_sdwa v[146:147], v108 src0_sel:WORD_1
	v_cvt_pk_f32_fp8_e32 v[148:149], v109
	v_cvt_pk_f32_fp8_sdwa v[150:151], v109 src0_sel:WORD_1
	v_cvt_pk_f32_fp8_e32 v[152:153], v110
	v_cvt_pk_f32_fp8_sdwa v[154:155], v110 src0_sel:WORD_1
	v_cvt_pk_f32_fp8_e32 v[156:157], v111
	v_cvt_pk_f32_fp8_sdwa v[158:159], v111 src0_sel:WORD_1
	v_fmac_f32_e32 v0, v71, v144
	v_fmac_f32_e32 v1, v71, v145
	v_fmac_f32_e32 v2, v71, v146
	v_fmac_f32_e32 v3, v71, v147
	v_fmac_f32_e32 v4, v71, v148
	v_fmac_f32_e32 v5, v71, v149
	v_fmac_f32_e32 v6, v71, v150
	v_fmac_f32_e32 v7, v71, v151
	v_fmac_f32_e32 v8, v71, v152
	v_fmac_f32_e32 v9, v71, v153
	v_fmac_f32_e32 v10, v71, v154
	v_fmac_f32_e32 v11, v71, v155
	v_fmac_f32_e32 v12, v71, v156
	v_fmac_f32_e32 v13, v71, v157
	v_fmac_f32_e32 v14, v71, v158
	v_fmac_f32_e32 v15, v71, v159
	v_lshl_add_u32 v161, v23, 7, v160
	global_load_dwordx4 v[108:111], v161, s[14:15]
	s_waitcnt vmcnt(15)
	v_cvt_pk_f32_fp8_e32 v[144:145], v112
	v_cvt_pk_f32_fp8_sdwa v[146:147], v112 src0_sel:WORD_1
	v_cvt_pk_f32_fp8_e32 v[148:149], v113
	v_cvt_pk_f32_fp8_sdwa v[150:151], v113 src0_sel:WORD_1
	v_cvt_pk_f32_fp8_e32 v[152:153], v114
	v_cvt_pk_f32_fp8_sdwa v[154:155], v114 src0_sel:WORD_1
	v_cvt_pk_f32_fp8_e32 v[156:157], v115
	v_cvt_pk_f32_fp8_sdwa v[158:159], v115 src0_sel:WORD_1
	v_fmac_f32_e32 v0, v72, v144
	v_fmac_f32_e32 v1, v72, v145
	v_fmac_f32_e32 v2, v72, v146
	v_fmac_f32_e32 v3, v72, v147
	v_fmac_f32_e32 v4, v72, v148
	v_fmac_f32_e32 v5, v72, v149
	v_fmac_f32_e32 v6, v72, v150
	v_fmac_f32_e32 v7, v72, v151
	v_fmac_f32_e32 v8, v72, v152
	v_fmac_f32_e32 v9, v72, v153
	v_fmac_f32_e32 v10, v72, v154
	v_fmac_f32_e32 v11, v72, v155
	v_fmac_f32_e32 v12, v72, v156
	v_fmac_f32_e32 v13, v72, v157
	v_fmac_f32_e32 v14, v72, v158
	v_fmac_f32_e32 v15, v72, v159
	v_lshl_add_u32 v161, v24, 7, v160
	global_load_dwordx4 v[112:115], v161, s[14:15]
	s_waitcnt vmcnt(15)
; DI void phase_peer_b(const Params& p, int layer, const float* gnext, bool last) {
;     ...
;       for (int j = 0; j < 16; ++j) {
;         const int e = bt * 16 + j;
;         const int eidx = __builtin_amdgcn_readlane(e < 64 ? i0 : i1, e & 63);
;         vr[j] = *(const u32x4*)(EV + (size_t)eidx * DM + lane * 16);
;       }
; #pragma unroll
;       for (int j = 0; j < 16; ++j) {
;         const int e = bt * 16 + j;
;         const float wj = __int_as_float(__builtin_amdgcn_readlane(__float_as_int(e < 64 ? w0 : w1), e & 63));
; #pragma unroll
;         for (int w = 0; w < 4; ++w) {
;           const f32x2 lo = __builtin_amdgcn_cvt_pk_f32_fp8((int)vr[j][w], false);
;           const f32x2 hi = __builtin_amdgcn_cvt_pk_f32_fp8((int)vr[j][w], true);
;           acc[4 * w] += wj * lo[0]; acc[4 * w + 1] += wj * lo[1]; acc[4 * w + 2] += wj * hi[0]; acc[4 * w + 3] += wj * hi[1];
;         }
	v_cvt_pk_f32_fp8_e32 v[144:145], v116
	v_cvt_pk_f32_fp8_sdwa v[146:147], v116 src0_sel:WORD_1
	v_cvt_pk_f32_fp8_e32 v[148:149], v117
	v_cvt_pk_f32_fp8_sdwa v[150:151], v117 src0_sel:WORD_1
	v_cvt_pk_f32_fp8_e32 v[152:153], v118
	v_cvt_pk_f32_fp8_sdwa v[154:155], v118 src0_sel:WORD_1
	v_cvt_pk_f32_fp8_e32 v[156:157], v119
	v_cvt_pk_f32_fp8_sdwa v[158:159], v119 src0_sel:WORD_1
	v_fmac_f32_e32 v0, v73, v144
	v_fmac_f32_e32 v1, v73, v145
	v_fmac_f32_e32 v2, v73, v146
	v_fmac_f32_e32 v3, v73, v147
	v_fmac_f32_e32 v4, v73, v148
	v_fmac_f32_e32 v5, v73, v149
	v_fmac_f32_e32 v6, v73, v150
	v_fmac_f32_e32 v7, v73, v151
	v_fmac_f32_e32 v8, v73, v152
	v_fmac_f32_e32 v9, v73, v153
	v_fmac_f32_e32 v10, v73, v154
	v_fmac_f32_e32 v11, v73, v155
	v_fmac_f32_e32 v12, v73, v156
	v_fmac_f32_e32 v13, v73, v157
	v_fmac_f32_e32 v14, v73, v158
	v_fmac_f32_e32 v15, v73, v159
	v_lshl_add_u32 v161, v25, 7, v160
	global_load_dwordx4 v[116:119], v161, s[14:15]
	s_waitcnt vmcnt(15)
	v_cvt_pk_f32_fp8_e32 v[144:145], v120
	v_cvt_pk_f32_fp8_sdwa v[146:147], v120 src0_sel:WORD_1
	v_cvt_pk_f32_fp8_e32 v[148:149], v121
	v_cvt_pk_f32_fp8_sdwa v[150:151], v121 src0_sel:WORD_1
	v_cvt_pk_f32_fp8_e32 v[152:153], v122
	v_cvt_pk_f32_fp8_sdwa v[154:155], v122 src0_sel:WORD_1
	v_cvt_pk_f32_fp8_e32 v[156:157], v123
	v_cvt_pk_f32_fp8_sdwa v[158:159], v123 src0_sel:WORD_1
	v_fmac_f32_e32 v0, v74, v144
	v_fmac_f32_e32 v1, v74, v145
	v_fmac_f32_e32 v2, v74, v146
	v_fmac_f32_e32 v3, v74, v147
	v_fmac_f32_e32 v4, v74, v148
	v_fmac_f32_e32 v5, v74, v149
	v_fmac_f32_e32 v6, v74, v150
	v_fmac_f32_e32 v7, v74, v151
	v_fmac_f32_e32 v8, v74, v152
	v_fmac_f32_e32 v9, v74, v153
	v_fmac_f32_e32 v10, v74, v154
	v_fmac_f32_e32 v11, v74, v155
	v_fmac_f32_e32 v12, v74, v156
	v_fmac_f32_e32 v13, v74, v157
	v_fmac_f32_e32 v14, v74, v158
	v_fmac_f32_e32 v15, v74, v159
	v_lshl_add_u32 v161, v26, 7, v160
	global_load_dwordx4 v[120:123], v161, s[14:15]
	s_waitcnt vmcnt(15)
	v_cvt_pk_f32_fp8_e32 v[144:145], v124
	v_cvt_pk_f32_fp8_sdwa v[146:147], v124 src0_sel:WORD_1
	v_cvt_pk_f32_fp8_e32 v[148:149], v125
	v_cvt_pk_f32_fp8_sdwa v[150:151], v125 src0_sel:WORD_1
	v_cvt_pk_f32_fp8_e32 v[152:153], v126
	v_cvt_pk_f32_fp8_sdwa v[154:155], v126 src0_sel:WORD_1
	v_cvt_pk_f32_fp8_e32 v[156:157], v127
	v_cvt_pk_f32_fp8_sdwa v[158:159], v127 src0_sel:WORD_1
	v_fmac_f32_e32 v0, v75, v144
	v_fmac_f32_e32 v1, v75, v145
	v_fmac_f32_e32 v2, v75, v146
	v_fmac_f32_e32 v3, v75, v147
	v_fmac_f32_e32 v4, v75, v148
	v_fmac_f32_e32 v5, v75, v149
	v_fmac_f32_e32 v6, v75, v150
	v_fmac_f32_e32 v7, v75, v151
	v_fmac_f32_e32 v8, v75, v152
	v_fmac_f32_e32 v9, v75, v153
	v_fmac_f32_e32 v10, v75, v154
	v_fmac_f32_e32 v11, v75, v155
	v_fmac_f32_e32 v12, v75, v156
	v_fmac_f32_e32 v13, v75, v157
	v_fmac_f32_e32 v14, v75, v158
	v_fmac_f32_e32 v15, v75, v159
	v_lshl_add_u32 v161, v27, 7, v160
	global_load_dwordx4 v[124:127], v161, s[14:15]
	s_waitcnt vmcnt(15)
	v_cvt_pk_f32_fp8_e32 v[144:145], v128
	v_cvt_pk_f32_fp8_sdwa v[146:147], v128 src0_sel:WORD_1
	v_cvt_pk_f32_fp8_e32 v[148:149], v129
	v_cvt_pk_f32_fp8_sdwa v[150:151], v129 src0_sel:WORD_1
	v_cvt_pk_f32_fp8_e32 v[152:153], v130
	v_cvt_pk_f32_fp8_sdwa v[154:155], v130 src0_sel:WORD_1
	v_cvt_pk_f32_fp8_e32 v[156:157], v131
	v_cvt_pk_f32_fp8_sdwa v[158:159], v131 src0_sel:WORD_1
	v_fmac_f32_e32 v0, v76, v144
	v_fmac_f32_e32 v1, v76, v145
	v_fmac_f32_e32 v2, v76, v146
	v_fmac_f32_e32 v3, v76, v147
	v_fmac_f32_e32 v4, v76, v148
	v_fmac_f32_e32 v5, v76, v149
	v_fmac_f32_e32 v6, v76, v150
	v_fmac_f32_e32 v7, v76, v151
	v_fmac_f32_e32 v8, v76, v152
	v_fmac_f32_e32 v9, v76, v153
	v_fmac_f32_e32 v10, v76, v154
	v_fmac_f32_e32 v11, v76, v155
	v_fmac_f32_e32 v12, v76, v156
	v_fmac_f32_e32 v13, v76, v157
	v_fmac_f32_e32 v14, v76, v158
	v_fmac_f32_e32 v15, v76, v159
	v_lshl_add_u32 v161, v28, 7, v160
	global_load_dwordx4 v[128:131], v161, s[14:15]
	s_waitcnt vmcnt(15)
	v_cvt_pk_f32_fp8_e32 v[144:145], v132
	v_cvt_pk_f32_fp8_sdwa v[146:147], v132 src0_sel:WORD_1
	v_cvt_pk_f32_fp8_e32 v[148:149], v133
	v_cvt_pk_f32_fp8_sdwa v[150:151], v133 src0_sel:WORD_1
	v_cvt_pk_f32_fp8_e32 v[152:153], v134
	v_cvt_pk_f32_fp8_sdwa v[154:155], v134 src0_sel:WORD_1
	v_cvt_pk_f32_fp8_e32 v[156:157], v135
	v_cvt_pk_f32_fp8_sdwa v[158:159], v135 src0_sel:WORD_1
	v_fmac_f32_e32 v0, v77, v144
	v_fmac_f32_e32 v1, v77, v145
	v_fmac_f32_e32 v2, v77, v146
	v_fmac_f32_e32 v3, v77, v147
	v_fmac_f32_e32 v4, v77, v148
	v_fmac_f32_e32 v5, v77, v149
	v_fmac_f32_e32 v6, v77, v150
	v_fmac_f32_e32 v7, v77, v151
	v_fmac_f32_e32 v8, v77, v152
	v_fmac_f32_e32 v9, v77, v153
	v_fmac_f32_e32 v10, v77, v154
	v_fmac_f32_e32 v11, v77, v155
	v_fmac_f32_e32 v12, v77, v156
	v_fmac_f32_e32 v13, v77, v157
	v_fmac_f32_e32 v14, v77, v158
	v_fmac_f32_e32 v15, v77, v159
	v_lshl_add_u32 v161, v29, 7, v160
	global_load_dwordx4 v[132:135], v161, s[14:15]
	s_waitcnt vmcnt(15)
	v_cvt_pk_f32_fp8_e32 v[144:145], v136
	v_cvt_pk_f32_fp8_sdwa v[146:147], v136 src0_sel:WORD_1
	v_cvt_pk_f32_fp8_e32 v[148:149], v137
	v_cvt_pk_f32_fp8_sdwa v[150:151], v137 src0_sel:WORD_1
	v_cvt_pk_f32_fp8_e32 v[152:153], v138
	v_cvt_pk_f32_fp8_sdwa v[154:155], v138 src0_sel:WORD_1
	v_cvt_pk_f32_fp8_e32 v[156:157], v139
	v_cvt_pk_f32_fp8_sdwa v[158:159], v139 src0_sel:WORD_1
	v_fmac_f32_e32 v0, v78, v144
	v_fmac_f32_e32 v1, v78, v145
	v_fmac_f32_e32 v2, v78, v146
	v_fmac_f32_e32 v3, v78, v147
	v_fmac_f32_e32 v4, v78, v148
	v_fmac_f32_e32 v5, v78, v149
	v_fmac_f32_e32 v6, v78, v150
	v_fmac_f32_e32 v7, v78, v151
	v_fmac_f32_e32 v8, v78, v152
	v_fmac_f32_e32 v9, v78, v153
	v_fmac_f32_e32 v10, v78, v154
	v_fmac_f32_e32 v11, v78, v155
	v_fmac_f32_e32 v12, v78, v156
	v_fmac_f32_e32 v13, v78, v157
	v_fmac_f32_e32 v14, v78, v158
	v_fmac_f32_e32 v15, v78, v159
	v_lshl_add_u32 v161, v30, 7, v160
	global_load_dwordx4 v[136:139], v161, s[14:15]
	s_waitcnt vmcnt(15)
; DI void phase_peer_b(const Params& p, int layer, const float* gnext, bool last) {
;     ...
;       u32x4 vr[16];
; #pragma unroll
;       for (int j = 0; j < 16; ++j) {
;         const int e = bt * 16 + j;
;         const int eidx = __builtin_amdgcn_readlane(e < 64 ? i0 : i1, e & 63);
;         vr[j] = *(const u32x4*)(EV + (size_t)eidx * DM + lane * 16);
;       }
; #pragma unroll
;       for (int j = 0; j < 16; ++j) {
;         const int e = bt * 16 + j;
;         const float wj = __int_as_float(__builtin_amdgcn_readlane(__float_as_int(e < 64 ? w0 : w1), e & 63));
; #pragma unroll
;         for (int w = 0; w < 4; ++w) {
;           const f32x2 lo = __builtin_amdgcn_cvt_pk_f32_fp8((int)vr[j][w], false);
;           const f32x2 hi = __builtin_amdgcn_cvt_pk_f32_fp8((int)vr[j][w], true);
;           acc[4 * w] += wj * lo[0]; acc[4 * w + 1] += wj * lo[1]; acc[4 * w + 2] += wj * hi[0]; acc[4 * w + 3] += wj * hi[1];
;         }
	v_cvt_pk_f32_fp8_e32 v[144:145], v140
	v_cvt_pk_f32_fp8_sdwa v[146:147], v140 src0_sel:WORD_1
	v_cvt_pk_f32_fp8_e32 v[148:149], v141
	v_cvt_pk_f32_fp8_sdwa v[150:151], v141 src0_sel:WORD_1
	v_cvt_pk_f32_fp8_e32 v[152:153], v142
	v_cvt_pk_f32_fp8_sdwa v[154:155], v142 src0_sel:WORD_1
	v_cvt_pk_f32_fp8_e32 v[156:157], v143
	v_cvt_pk_f32_fp8_sdwa v[158:159], v143 src0_sel:WORD_1
	v_fmac_f32_e32 v0, v79, v144
	v_fmac_f32_e32 v1, v79, v145
	v_fmac_f32_e32 v2, v79, v146
	v_fmac_f32_e32 v3, v79, v147
	v_fmac_f32_e32 v4, v79, v148
	v_fmac_f32_e32 v5, v79, v149
	v_fmac_f32_e32 v6, v79, v150
	v_fmac_f32_e32 v7, v79, v151
	v_fmac_f32_e32 v8, v79, v152
	v_fmac_f32_e32 v9, v79, v153
	v_fmac_f32_e32 v10, v79, v154
	v_fmac_f32_e32 v11, v79, v155
	v_fmac_f32_e32 v12, v79, v156
	v_fmac_f32_e32 v13, v79, v157
	v_fmac_f32_e32 v14, v79, v158
	v_fmac_f32_e32 v15, v79, v159
	v_lshl_add_u32 v161, v31, 7, v160
	global_load_dwordx4 v[140:143], v161, s[14:15]
	s_waitcnt lgkmcnt(0)
	ds_read_b128 v[16:19], v163 offset:256
	ds_read_b128 v[20:23], v163 offset:272
	ds_read_b128 v[24:27], v163 offset:288
	ds_read_b128 v[28:31], v163 offset:304
	ds_read_b128 v[64:67], v163 offset:4416
	ds_read_b128 v[68:71], v163 offset:4432
	ds_read_b128 v[72:75], v163 offset:4448
	ds_read_b128 v[76:79], v163 offset:4464
	s_waitcnt vmcnt(15)
	v_cvt_pk_f32_fp8_e32 v[144:145], v80
	v_cvt_pk_f32_fp8_sdwa v[146:147], v80 src0_sel:WORD_1
	v_cvt_pk_f32_fp8_e32 v[148:149], v81
	v_cvt_pk_f32_fp8_sdwa v[150:151], v81 src0_sel:WORD_1
	v_cvt_pk_f32_fp8_e32 v[152:153], v82
	v_cvt_pk_f32_fp8_sdwa v[154:155], v82 src0_sel:WORD_1
	v_cvt_pk_f32_fp8_e32 v[156:157], v83
	v_cvt_pk_f32_fp8_sdwa v[158:159], v83 src0_sel:WORD_1
	v_fmac_f32_e32 v0, v48, v144
	v_fmac_f32_e32 v1, v48, v145
	v_fmac_f32_e32 v2, v48, v146
	v_fmac_f32_e32 v3, v48, v147
	v_fmac_f32_e32 v4, v48, v148
	v_fmac_f32_e32 v5, v48, v149
	v_fmac_f32_e32 v6, v48, v150
	v_fmac_f32_e32 v7, v48, v151
	v_fmac_f32_e32 v8, v48, v152
	v_fmac_f32_e32 v9, v48, v153
	v_fmac_f32_e32 v10, v48, v154
	v_fmac_f32_e32 v11, v48, v155
	v_fmac_f32_e32 v12, v48, v156
	v_fmac_f32_e32 v13, v48, v157
	v_fmac_f32_e32 v14, v48, v158
	v_fmac_f32_e32 v15, v48, v159
	v_lshl_add_u32 v161, v32, 7, v160
	global_load_dwordx4 v[80:83], v161, s[14:15]
	s_waitcnt vmcnt(15)
	v_cvt_pk_f32_fp8_e32 v[144:145], v84
	v_cvt_pk_f32_fp8_sdwa v[146:147], v84 src0_sel:WORD_1
	v_cvt_pk_f32_fp8_e32 v[148:149], v85
	v_cvt_pk_f32_fp8_sdwa v[150:151], v85 src0_sel:WORD_1
	v_cvt_pk_f32_fp8_e32 v[152:153], v86
	v_cvt_pk_f32_fp8_sdwa v[154:155], v86 src0_sel:WORD_1
	v_cvt_pk_f32_fp8_e32 v[156:157], v87
	v_cvt_pk_f32_fp8_sdwa v[158:159], v87 src0_sel:WORD_1
	v_fmac_f32_e32 v0, v49, v144
	v_fmac_f32_e32 v1, v49, v145
	v_fmac_f32_e32 v2, v49, v146
	v_fmac_f32_e32 v3, v49, v147
	v_fmac_f32_e32 v4, v49, v148
	v_fmac_f32_e32 v5, v49, v149
	v_fmac_f32_e32 v6, v49, v150
	v_fmac_f32_e32 v7, v49, v151
	v_fmac_f32_e32 v8, v49, v152
	v_fmac_f32_e32 v9, v49, v153
	v_fmac_f32_e32 v10, v49, v154
	v_fmac_f32_e32 v11, v49, v155
	v_fmac_f32_e32 v12, v49, v156
	v_fmac_f32_e32 v13, v49, v157
	v_fmac_f32_e32 v14, v49, v158
	v_fmac_f32_e32 v15, v49, v159
	v_lshl_add_u32 v161, v33, 7, v160
	global_load_dwordx4 v[84:87], v161, s[14:15]
	s_waitcnt vmcnt(15)
	v_cvt_pk_f32_fp8_e32 v[144:145], v88
	v_cvt_pk_f32_fp8_sdwa v[146:147], v88 src0_sel:WORD_1
	v_cvt_pk_f32_fp8_e32 v[148:149], v89
	v_cvt_pk_f32_fp8_sdwa v[150:151], v89 src0_sel:WORD_1
	v_cvt_pk_f32_fp8_e32 v[152:153], v90
	v_cvt_pk_f32_fp8_sdwa v[154:155], v90 src0_sel:WORD_1
	v_cvt_pk_f32_fp8_e32 v[156:157], v91
	v_cvt_pk_f32_fp8_sdwa v[158:159], v91 src0_sel:WORD_1
	v_fmac_f32_e32 v0, v50, v144
	v_fmac_f32_e32 v1, v50, v145
	v_fmac_f32_e32 v2, v50, v146
	v_fmac_f32_e32 v3, v50, v147
	v_fmac_f32_e32 v4, v50, v148
	v_fmac_f32_e32 v5, v50, v149
	v_fmac_f32_e32 v6, v50, v150
	v_fmac_f32_e32 v7, v50, v151
	v_fmac_f32_e32 v8, v50, v152
	v_fmac_f32_e32 v9, v50, v153
	v_fmac_f32_e32 v10, v50, v154
	v_fmac_f32_e32 v11, v50, v155
	v_fmac_f32_e32 v12, v50, v156
	v_fmac_f32_e32 v13, v50, v157
	v_fmac_f32_e32 v14, v50, v158
	v_fmac_f32_e32 v15, v50, v159
	v_lshl_add_u32 v161, v34, 7, v160
	global_load_dwordx4 v[88:91], v161, s[14:15]
	s_waitcnt vmcnt(15)
	v_cvt_pk_f32_fp8_e32 v[144:145], v92
	v_cvt_pk_f32_fp8_sdwa v[146:147], v92 src0_sel:WORD_1
	v_cvt_pk_f32_fp8_e32 v[148:149], v93
	v_cvt_pk_f32_fp8_sdwa v[150:151], v93 src0_sel:WORD_1
	v_cvt_pk_f32_fp8_e32 v[152:153], v94
	v_cvt_pk_f32_fp8_sdwa v[154:155], v94 src0_sel:WORD_1
	v_cvt_pk_f32_fp8_e32 v[156:157], v95
	v_cvt_pk_f32_fp8_sdwa v[158:159], v95 src0_sel:WORD_1
	v_fmac_f32_e32 v0, v51, v144
	v_fmac_f32_e32 v1, v51, v145
	v_fmac_f32_e32 v2, v51, v146
	v_fmac_f32_e32 v3, v51, v147
	v_fmac_f32_e32 v4, v51, v148
	v_fmac_f32_e32 v5, v51, v149
	v_fmac_f32_e32 v6, v51, v150
	v_fmac_f32_e32 v7, v51, v151
	v_fmac_f32_e32 v8, v51, v152
	v_fmac_f32_e32 v9, v51, v153
	v_fmac_f32_e32 v10, v51, v154
	v_fmac_f32_e32 v11, v51, v155
	v_fmac_f32_e32 v12, v51, v156
	v_fmac_f32_e32 v13, v51, v157
	v_fmac_f32_e32 v14, v51, v158
	v_fmac_f32_e32 v15, v51, v159
	v_lshl_add_u32 v161, v35, 7, v160
	global_load_dwordx4 v[92:95], v161, s[14:15]
	s_waitcnt vmcnt(15)
	v_cvt_pk_f32_fp8_e32 v[144:145], v96
	v_cvt_pk_f32_fp8_sdwa v[146:147], v96 src0_sel:WORD_1
	v_cvt_pk_f32_fp8_e32 v[148:149], v97
	v_cvt_pk_f32_fp8_sdwa v[150:151], v97 src0_sel:WORD_1
	v_cvt_pk_f32_fp8_e32 v[152:153], v98
	v_cvt_pk_f32_fp8_sdwa v[154:155], v98 src0_sel:WORD_1
	v_cvt_pk_f32_fp8_e32 v[156:157], v99
	v_cvt_pk_f32_fp8_sdwa v[158:159], v99 src0_sel:WORD_1
	v_fmac_f32_e32 v0, v52, v144
	v_fmac_f32_e32 v1, v52, v145
	v_fmac_f32_e32 v2, v52, v146
	v_fmac_f32_e32 v3, v52, v147
	v_fmac_f32_e32 v4, v52, v148
	v_fmac_f32_e32 v5, v52, v149
	v_fmac_f32_e32 v6, v52, v150
	v_fmac_f32_e32 v7, v52, v151
	v_fmac_f32_e32 v8, v52, v152
	v_fmac_f32_e32 v9, v52, v153
	v_fmac_f32_e32 v10, v52, v154
	v_fmac_f32_e32 v11, v52, v155
	v_fmac_f32_e32 v12, v52, v156
	v_fmac_f32_e32 v13, v52, v157
	v_fmac_f32_e32 v14, v52, v158
	v_fmac_f32_e32 v15, v52, v159
	v_lshl_add_u32 v161, v36, 7, v160
	global_load_dwordx4 v[96:99], v161, s[14:15]
	s_waitcnt vmcnt(15)
; DI void phase_peer_b(const Params& p, int layer, const float* gnext, bool last) {
;     ...
;       for (int j = 0; j < 16; ++j) {
;         const int e = bt * 16 + j;
;         const int eidx = __builtin_amdgcn_readlane(e < 64 ? i0 : i1, e & 63);
;         vr[j] = *(const u32x4*)(EV + (size_t)eidx * DM + lane * 16);
;       }
; #pragma unroll
;       for (int j = 0; j < 16; ++j) {
;         const int e = bt * 16 + j;
;         const float wj = __int_as_float(__builtin_amdgcn_readlane(__float_as_int(e < 64 ? w0 : w1), e & 63));
; #pragma unroll
;         for (int w = 0; w < 4; ++w) {
;           const f32x2 lo = __builtin_amdgcn_cvt_pk_f32_fp8((int)vr[j][w], false);
;           const f32x2 hi = __builtin_amdgcn_cvt_pk_f32_fp8((int)vr[j][w], true);
;           acc[4 * w] += wj * lo[0]; acc[4 * w + 1] += wj * lo[1]; acc[4 * w + 2] += wj * hi[0]; acc[4 * w + 3] += wj * hi[1];
;         }
	v_cvt_pk_f32_fp8_e32 v[144:145], v100
	v_cvt_pk_f32_fp8_sdwa v[146:147], v100 src0_sel:WORD_1
	v_cvt_pk_f32_fp8_e32 v[148:149], v101
	v_cvt_pk_f32_fp8_sdwa v[150:151], v101 src0_sel:WORD_1
	v_cvt_pk_f32_fp8_e32 v[152:153], v102
	v_cvt_pk_f32_fp8_sdwa v[154:155], v102 src0_sel:WORD_1
	v_cvt_pk_f32_fp8_e32 v[156:157], v103
	v_cvt_pk_f32_fp8_sdwa v[158:159], v103 src0_sel:WORD_1
	v_fmac_f32_e32 v0, v53, v144
	v_fmac_f32_e32 v1, v53, v145
	v_fmac_f32_e32 v2, v53, v146
	v_fmac_f32_e32 v3, v53, v147
	v_fmac_f32_e32 v4, v53, v148
	v_fmac_f32_e32 v5, v53, v149
	v_fmac_f32_e32 v6, v53, v150
	v_fmac_f32_e32 v7, v53, v151
	v_fmac_f32_e32 v8, v53, v152
	v_fmac_f32_e32 v9, v53, v153
	v_fmac_f32_e32 v10, v53, v154
	v_fmac_f32_e32 v11, v53, v155
	v_fmac_f32_e32 v12, v53, v156
	v_fmac_f32_e32 v13, v53, v157
	v_fmac_f32_e32 v14, v53, v158
	v_fmac_f32_e32 v15, v53, v159
	v_lshl_add_u32 v161, v37, 7, v160
	global_load_dwordx4 v[100:103], v161, s[14:15]
	s_waitcnt vmcnt(15)
	v_cvt_pk_f32_fp8_e32 v[144:145], v104
	v_cvt_pk_f32_fp8_sdwa v[146:147], v104 src0_sel:WORD_1
	v_cvt_pk_f32_fp8_e32 v[148:149], v105
	v_cvt_pk_f32_fp8_sdwa v[150:151], v105 src0_sel:WORD_1
	v_cvt_pk_f32_fp8_e32 v[152:153], v106
	v_cvt_pk_f32_fp8_sdwa v[154:155], v106 src0_sel:WORD_1
	v_cvt_pk_f32_fp8_e32 v[156:157], v107
	v_cvt_pk_f32_fp8_sdwa v[158:159], v107 src0_sel:WORD_1
	v_fmac_f32_e32 v0, v54, v144
	v_fmac_f32_e32 v1, v54, v145
	v_fmac_f32_e32 v2, v54, v146
	v_fmac_f32_e32 v3, v54, v147
	v_fmac_f32_e32 v4, v54, v148
	v_fmac_f32_e32 v5, v54, v149
	v_fmac_f32_e32 v6, v54, v150
	v_fmac_f32_e32 v7, v54, v151
	v_fmac_f32_e32 v8, v54, v152
	v_fmac_f32_e32 v9, v54, v153
	v_fmac_f32_e32 v10, v54, v154
	v_fmac_f32_e32 v11, v54, v155
	v_fmac_f32_e32 v12, v54, v156
	v_fmac_f32_e32 v13, v54, v157
	v_fmac_f32_e32 v14, v54, v158
	v_fmac_f32_e32 v15, v54, v159
	v_lshl_add_u32 v161, v38, 7, v160
	global_load_dwordx4 v[104:107], v161, s[14:15]
	s_waitcnt vmcnt(15)
	v_cvt_pk_f32_fp8_e32 v[144:145], v108
	v_cvt_pk_f32_fp8_sdwa v[146:147], v108 src0_sel:WORD_1
	v_cvt_pk_f32_fp8_e32 v[148:149], v109
	v_cvt_pk_f32_fp8_sdwa v[150:151], v109 src0_sel:WORD_1
	v_cvt_pk_f32_fp8_e32 v[152:153], v110
	v_cvt_pk_f32_fp8_sdwa v[154:155], v110 src0_sel:WORD_1
	v_cvt_pk_f32_fp8_e32 v[156:157], v111
	v_cvt_pk_f32_fp8_sdwa v[158:159], v111 src0_sel:WORD_1
	v_fmac_f32_e32 v0, v55, v144
	v_fmac_f32_e32 v1, v55, v145
	v_fmac_f32_e32 v2, v55, v146
	v_fmac_f32_e32 v3, v55, v147
	v_fmac_f32_e32 v4, v55, v148
	v_fmac_f32_e32 v5, v55, v149
	v_fmac_f32_e32 v6, v55, v150
	v_fmac_f32_e32 v7, v55, v151
	v_fmac_f32_e32 v8, v55, v152
	v_fmac_f32_e32 v9, v55, v153
	v_fmac_f32_e32 v10, v55, v154
	v_fmac_f32_e32 v11, v55, v155
	v_fmac_f32_e32 v12, v55, v156
	v_fmac_f32_e32 v13, v55, v157
	v_fmac_f32_e32 v14, v55, v158
	v_fmac_f32_e32 v15, v55, v159
	v_lshl_add_u32 v161, v39, 7, v160
	global_load_dwordx4 v[108:111], v161, s[14:15]
	s_waitcnt vmcnt(15)
	v_cvt_pk_f32_fp8_e32 v[144:145], v112
	v_cvt_pk_f32_fp8_sdwa v[146:147], v112 src0_sel:WORD_1
	v_cvt_pk_f32_fp8_e32 v[148:149], v113
	v_cvt_pk_f32_fp8_sdwa v[150:151], v113 src0_sel:WORD_1
	v_cvt_pk_f32_fp8_e32 v[152:153], v114
	v_cvt_pk_f32_fp8_sdwa v[154:155], v114 src0_sel:WORD_1
	v_cvt_pk_f32_fp8_e32 v[156:157], v115
	v_cvt_pk_f32_fp8_sdwa v[158:159], v115 src0_sel:WORD_1
	v_fmac_f32_e32 v0, v56, v144
	v_fmac_f32_e32 v1, v56, v145
	v_fmac_f32_e32 v2, v56, v146
	v_fmac_f32_e32 v3, v56, v147
	v_fmac_f32_e32 v4, v56, v148
	v_fmac_f32_e32 v5, v56, v149
	v_fmac_f32_e32 v6, v56, v150
	v_fmac_f32_e32 v7, v56, v151
	v_fmac_f32_e32 v8, v56, v152
	v_fmac_f32_e32 v9, v56, v153
	v_fmac_f32_e32 v10, v56, v154
	v_fmac_f32_e32 v11, v56, v155
	v_fmac_f32_e32 v12, v56, v156
	v_fmac_f32_e32 v13, v56, v157
	v_fmac_f32_e32 v14, v56, v158
	v_fmac_f32_e32 v15, v56, v159
	v_lshl_add_u32 v161, v40, 7, v160
	global_load_dwordx4 v[112:115], v161, s[14:15]
	s_waitcnt vmcnt(15)
	v_cvt_pk_f32_fp8_e32 v[144:145], v116
	v_cvt_pk_f32_fp8_sdwa v[146:147], v116 src0_sel:WORD_1
	v_cvt_pk_f32_fp8_e32 v[148:149], v117
	v_cvt_pk_f32_fp8_sdwa v[150:151], v117 src0_sel:WORD_1
	v_cvt_pk_f32_fp8_e32 v[152:153], v118
	v_cvt_pk_f32_fp8_sdwa v[154:155], v118 src0_sel:WORD_1
	v_cvt_pk_f32_fp8_e32 v[156:157], v119
	v_cvt_pk_f32_fp8_sdwa v[158:159], v119 src0_sel:WORD_1
	v_fmac_f32_e32 v0, v57, v144
	v_fmac_f32_e32 v1, v57, v145
	v_fmac_f32_e32 v2, v57, v146
	v_fmac_f32_e32 v3, v57, v147
	v_fmac_f32_e32 v4, v57, v148
	v_fmac_f32_e32 v5, v57, v149
	v_fmac_f32_e32 v6, v57, v150
	v_fmac_f32_e32 v7, v57, v151
	v_fmac_f32_e32 v8, v57, v152
	v_fmac_f32_e32 v9, v57, v153
	v_fmac_f32_e32 v10, v57, v154
	v_fmac_f32_e32 v11, v57, v155
	v_fmac_f32_e32 v12, v57, v156
	v_fmac_f32_e32 v13, v57, v157
	v_fmac_f32_e32 v14, v57, v158
	v_fmac_f32_e32 v15, v57, v159
	v_lshl_add_u32 v161, v41, 7, v160
	global_load_dwordx4 v[116:119], v161, s[14:15]
	s_waitcnt vmcnt(15)
	v_cvt_pk_f32_fp8_e32 v[144:145], v120
	v_cvt_pk_f32_fp8_sdwa v[146:147], v120 src0_sel:WORD_1
	v_cvt_pk_f32_fp8_e32 v[148:149], v121
	v_cvt_pk_f32_fp8_sdwa v[150:151], v121 src0_sel:WORD_1
	v_cvt_pk_f32_fp8_e32 v[152:153], v122
	v_cvt_pk_f32_fp8_sdwa v[154:155], v122 src0_sel:WORD_1
	v_cvt_pk_f32_fp8_e32 v[156:157], v123
	v_cvt_pk_f32_fp8_sdwa v[158:159], v123 src0_sel:WORD_1
	v_fmac_f32_e32 v0, v58, v144
	v_fmac_f32_e32 v1, v58, v145
	v_fmac_f32_e32 v2, v58, v146
	v_fmac_f32_e32 v3, v58, v147
	v_fmac_f32_e32 v4, v58, v148
	v_fmac_f32_e32 v5, v58, v149
	v_fmac_f32_e32 v6, v58, v150
	v_fmac_f32_e32 v7, v58, v151
	v_fmac_f32_e32 v8, v58, v152
	v_fmac_f32_e32 v9, v58, v153
	v_fmac_f32_e32 v10, v58, v154
	v_fmac_f32_e32 v11, v58, v155
	v_fmac_f32_e32 v12, v58, v156
	v_fmac_f32_e32 v13, v58, v157
	v_fmac_f32_e32 v14, v58, v158
	v_fmac_f32_e32 v15, v58, v159
	v_lshl_add_u32 v161, v42, 7, v160
	global_load_dwordx4 v[120:123], v161, s[14:15]
	s_waitcnt vmcnt(15)
; DI void phase_peer_b(const Params& p, int layer, const float* gnext, bool last) {
;     ...
;       u32x4 vr[16];
; #pragma unroll
;       for (int j = 0; j < 16; ++j) {
;         const int e = bt * 16 + j;
;         const int eidx = __builtin_amdgcn_readlane(e < 64 ? i0 : i1, e & 63);
;         vr[j] = *(const u32x4*)(EV + (size_t)eidx * DM + lane * 16);
;       }
; #pragma unroll
;       for (int j = 0; j < 16; ++j) {
;         const int e = bt * 16 + j;
;         const float wj = __int_as_float(__builtin_amdgcn_readlane(__float_as_int(e < 64 ? w0 : w1), e & 63));
; #pragma unroll
;         for (int w = 0; w < 4; ++w) {
;           const f32x2 lo = __builtin_amdgcn_cvt_pk_f32_fp8((int)vr[j][w], false);
;           const f32x2 hi = __builtin_amdgcn_cvt_pk_f32_fp8((int)vr[j][w], true);
;           acc[4 * w] += wj * lo[0]; acc[4 * w + 1] += wj * lo[1]; acc[4 * w + 2] += wj * hi[0]; acc[4 * w + 3] += wj * hi[1];
;         }
	v_cvt_pk_f32_fp8_e32 v[144:145], v124
	v_cvt_pk_f32_fp8_sdwa v[146:147], v124 src0_sel:WORD_1
	v_cvt_pk_f32_fp8_e32 v[148:149], v125
	v_cvt_pk_f32_fp8_sdwa v[150:151], v125 src0_sel:WORD_1
	v_cvt_pk_f32_fp8_e32 v[152:153], v126
	v_cvt_pk_f32_fp8_sdwa v[154:155], v126 src0_sel:WORD_1
	v_cvt_pk_f32_fp8_e32 v[156:157], v127
	v_cvt_pk_f32_fp8_sdwa v[158:159], v127 src0_sel:WORD_1
	v_fmac_f32_e32 v0, v59, v144
	v_fmac_f32_e32 v1, v59, v145
	v_fmac_f32_e32 v2, v59, v146
	v_fmac_f32_e32 v3, v59, v147
	v_fmac_f32_e32 v4, v59, v148
	v_fmac_f32_e32 v5, v59, v149
	v_fmac_f32_e32 v6, v59, v150
	v_fmac_f32_e32 v7, v59, v151
	v_fmac_f32_e32 v8, v59, v152
	v_fmac_f32_e32 v9, v59, v153
	v_fmac_f32_e32 v10, v59, v154
	v_fmac_f32_e32 v11, v59, v155
	v_fmac_f32_e32 v12, v59, v156
	v_fmac_f32_e32 v13, v59, v157
	v_fmac_f32_e32 v14, v59, v158
	v_fmac_f32_e32 v15, v59, v159
	v_lshl_add_u32 v161, v43, 7, v160
	global_load_dwordx4 v[124:127], v161, s[14:15]
	s_waitcnt vmcnt(15)
	v_cvt_pk_f32_fp8_e32 v[144:145], v128
	v_cvt_pk_f32_fp8_sdwa v[146:147], v128 src0_sel:WORD_1
	v_cvt_pk_f32_fp8_e32 v[148:149], v129
	v_cvt_pk_f32_fp8_sdwa v[150:151], v129 src0_sel:WORD_1
	v_cvt_pk_f32_fp8_e32 v[152:153], v130
	v_cvt_pk_f32_fp8_sdwa v[154:155], v130 src0_sel:WORD_1
	v_cvt_pk_f32_fp8_e32 v[156:157], v131
	v_cvt_pk_f32_fp8_sdwa v[158:159], v131 src0_sel:WORD_1
	v_fmac_f32_e32 v0, v60, v144
	v_fmac_f32_e32 v1, v60, v145
	v_fmac_f32_e32 v2, v60, v146
	v_fmac_f32_e32 v3, v60, v147
	v_fmac_f32_e32 v4, v60, v148
	v_fmac_f32_e32 v5, v60, v149
	v_fmac_f32_e32 v6, v60, v150
	v_fmac_f32_e32 v7, v60, v151
	v_fmac_f32_e32 v8, v60, v152
	v_fmac_f32_e32 v9, v60, v153
	v_fmac_f32_e32 v10, v60, v154
	v_fmac_f32_e32 v11, v60, v155
	v_fmac_f32_e32 v12, v60, v156
	v_fmac_f32_e32 v13, v60, v157
	v_fmac_f32_e32 v14, v60, v158
	v_fmac_f32_e32 v15, v60, v159
	v_lshl_add_u32 v161, v44, 7, v160
	global_load_dwordx4 v[128:131], v161, s[14:15]
	s_waitcnt vmcnt(15)
	v_cvt_pk_f32_fp8_e32 v[144:145], v132
	v_cvt_pk_f32_fp8_sdwa v[146:147], v132 src0_sel:WORD_1
	v_cvt_pk_f32_fp8_e32 v[148:149], v133
	v_cvt_pk_f32_fp8_sdwa v[150:151], v133 src0_sel:WORD_1
	v_cvt_pk_f32_fp8_e32 v[152:153], v134
	v_cvt_pk_f32_fp8_sdwa v[154:155], v134 src0_sel:WORD_1
	v_cvt_pk_f32_fp8_e32 v[156:157], v135
	v_cvt_pk_f32_fp8_sdwa v[158:159], v135 src0_sel:WORD_1
	v_fmac_f32_e32 v0, v61, v144
	v_fmac_f32_e32 v1, v61, v145
	v_fmac_f32_e32 v2, v61, v146
	v_fmac_f32_e32 v3, v61, v147
	v_fmac_f32_e32 v4, v61, v148
	v_fmac_f32_e32 v5, v61, v149
	v_fmac_f32_e32 v6, v61, v150
	v_fmac_f32_e32 v7, v61, v151
	v_fmac_f32_e32 v8, v61, v152
	v_fmac_f32_e32 v9, v61, v153
	v_fmac_f32_e32 v10, v61, v154
	v_fmac_f32_e32 v11, v61, v155
	v_fmac_f32_e32 v12, v61, v156
	v_fmac_f32_e32 v13, v61, v157
	v_fmac_f32_e32 v14, v61, v158
	v_fmac_f32_e32 v15, v61, v159
	v_lshl_add_u32 v161, v45, 7, v160
	global_load_dwordx4 v[132:135], v161, s[14:15]
	s_waitcnt vmcnt(15)
	v_cvt_pk_f32_fp8_e32 v[144:145], v136
	v_cvt_pk_f32_fp8_sdwa v[146:147], v136 src0_sel:WORD_1
	v_cvt_pk_f32_fp8_e32 v[148:149], v137
	v_cvt_pk_f32_fp8_sdwa v[150:151], v137 src0_sel:WORD_1
	v_cvt_pk_f32_fp8_e32 v[152:153], v138
	v_cvt_pk_f32_fp8_sdwa v[154:155], v138 src0_sel:WORD_1
	v_cvt_pk_f32_fp8_e32 v[156:157], v139
	v_cvt_pk_f32_fp8_sdwa v[158:159], v139 src0_sel:WORD_1
	v_fmac_f32_e32 v0, v62, v144
	v_fmac_f32_e32 v1, v62, v145
	v_fmac_f32_e32 v2, v62, v146
	v_fmac_f32_e32 v3, v62, v147
	v_fmac_f32_e32 v4, v62, v148
	v_fmac_f32_e32 v5, v62, v149
	v_fmac_f32_e32 v6, v62, v150
	v_fmac_f32_e32 v7, v62, v151
	v_fmac_f32_e32 v8, v62, v152
	v_fmac_f32_e32 v9, v62, v153
	v_fmac_f32_e32 v10, v62, v154
	v_fmac_f32_e32 v11, v62, v155
	v_fmac_f32_e32 v12, v62, v156
	v_fmac_f32_e32 v13, v62, v157
	v_fmac_f32_e32 v14, v62, v158
	v_fmac_f32_e32 v15, v62, v159
	v_lshl_add_u32 v161, v46, 7, v160
	global_load_dwordx4 v[136:139], v161, s[14:15]
	s_waitcnt vmcnt(15)
	v_cvt_pk_f32_fp8_e32 v[144:145], v140
	v_cvt_pk_f32_fp8_sdwa v[146:147], v140 src0_sel:WORD_1
	v_cvt_pk_f32_fp8_e32 v[148:149], v141
	v_cvt_pk_f32_fp8_sdwa v[150:151], v141 src0_sel:WORD_1
	v_cvt_pk_f32_fp8_e32 v[152:153], v142
	v_cvt_pk_f32_fp8_sdwa v[154:155], v142 src0_sel:WORD_1
	v_cvt_pk_f32_fp8_e32 v[156:157], v143
	v_cvt_pk_f32_fp8_sdwa v[158:159], v143 src0_sel:WORD_1
	v_fmac_f32_e32 v0, v63, v144
	v_fmac_f32_e32 v1, v63, v145
	v_fmac_f32_e32 v2, v63, v146
	v_fmac_f32_e32 v3, v63, v147
	v_fmac_f32_e32 v4, v63, v148
	v_fmac_f32_e32 v5, v63, v149
	v_fmac_f32_e32 v6, v63, v150
	v_fmac_f32_e32 v7, v63, v151
	v_fmac_f32_e32 v8, v63, v152
	v_fmac_f32_e32 v9, v63, v153
	v_fmac_f32_e32 v10, v63, v154
	v_fmac_f32_e32 v11, v63, v155
	v_fmac_f32_e32 v12, v63, v156
	v_fmac_f32_e32 v13, v63, v157
	v_fmac_f32_e32 v14, v63, v158
	v_fmac_f32_e32 v15, v63, v159
	v_lshl_add_u32 v161, v47, 7, v160
	global_load_dwordx4 v[140:143], v161, s[14:15]
	s_waitcnt lgkmcnt(0)
	ds_read_b128 v[32:35], v163 offset:320
	ds_read_b128 v[36:39], v163 offset:336
	ds_read_b128 v[40:43], v163 offset:352
	ds_read_b128 v[44:47], v163 offset:368
	ds_read_b128 v[48:51], v163 offset:4480
	ds_read_b128 v[52:55], v163 offset:4496
	ds_read_b128 v[56:59], v163 offset:4512
	ds_read_b128 v[60:63], v163 offset:4528
	s_waitcnt vmcnt(15)
; DI void phase_peer_b(const Params& p, int layer, const float* gnext, bool last) {
;     ...
;       for (int j = 0; j < 16; ++j) {
;         const int e = bt * 16 + j;
;         const int eidx = __builtin_amdgcn_readlane(e < 64 ? i0 : i1, e & 63);
;         vr[j] = *(const u32x4*)(EV + (size_t)eidx * DM + lane * 16);
;       }
; #pragma unroll
;       for (int j = 0; j < 16; ++j) {
;         const int e = bt * 16 + j;
;         const float wj = __int_as_float(__builtin_amdgcn_readlane(__float_as_int(e < 64 ? w0 : w1), e & 63));
; #pragma unroll
;         for (int w = 0; w < 4; ++w) {
;           const f32x2 lo = __builtin_amdgcn_cvt_pk_f32_fp8((int)vr[j][w], false);
;           const f32x2 hi = __builtin_amdgcn_cvt_pk_f32_fp8((int)vr[j][w], true);
;           acc[4 * w] += wj * lo[0]; acc[4 * w + 1] += wj * lo[1]; acc[4 * w + 2] += wj * hi[0]; acc[4 * w + 3] += wj * hi[1];
;         }
	v_cvt_pk_f32_fp8_e32 v[144:145], v80
	v_cvt_pk_f32_fp8_sdwa v[146:147], v80 src0_sel:WORD_1
	v_cvt_pk_f32_fp8_e32 v[148:149], v81
	v_cvt_pk_f32_fp8_sdwa v[150:151], v81 src0_sel:WORD_1
	v_cvt_pk_f32_fp8_e32 v[152:153], v82
	v_cvt_pk_f32_fp8_sdwa v[154:155], v82 src0_sel:WORD_1
	v_cvt_pk_f32_fp8_e32 v[156:157], v83
	v_cvt_pk_f32_fp8_sdwa v[158:159], v83 src0_sel:WORD_1
	v_fmac_f32_e32 v0, v64, v144
	v_fmac_f32_e32 v1, v64, v145
	v_fmac_f32_e32 v2, v64, v146
	v_fmac_f32_e32 v3, v64, v147
	v_fmac_f32_e32 v4, v64, v148
	v_fmac_f32_e32 v5, v64, v149
	v_fmac_f32_e32 v6, v64, v150
	v_fmac_f32_e32 v7, v64, v151
	v_fmac_f32_e32 v8, v64, v152
	v_fmac_f32_e32 v9, v64, v153
	v_fmac_f32_e32 v10, v64, v154
	v_fmac_f32_e32 v11, v64, v155
	v_fmac_f32_e32 v12, v64, v156
	v_fmac_f32_e32 v13, v64, v157
	v_fmac_f32_e32 v14, v64, v158
	v_fmac_f32_e32 v15, v64, v159
	v_lshl_add_u32 v161, v16, 7, v160
	global_load_dwordx4 v[80:83], v161, s[14:15]
	s_waitcnt vmcnt(15)
	v_cvt_pk_f32_fp8_e32 v[144:145], v84
	v_cvt_pk_f32_fp8_sdwa v[146:147], v84 src0_sel:WORD_1
	v_cvt_pk_f32_fp8_e32 v[148:149], v85
	v_cvt_pk_f32_fp8_sdwa v[150:151], v85 src0_sel:WORD_1
	v_cvt_pk_f32_fp8_e32 v[152:153], v86
	v_cvt_pk_f32_fp8_sdwa v[154:155], v86 src0_sel:WORD_1
	v_cvt_pk_f32_fp8_e32 v[156:157], v87
	v_cvt_pk_f32_fp8_sdwa v[158:159], v87 src0_sel:WORD_1
	v_fmac_f32_e32 v0, v65, v144
	v_fmac_f32_e32 v1, v65, v145
	v_fmac_f32_e32 v2, v65, v146
	v_fmac_f32_e32 v3, v65, v147
	v_fmac_f32_e32 v4, v65, v148
	v_fmac_f32_e32 v5, v65, v149
	v_fmac_f32_e32 v6, v65, v150
	v_fmac_f32_e32 v7, v65, v151
	v_fmac_f32_e32 v8, v65, v152
	v_fmac_f32_e32 v9, v65, v153
	v_fmac_f32_e32 v10, v65, v154
	v_fmac_f32_e32 v11, v65, v155
	v_fmac_f32_e32 v12, v65, v156
	v_fmac_f32_e32 v13, v65, v157
	v_fmac_f32_e32 v14, v65, v158
	v_fmac_f32_e32 v15, v65, v159
	v_lshl_add_u32 v161, v17, 7, v160
	global_load_dwordx4 v[84:87], v161, s[14:15]
	s_waitcnt vmcnt(15)
	v_cvt_pk_f32_fp8_e32 v[144:145], v88
	v_cvt_pk_f32_fp8_sdwa v[146:147], v88 src0_sel:WORD_1
	v_cvt_pk_f32_fp8_e32 v[148:149], v89
	v_cvt_pk_f32_fp8_sdwa v[150:151], v89 src0_sel:WORD_1
	v_cvt_pk_f32_fp8_e32 v[152:153], v90
	v_cvt_pk_f32_fp8_sdwa v[154:155], v90 src0_sel:WORD_1
	v_cvt_pk_f32_fp8_e32 v[156:157], v91
	v_cvt_pk_f32_fp8_sdwa v[158:159], v91 src0_sel:WORD_1
	v_fmac_f32_e32 v0, v66, v144
	v_fmac_f32_e32 v1, v66, v145
	v_fmac_f32_e32 v2, v66, v146
	v_fmac_f32_e32 v3, v66, v147
	v_fmac_f32_e32 v4, v66, v148
	v_fmac_f32_e32 v5, v66, v149
	v_fmac_f32_e32 v6, v66, v150
	v_fmac_f32_e32 v7, v66, v151
	v_fmac_f32_e32 v8, v66, v152
	v_fmac_f32_e32 v9, v66, v153
	v_fmac_f32_e32 v10, v66, v154
	v_fmac_f32_e32 v11, v66, v155
	v_fmac_f32_e32 v12, v66, v156
	v_fmac_f32_e32 v13, v66, v157
	v_fmac_f32_e32 v14, v66, v158
	v_fmac_f32_e32 v15, v66, v159
	v_lshl_add_u32 v161, v18, 7, v160
	global_load_dwordx4 v[88:91], v161, s[14:15]
	s_waitcnt vmcnt(15)
	v_cvt_pk_f32_fp8_e32 v[144:145], v92
	v_cvt_pk_f32_fp8_sdwa v[146:147], v92 src0_sel:WORD_1
	v_cvt_pk_f32_fp8_e32 v[148:149], v93
	v_cvt_pk_f32_fp8_sdwa v[150:151], v93 src0_sel:WORD_1
	v_cvt_pk_f32_fp8_e32 v[152:153], v94
	v_cvt_pk_f32_fp8_sdwa v[154:155], v94 src0_sel:WORD_1
	v_cvt_pk_f32_fp8_e32 v[156:157], v95
	v_cvt_pk_f32_fp8_sdwa v[158:159], v95 src0_sel:WORD_1
	v_fmac_f32_e32 v0, v67, v144
	v_fmac_f32_e32 v1, v67, v145
	v_fmac_f32_e32 v2, v67, v146
	v_fmac_f32_e32 v3, v67, v147
	v_fmac_f32_e32 v4, v67, v148
	v_fmac_f32_e32 v5, v67, v149
	v_fmac_f32_e32 v6, v67, v150
	v_fmac_f32_e32 v7, v67, v151
	v_fmac_f32_e32 v8, v67, v152
	v_fmac_f32_e32 v9, v67, v153
	v_fmac_f32_e32 v10, v67, v154
	v_fmac_f32_e32 v11, v67, v155
	v_fmac_f32_e32 v12, v67, v156
	v_fmac_f32_e32 v13, v67, v157
	v_fmac_f32_e32 v14, v67, v158
	v_fmac_f32_e32 v15, v67, v159
	v_lshl_add_u32 v161, v19, 7, v160
	global_load_dwordx4 v[92:95], v161, s[14:15]
	s_waitcnt vmcnt(15)
	v_cvt_pk_f32_fp8_e32 v[144:145], v96
	v_cvt_pk_f32_fp8_sdwa v[146:147], v96 src0_sel:WORD_1
	v_cvt_pk_f32_fp8_e32 v[148:149], v97
	v_cvt_pk_f32_fp8_sdwa v[150:151], v97 src0_sel:WORD_1
	v_cvt_pk_f32_fp8_e32 v[152:153], v98
	v_cvt_pk_f32_fp8_sdwa v[154:155], v98 src0_sel:WORD_1
	v_cvt_pk_f32_fp8_e32 v[156:157], v99
	v_cvt_pk_f32_fp8_sdwa v[158:159], v99 src0_sel:WORD_1
	v_fmac_f32_e32 v0, v68, v144
	v_fmac_f32_e32 v1, v68, v145
	v_fmac_f32_e32 v2, v68, v146
	v_fmac_f32_e32 v3, v68, v147
	v_fmac_f32_e32 v4, v68, v148
	v_fmac_f32_e32 v5, v68, v149
	v_fmac_f32_e32 v6, v68, v150
	v_fmac_f32_e32 v7, v68, v151
	v_fmac_f32_e32 v8, v68, v152
	v_fmac_f32_e32 v9, v68, v153
	v_fmac_f32_e32 v10, v68, v154
	v_fmac_f32_e32 v11, v68, v155
	v_fmac_f32_e32 v12, v68, v156
	v_fmac_f32_e32 v13, v68, v157
	v_fmac_f32_e32 v14, v68, v158
	v_fmac_f32_e32 v15, v68, v159
	v_lshl_add_u32 v161, v20, 7, v160
	global_load_dwordx4 v[96:99], v161, s[14:15]
	s_waitcnt vmcnt(15)
	v_cvt_pk_f32_fp8_e32 v[144:145], v100
	v_cvt_pk_f32_fp8_sdwa v[146:147], v100 src0_sel:WORD_1
	v_cvt_pk_f32_fp8_e32 v[148:149], v101
	v_cvt_pk_f32_fp8_sdwa v[150:151], v101 src0_sel:WORD_1
	v_cvt_pk_f32_fp8_e32 v[152:153], v102
	v_cvt_pk_f32_fp8_sdwa v[154:155], v102 src0_sel:WORD_1
	v_cvt_pk_f32_fp8_e32 v[156:157], v103
	v_cvt_pk_f32_fp8_sdwa v[158:159], v103 src0_sel:WORD_1
	v_fmac_f32_e32 v0, v69, v144
	v_fmac_f32_e32 v1, v69, v145
	v_fmac_f32_e32 v2, v69, v146
	v_fmac_f32_e32 v3, v69, v147
	v_fmac_f32_e32 v4, v69, v148
	v_fmac_f32_e32 v5, v69, v149
	v_fmac_f32_e32 v6, v69, v150
	v_fmac_f32_e32 v7, v69, v151
	v_fmac_f32_e32 v8, v69, v152
	v_fmac_f32_e32 v9, v69, v153
	v_fmac_f32_e32 v10, v69, v154
	v_fmac_f32_e32 v11, v69, v155
	v_fmac_f32_e32 v12, v69, v156
	v_fmac_f32_e32 v13, v69, v157
	v_fmac_f32_e32 v14, v69, v158
	v_fmac_f32_e32 v15, v69, v159
	v_lshl_add_u32 v161, v21, 7, v160
	global_load_dwordx4 v[100:103], v161, s[14:15]
	s_waitcnt vmcnt(15)
; DI void phase_peer_b(const Params& p, int layer, const float* gnext, bool last) {
;     ...
;       for (int j = 0; j < 16; ++j) {
;         const int e = bt * 16 + j;
;         const int eidx = __builtin_amdgcn_readlane(e < 64 ? i0 : i1, e & 63);
;         vr[j] = *(const u32x4*)(EV + (size_t)eidx * DM + lane * 16);
;       }
; #pragma unroll
;       for (int j = 0; j < 16; ++j) {
;         const int e = bt * 16 + j;
;         const float wj = __int_as_float(__builtin_amdgcn_readlane(__float_as_int(e < 64 ? w0 : w1), e & 63));
; #pragma unroll
;         for (int w = 0; w < 4; ++w) {
;           const f32x2 lo = __builtin_amdgcn_cvt_pk_f32_fp8((int)vr[j][w], false);
;           const f32x2 hi = __builtin_amdgcn_cvt_pk_f32_fp8((int)vr[j][w], true);
;           acc[4 * w] += wj * lo[0]; acc[4 * w + 1] += wj * lo[1]; acc[4 * w + 2] += wj * hi[0]; acc[4 * w + 3] += wj * hi[1];
;         }
	v_cvt_pk_f32_fp8_e32 v[144:145], v104
	v_cvt_pk_f32_fp8_sdwa v[146:147], v104 src0_sel:WORD_1
	v_cvt_pk_f32_fp8_e32 v[148:149], v105
	v_cvt_pk_f32_fp8_sdwa v[150:151], v105 src0_sel:WORD_1
	v_cvt_pk_f32_fp8_e32 v[152:153], v106
	v_cvt_pk_f32_fp8_sdwa v[154:155], v106 src0_sel:WORD_1
	v_cvt_pk_f32_fp8_e32 v[156:157], v107
	v_cvt_pk_f32_fp8_sdwa v[158:159], v107 src0_sel:WORD_1
	v_fmac_f32_e32 v0, v70, v144
	v_fmac_f32_e32 v1, v70, v145
	v_fmac_f32_e32 v2, v70, v146
	v_fmac_f32_e32 v3, v70, v147
	v_fmac_f32_e32 v4, v70, v148
	v_fmac_f32_e32 v5, v70, v149
	v_fmac_f32_e32 v6, v70, v150
	v_fmac_f32_e32 v7, v70, v151
	v_fmac_f32_e32 v8, v70, v152
	v_fmac_f32_e32 v9, v70, v153
	v_fmac_f32_e32 v10, v70, v154
	v_fmac_f32_e32 v11, v70, v155
	v_fmac_f32_e32 v12, v70, v156
	v_fmac_f32_e32 v13, v70, v157
	v_fmac_f32_e32 v14, v70, v158
	v_fmac_f32_e32 v15, v70, v159
	v_lshl_add_u32 v161, v22, 7, v160
	global_load_dwordx4 v[104:107], v161, s[14:15]
	s_waitcnt vmcnt(15)
	v_cvt_pk_f32_fp8_e32 v[144:145], v108
	v_cvt_pk_f32_fp8_sdwa v[146:147], v108 src0_sel:WORD_1
	v_cvt_pk_f32_fp8_e32 v[148:149], v109
	v_cvt_pk_f32_fp8_sdwa v[150:151], v109 src0_sel:WORD_1
	v_cvt_pk_f32_fp8_e32 v[152:153], v110
	v_cvt_pk_f32_fp8_sdwa v[154:155], v110 src0_sel:WORD_1
	v_cvt_pk_f32_fp8_e32 v[156:157], v111
	v_cvt_pk_f32_fp8_sdwa v[158:159], v111 src0_sel:WORD_1
	v_fmac_f32_e32 v0, v71, v144
	v_fmac_f32_e32 v1, v71, v145
	v_fmac_f32_e32 v2, v71, v146
	v_fmac_f32_e32 v3, v71, v147
	v_fmac_f32_e32 v4, v71, v148
	v_fmac_f32_e32 v5, v71, v149
	v_fmac_f32_e32 v6, v71, v150
	v_fmac_f32_e32 v7, v71, v151
	v_fmac_f32_e32 v8, v71, v152
	v_fmac_f32_e32 v9, v71, v153
	v_fmac_f32_e32 v10, v71, v154
	v_fmac_f32_e32 v11, v71, v155
	v_fmac_f32_e32 v12, v71, v156
	v_fmac_f32_e32 v13, v71, v157
	v_fmac_f32_e32 v14, v71, v158
	v_fmac_f32_e32 v15, v71, v159
	v_lshl_add_u32 v161, v23, 7, v160
	global_load_dwordx4 v[108:111], v161, s[14:15]
	s_waitcnt vmcnt(15)
	v_cvt_pk_f32_fp8_e32 v[144:145], v112
	v_cvt_pk_f32_fp8_sdwa v[146:147], v112 src0_sel:WORD_1
	v_cvt_pk_f32_fp8_e32 v[148:149], v113
	v_cvt_pk_f32_fp8_sdwa v[150:151], v113 src0_sel:WORD_1
	v_cvt_pk_f32_fp8_e32 v[152:153], v114
	v_cvt_pk_f32_fp8_sdwa v[154:155], v114 src0_sel:WORD_1
	v_cvt_pk_f32_fp8_e32 v[156:157], v115
	v_cvt_pk_f32_fp8_sdwa v[158:159], v115 src0_sel:WORD_1
	v_fmac_f32_e32 v0, v72, v144
	v_fmac_f32_e32 v1, v72, v145
	v_fmac_f32_e32 v2, v72, v146
	v_fmac_f32_e32 v3, v72, v147
	v_fmac_f32_e32 v4, v72, v148
	v_fmac_f32_e32 v5, v72, v149
	v_fmac_f32_e32 v6, v72, v150
	v_fmac_f32_e32 v7, v72, v151
	v_fmac_f32_e32 v8, v72, v152
	v_fmac_f32_e32 v9, v72, v153
	v_fmac_f32_e32 v10, v72, v154
	v_fmac_f32_e32 v11, v72, v155
	v_fmac_f32_e32 v12, v72, v156
	v_fmac_f32_e32 v13, v72, v157
	v_fmac_f32_e32 v14, v72, v158
	v_fmac_f32_e32 v15, v72, v159
	v_lshl_add_u32 v161, v24, 7, v160
	global_load_dwordx4 v[112:115], v161, s[14:15]
	s_waitcnt vmcnt(15)
	v_cvt_pk_f32_fp8_e32 v[144:145], v116
	v_cvt_pk_f32_fp8_sdwa v[146:147], v116 src0_sel:WORD_1
	v_cvt_pk_f32_fp8_e32 v[148:149], v117
	v_cvt_pk_f32_fp8_sdwa v[150:151], v117 src0_sel:WORD_1
	v_cvt_pk_f32_fp8_e32 v[152:153], v118
	v_cvt_pk_f32_fp8_sdwa v[154:155], v118 src0_sel:WORD_1
	v_cvt_pk_f32_fp8_e32 v[156:157], v119
	v_cvt_pk_f32_fp8_sdwa v[158:159], v119 src0_sel:WORD_1
	v_fmac_f32_e32 v0, v73, v144
	v_fmac_f32_e32 v1, v73, v145
	v_fmac_f32_e32 v2, v73, v146
	v_fmac_f32_e32 v3, v73, v147
	v_fmac_f32_e32 v4, v73, v148
	v_fmac_f32_e32 v5, v73, v149
	v_fmac_f32_e32 v6, v73, v150
	v_fmac_f32_e32 v7, v73, v151
	v_fmac_f32_e32 v8, v73, v152
	v_fmac_f32_e32 v9, v73, v153
	v_fmac_f32_e32 v10, v73, v154
	v_fmac_f32_e32 v11, v73, v155
	v_fmac_f32_e32 v12, v73, v156
	v_fmac_f32_e32 v13, v73, v157
	v_fmac_f32_e32 v14, v73, v158
	v_fmac_f32_e32 v15, v73, v159
	v_lshl_add_u32 v161, v25, 7, v160
	global_load_dwordx4 v[116:119], v161, s[14:15]
	s_waitcnt vmcnt(15)
	v_cvt_pk_f32_fp8_e32 v[144:145], v120
	v_cvt_pk_f32_fp8_sdwa v[146:147], v120 src0_sel:WORD_1
	v_cvt_pk_f32_fp8_e32 v[148:149], v121
	v_cvt_pk_f32_fp8_sdwa v[150:151], v121 src0_sel:WORD_1
	v_cvt_pk_f32_fp8_e32 v[152:153], v122
	v_cvt_pk_f32_fp8_sdwa v[154:155], v122 src0_sel:WORD_1
	v_cvt_pk_f32_fp8_e32 v[156:157], v123
	v_cvt_pk_f32_fp8_sdwa v[158:159], v123 src0_sel:WORD_1
	v_fmac_f32_e32 v0, v74, v144
	v_fmac_f32_e32 v1, v74, v145
	v_fmac_f32_e32 v2, v74, v146
	v_fmac_f32_e32 v3, v74, v147
	v_fmac_f32_e32 v4, v74, v148
	v_fmac_f32_e32 v5, v74, v149
	v_fmac_f32_e32 v6, v74, v150
	v_fmac_f32_e32 v7, v74, v151
	v_fmac_f32_e32 v8, v74, v152
	v_fmac_f32_e32 v9, v74, v153
	v_fmac_f32_e32 v10, v74, v154
	v_fmac_f32_e32 v11, v74, v155
	v_fmac_f32_e32 v12, v74, v156
	v_fmac_f32_e32 v13, v74, v157
	v_fmac_f32_e32 v14, v74, v158
	v_fmac_f32_e32 v15, v74, v159
	v_lshl_add_u32 v161, v26, 7, v160
	global_load_dwordx4 v[120:123], v161, s[14:15]
	s_waitcnt vmcnt(15)
	v_cvt_pk_f32_fp8_e32 v[144:145], v124
	v_cvt_pk_f32_fp8_sdwa v[146:147], v124 src0_sel:WORD_1
	v_cvt_pk_f32_fp8_e32 v[148:149], v125
	v_cvt_pk_f32_fp8_sdwa v[150:151], v125 src0_sel:WORD_1
	v_cvt_pk_f32_fp8_e32 v[152:153], v126
	v_cvt_pk_f32_fp8_sdwa v[154:155], v126 src0_sel:WORD_1
	v_cvt_pk_f32_fp8_e32 v[156:157], v127
	v_cvt_pk_f32_fp8_sdwa v[158:159], v127 src0_sel:WORD_1
	v_fmac_f32_e32 v0, v75, v144
	v_fmac_f32_e32 v1, v75, v145
	v_fmac_f32_e32 v2, v75, v146
	v_fmac_f32_e32 v3, v75, v147
	v_fmac_f32_e32 v4, v75, v148
	v_fmac_f32_e32 v5, v75, v149
	v_fmac_f32_e32 v6, v75, v150
	v_fmac_f32_e32 v7, v75, v151
	v_fmac_f32_e32 v8, v75, v152
	v_fmac_f32_e32 v9, v75, v153
	v_fmac_f32_e32 v10, v75, v154
	v_fmac_f32_e32 v11, v75, v155
	v_fmac_f32_e32 v12, v75, v156
	v_fmac_f32_e32 v13, v75, v157
	v_fmac_f32_e32 v14, v75, v158
	v_fmac_f32_e32 v15, v75, v159
	v_lshl_add_u32 v161, v27, 7, v160
	global_load_dwordx4 v[124:127], v161, s[14:15]
	s_waitcnt vmcnt(15)
; DI void phase_peer_b(const Params& p, int layer, const float* gnext, bool last) {
;     ...
;       u32x4 vr[16];
; #pragma unroll
;       for (int j = 0; j < 16; ++j) {
;         const int e = bt * 16 + j;
;         const int eidx = __builtin_amdgcn_readlane(e < 64 ? i0 : i1, e & 63);
;         vr[j] = *(const u32x4*)(EV + (size_t)eidx * DM + lane * 16);
;       }
; #pragma unroll
;       for (int j = 0; j < 16; ++j) {
;         const int e = bt * 16 + j;
;         const float wj = __int_as_float(__builtin_amdgcn_readlane(__float_as_int(e < 64 ? w0 : w1), e & 63));
; #pragma unroll
;         for (int w = 0; w < 4; ++w) {
;           const f32x2 lo = __builtin_amdgcn_cvt_pk_f32_fp8((int)vr[j][w], false);
;           const f32x2 hi = __builtin_amdgcn_cvt_pk_f32_fp8((int)vr[j][w], true);
;           acc[4 * w] += wj * lo[0]; acc[4 * w + 1] += wj * lo[1]; acc[4 * w + 2] += wj * hi[0]; acc[4 * w + 3] += wj * hi[1];
;         }
	v_cvt_pk_f32_fp8_e32 v[144:145], v128
	v_cvt_pk_f32_fp8_sdwa v[146:147], v128 src0_sel:WORD_1
	v_cvt_pk_f32_fp8_e32 v[148:149], v129
	v_cvt_pk_f32_fp8_sdwa v[150:151], v129 src0_sel:WORD_1
	v_cvt_pk_f32_fp8_e32 v[152:153], v130
	v_cvt_pk_f32_fp8_sdwa v[154:155], v130 src0_sel:WORD_1
	v_cvt_pk_f32_fp8_e32 v[156:157], v131
	v_cvt_pk_f32_fp8_sdwa v[158:159], v131 src0_sel:WORD_1
	v_fmac_f32_e32 v0, v76, v144
	v_fmac_f32_e32 v1, v76, v145
	v_fmac_f32_e32 v2, v76, v146
	v_fmac_f32_e32 v3, v76, v147
	v_fmac_f32_e32 v4, v76, v148
	v_fmac_f32_e32 v5, v76, v149
	v_fmac_f32_e32 v6, v76, v150
	v_fmac_f32_e32 v7, v76, v151
	v_fmac_f32_e32 v8, v76, v152
	v_fmac_f32_e32 v9, v76, v153
	v_fmac_f32_e32 v10, v76, v154
	v_fmac_f32_e32 v11, v76, v155
	v_fmac_f32_e32 v12, v76, v156
	v_fmac_f32_e32 v13, v76, v157
	v_fmac_f32_e32 v14, v76, v158
	v_fmac_f32_e32 v15, v76, v159
	v_lshl_add_u32 v161, v28, 7, v160
	global_load_dwordx4 v[128:131], v161, s[14:15]
	s_waitcnt vmcnt(15)
	v_cvt_pk_f32_fp8_e32 v[144:145], v132
	v_cvt_pk_f32_fp8_sdwa v[146:147], v132 src0_sel:WORD_1
	v_cvt_pk_f32_fp8_e32 v[148:149], v133
	v_cvt_pk_f32_fp8_sdwa v[150:151], v133 src0_sel:WORD_1
	v_cvt_pk_f32_fp8_e32 v[152:153], v134
	v_cvt_pk_f32_fp8_sdwa v[154:155], v134 src0_sel:WORD_1
	v_cvt_pk_f32_fp8_e32 v[156:157], v135
	v_cvt_pk_f32_fp8_sdwa v[158:159], v135 src0_sel:WORD_1
	v_fmac_f32_e32 v0, v77, v144
	v_fmac_f32_e32 v1, v77, v145
	v_fmac_f32_e32 v2, v77, v146
	v_fmac_f32_e32 v3, v77, v147
	v_fmac_f32_e32 v4, v77, v148
	v_fmac_f32_e32 v5, v77, v149
	v_fmac_f32_e32 v6, v77, v150
	v_fmac_f32_e32 v7, v77, v151
	v_fmac_f32_e32 v8, v77, v152
	v_fmac_f32_e32 v9, v77, v153
	v_fmac_f32_e32 v10, v77, v154
	v_fmac_f32_e32 v11, v77, v155
	v_fmac_f32_e32 v12, v77, v156
	v_fmac_f32_e32 v13, v77, v157
	v_fmac_f32_e32 v14, v77, v158
	v_fmac_f32_e32 v15, v77, v159
	v_lshl_add_u32 v161, v29, 7, v160
	global_load_dwordx4 v[132:135], v161, s[14:15]
	s_waitcnt vmcnt(15)
	v_cvt_pk_f32_fp8_e32 v[144:145], v136
	v_cvt_pk_f32_fp8_sdwa v[146:147], v136 src0_sel:WORD_1
	v_cvt_pk_f32_fp8_e32 v[148:149], v137
	v_cvt_pk_f32_fp8_sdwa v[150:151], v137 src0_sel:WORD_1
	v_cvt_pk_f32_fp8_e32 v[152:153], v138
	v_cvt_pk_f32_fp8_sdwa v[154:155], v138 src0_sel:WORD_1
	v_cvt_pk_f32_fp8_e32 v[156:157], v139
	v_cvt_pk_f32_fp8_sdwa v[158:159], v139 src0_sel:WORD_1
	v_fmac_f32_e32 v0, v78, v144
	v_fmac_f32_e32 v1, v78, v145
	v_fmac_f32_e32 v2, v78, v146
	v_fmac_f32_e32 v3, v78, v147
	v_fmac_f32_e32 v4, v78, v148
	v_fmac_f32_e32 v5, v78, v149
	v_fmac_f32_e32 v6, v78, v150
	v_fmac_f32_e32 v7, v78, v151
	v_fmac_f32_e32 v8, v78, v152
	v_fmac_f32_e32 v9, v78, v153
	v_fmac_f32_e32 v10, v78, v154
	v_fmac_f32_e32 v11, v78, v155
	v_fmac_f32_e32 v12, v78, v156
	v_fmac_f32_e32 v13, v78, v157
	v_fmac_f32_e32 v14, v78, v158
	v_fmac_f32_e32 v15, v78, v159
	v_lshl_add_u32 v161, v30, 7, v160
	global_load_dwordx4 v[136:139], v161, s[14:15]
	s_waitcnt vmcnt(15)
	v_cvt_pk_f32_fp8_e32 v[144:145], v140
	v_cvt_pk_f32_fp8_sdwa v[146:147], v140 src0_sel:WORD_1
	v_cvt_pk_f32_fp8_e32 v[148:149], v141
	v_cvt_pk_f32_fp8_sdwa v[150:151], v141 src0_sel:WORD_1
	v_cvt_pk_f32_fp8_e32 v[152:153], v142
	v_cvt_pk_f32_fp8_sdwa v[154:155], v142 src0_sel:WORD_1
	v_cvt_pk_f32_fp8_e32 v[156:157], v143
	v_cvt_pk_f32_fp8_sdwa v[158:159], v143 src0_sel:WORD_1
	v_fmac_f32_e32 v0, v79, v144
	v_fmac_f32_e32 v1, v79, v145
	v_fmac_f32_e32 v2, v79, v146
	v_fmac_f32_e32 v3, v79, v147
	v_fmac_f32_e32 v4, v79, v148
	v_fmac_f32_e32 v5, v79, v149
	v_fmac_f32_e32 v6, v79, v150
	v_fmac_f32_e32 v7, v79, v151
	v_fmac_f32_e32 v8, v79, v152
	v_fmac_f32_e32 v9, v79, v153
	v_fmac_f32_e32 v10, v79, v154
	v_fmac_f32_e32 v11, v79, v155
	v_fmac_f32_e32 v12, v79, v156
	v_fmac_f32_e32 v13, v79, v157
	v_fmac_f32_e32 v14, v79, v158
	v_fmac_f32_e32 v15, v79, v159
	v_lshl_add_u32 v161, v31, 7, v160
	global_load_dwordx4 v[140:143], v161, s[14:15]
	s_waitcnt lgkmcnt(0)
	ds_read_b128 v[16:19], v163 offset:384
	ds_read_b128 v[20:23], v163 offset:400
	ds_read_b128 v[24:27], v163 offset:416
	ds_read_b128 v[28:31], v163 offset:432
	ds_read_b128 v[64:67], v163 offset:4544
	ds_read_b128 v[68:71], v163 offset:4560
	ds_read_b128 v[72:75], v163 offset:4576
	ds_read_b128 v[76:79], v163 offset:4592
	s_waitcnt vmcnt(15)
	v_cvt_pk_f32_fp8_e32 v[144:145], v80
	v_cvt_pk_f32_fp8_sdwa v[146:147], v80 src0_sel:WORD_1
	v_cvt_pk_f32_fp8_e32 v[148:149], v81
	v_cvt_pk_f32_fp8_sdwa v[150:151], v81 src0_sel:WORD_1
	v_cvt_pk_f32_fp8_e32 v[152:153], v82
	v_cvt_pk_f32_fp8_sdwa v[154:155], v82 src0_sel:WORD_1
	v_cvt_pk_f32_fp8_e32 v[156:157], v83
	v_cvt_pk_f32_fp8_sdwa v[158:159], v83 src0_sel:WORD_1
	v_fmac_f32_e32 v0, v48, v144
	v_fmac_f32_e32 v1, v48, v145
	v_fmac_f32_e32 v2, v48, v146
	v_fmac_f32_e32 v3, v48, v147
	v_fmac_f32_e32 v4, v48, v148
	v_fmac_f32_e32 v5, v48, v149
	v_fmac_f32_e32 v6, v48, v150
	v_fmac_f32_e32 v7, v48, v151
	v_fmac_f32_e32 v8, v48, v152
	v_fmac_f32_e32 v9, v48, v153
	v_fmac_f32_e32 v10, v48, v154
	v_fmac_f32_e32 v11, v48, v155
	v_fmac_f32_e32 v12, v48, v156
	v_fmac_f32_e32 v13, v48, v157
	v_fmac_f32_e32 v14, v48, v158
	v_fmac_f32_e32 v15, v48, v159
	v_lshl_add_u32 v161, v32, 7, v160
	global_load_dwordx4 v[80:83], v161, s[14:15]
	s_waitcnt vmcnt(15)
; DI void phase_peer_b(const Params& p, int layer, const float* gnext, bool last) {
;     ...
;       for (int j = 0; j < 16; ++j) {
;         const int e = bt * 16 + j;
;         const int eidx = __builtin_amdgcn_readlane(e < 64 ? i0 : i1, e & 63);
;         vr[j] = *(const u32x4*)(EV + (size_t)eidx * DM + lane * 16);
;       }
; #pragma unroll
;       for (int j = 0; j < 16; ++j) {
;         const int e = bt * 16 + j;
;         const float wj = __int_as_float(__builtin_amdgcn_readlane(__float_as_int(e < 64 ? w0 : w1), e & 63));
; #pragma unroll
;         for (int w = 0; w < 4; ++w) {
;           const f32x2 lo = __builtin_amdgcn_cvt_pk_f32_fp8((int)vr[j][w], false);
;           const f32x2 hi = __builtin_amdgcn_cvt_pk_f32_fp8((int)vr[j][w], true);
;           acc[4 * w] += wj * lo[0]; acc[4 * w + 1] += wj * lo[1]; acc[4 * w + 2] += wj * hi[0]; acc[4 * w + 3] += wj * hi[1];
;         }
	v_cvt_pk_f32_fp8_e32 v[144:145], v84
	v_cvt_pk_f32_fp8_sdwa v[146:147], v84 src0_sel:WORD_1
	v_cvt_pk_f32_fp8_e32 v[148:149], v85
	v_cvt_pk_f32_fp8_sdwa v[150:151], v85 src0_sel:WORD_1
	v_cvt_pk_f32_fp8_e32 v[152:153], v86
	v_cvt_pk_f32_fp8_sdwa v[154:155], v86 src0_sel:WORD_1
	v_cvt_pk_f32_fp8_e32 v[156:157], v87
	v_cvt_pk_f32_fp8_sdwa v[158:159], v87 src0_sel:WORD_1
	v_fmac_f32_e32 v0, v49, v144
	v_fmac_f32_e32 v1, v49, v145
	v_fmac_f32_e32 v2, v49, v146
	v_fmac_f32_e32 v3, v49, v147
	v_fmac_f32_e32 v4, v49, v148
	v_fmac_f32_e32 v5, v49, v149
	v_fmac_f32_e32 v6, v49, v150
	v_fmac_f32_e32 v7, v49, v151
	v_fmac_f32_e32 v8, v49, v152
	v_fmac_f32_e32 v9, v49, v153
	v_fmac_f32_e32 v10, v49, v154
	v_fmac_f32_e32 v11, v49, v155
	v_fmac_f32_e32 v12, v49, v156
	v_fmac_f32_e32 v13, v49, v157
	v_fmac_f32_e32 v14, v49, v158
	v_fmac_f32_e32 v15, v49, v159
	v_lshl_add_u32 v161, v33, 7, v160
	global_load_dwordx4 v[84:87], v161, s[14:15]
	s_waitcnt vmcnt(15)
	v_cvt_pk_f32_fp8_e32 v[144:145], v88
	v_cvt_pk_f32_fp8_sdwa v[146:147], v88 src0_sel:WORD_1
	v_cvt_pk_f32_fp8_e32 v[148:149], v89
	v_cvt_pk_f32_fp8_sdwa v[150:151], v89 src0_sel:WORD_1
	v_cvt_pk_f32_fp8_e32 v[152:153], v90
	v_cvt_pk_f32_fp8_sdwa v[154:155], v90 src0_sel:WORD_1
	v_cvt_pk_f32_fp8_e32 v[156:157], v91
	v_cvt_pk_f32_fp8_sdwa v[158:159], v91 src0_sel:WORD_1
	v_fmac_f32_e32 v0, v50, v144
	v_fmac_f32_e32 v1, v50, v145
	v_fmac_f32_e32 v2, v50, v146
	v_fmac_f32_e32 v3, v50, v147
	v_fmac_f32_e32 v4, v50, v148
	v_fmac_f32_e32 v5, v50, v149
	v_fmac_f32_e32 v6, v50, v150
	v_fmac_f32_e32 v7, v50, v151
	v_fmac_f32_e32 v8, v50, v152
	v_fmac_f32_e32 v9, v50, v153
	v_fmac_f32_e32 v10, v50, v154
	v_fmac_f32_e32 v11, v50, v155
	v_fmac_f32_e32 v12, v50, v156
	v_fmac_f32_e32 v13, v50, v157
	v_fmac_f32_e32 v14, v50, v158
	v_fmac_f32_e32 v15, v50, v159
	v_lshl_add_u32 v161, v34, 7, v160
	global_load_dwordx4 v[88:91], v161, s[14:15]
	s_waitcnt vmcnt(15)
	v_cvt_pk_f32_fp8_e32 v[144:145], v92
	v_cvt_pk_f32_fp8_sdwa v[146:147], v92 src0_sel:WORD_1
	v_cvt_pk_f32_fp8_e32 v[148:149], v93
	v_cvt_pk_f32_fp8_sdwa v[150:151], v93 src0_sel:WORD_1
	v_cvt_pk_f32_fp8_e32 v[152:153], v94
	v_cvt_pk_f32_fp8_sdwa v[154:155], v94 src0_sel:WORD_1
	v_cvt_pk_f32_fp8_e32 v[156:157], v95
	v_cvt_pk_f32_fp8_sdwa v[158:159], v95 src0_sel:WORD_1
	v_fmac_f32_e32 v0, v51, v144
	v_fmac_f32_e32 v1, v51, v145
	v_fmac_f32_e32 v2, v51, v146
	v_fmac_f32_e32 v3, v51, v147
	v_fmac_f32_e32 v4, v51, v148
	v_fmac_f32_e32 v5, v51, v149
	v_fmac_f32_e32 v6, v51, v150
	v_fmac_f32_e32 v7, v51, v151
	v_fmac_f32_e32 v8, v51, v152
	v_fmac_f32_e32 v9, v51, v153
	v_fmac_f32_e32 v10, v51, v154
	v_fmac_f32_e32 v11, v51, v155
	v_fmac_f32_e32 v12, v51, v156
	v_fmac_f32_e32 v13, v51, v157
	v_fmac_f32_e32 v14, v51, v158
	v_fmac_f32_e32 v15, v51, v159
	v_lshl_add_u32 v161, v35, 7, v160
	global_load_dwordx4 v[92:95], v161, s[14:15]
	s_waitcnt vmcnt(15)
	v_cvt_pk_f32_fp8_e32 v[144:145], v96
	v_cvt_pk_f32_fp8_sdwa v[146:147], v96 src0_sel:WORD_1
	v_cvt_pk_f32_fp8_e32 v[148:149], v97
	v_cvt_pk_f32_fp8_sdwa v[150:151], v97 src0_sel:WORD_1
	v_cvt_pk_f32_fp8_e32 v[152:153], v98
	v_cvt_pk_f32_fp8_sdwa v[154:155], v98 src0_sel:WORD_1
	v_cvt_pk_f32_fp8_e32 v[156:157], v99
	v_cvt_pk_f32_fp8_sdwa v[158:159], v99 src0_sel:WORD_1
	v_fmac_f32_e32 v0, v52, v144
	v_fmac_f32_e32 v1, v52, v145
	v_fmac_f32_e32 v2, v52, v146
	v_fmac_f32_e32 v3, v52, v147
	v_fmac_f32_e32 v4, v52, v148
	v_fmac_f32_e32 v5, v52, v149
	v_fmac_f32_e32 v6, v52, v150
	v_fmac_f32_e32 v7, v52, v151
	v_fmac_f32_e32 v8, v52, v152
	v_fmac_f32_e32 v9, v52, v153
	v_fmac_f32_e32 v10, v52, v154
	v_fmac_f32_e32 v11, v52, v155
	v_fmac_f32_e32 v12, v52, v156
	v_fmac_f32_e32 v13, v52, v157
	v_fmac_f32_e32 v14, v52, v158
	v_fmac_f32_e32 v15, v52, v159
	v_lshl_add_u32 v161, v36, 7, v160
	global_load_dwordx4 v[96:99], v161, s[14:15]
	s_waitcnt vmcnt(15)
	v_cvt_pk_f32_fp8_e32 v[144:145], v100
	v_cvt_pk_f32_fp8_sdwa v[146:147], v100 src0_sel:WORD_1
	v_cvt_pk_f32_fp8_e32 v[148:149], v101
	v_cvt_pk_f32_fp8_sdwa v[150:151], v101 src0_sel:WORD_1
	v_cvt_pk_f32_fp8_e32 v[152:153], v102
	v_cvt_pk_f32_fp8_sdwa v[154:155], v102 src0_sel:WORD_1
	v_cvt_pk_f32_fp8_e32 v[156:157], v103
	v_cvt_pk_f32_fp8_sdwa v[158:159], v103 src0_sel:WORD_1
	v_fmac_f32_e32 v0, v53, v144
	v_fmac_f32_e32 v1, v53, v145
	v_fmac_f32_e32 v2, v53, v146
	v_fmac_f32_e32 v3, v53, v147
	v_fmac_f32_e32 v4, v53, v148
	v_fmac_f32_e32 v5, v53, v149
	v_fmac_f32_e32 v6, v53, v150
	v_fmac_f32_e32 v7, v53, v151
	v_fmac_f32_e32 v8, v53, v152
	v_fmac_f32_e32 v9, v53, v153
	v_fmac_f32_e32 v10, v53, v154
	v_fmac_f32_e32 v11, v53, v155
	v_fmac_f32_e32 v12, v53, v156
	v_fmac_f32_e32 v13, v53, v157
	v_fmac_f32_e32 v14, v53, v158
	v_fmac_f32_e32 v15, v53, v159
	v_lshl_add_u32 v161, v37, 7, v160
	global_load_dwordx4 v[100:103], v161, s[14:15]
	s_waitcnt vmcnt(15)
	v_cvt_pk_f32_fp8_e32 v[144:145], v104
	v_cvt_pk_f32_fp8_sdwa v[146:147], v104 src0_sel:WORD_1
	v_cvt_pk_f32_fp8_e32 v[148:149], v105
	v_cvt_pk_f32_fp8_sdwa v[150:151], v105 src0_sel:WORD_1
	v_cvt_pk_f32_fp8_e32 v[152:153], v106
	v_cvt_pk_f32_fp8_sdwa v[154:155], v106 src0_sel:WORD_1
	v_cvt_pk_f32_fp8_e32 v[156:157], v107
	v_cvt_pk_f32_fp8_sdwa v[158:159], v107 src0_sel:WORD_1
	v_fmac_f32_e32 v0, v54, v144
	v_fmac_f32_e32 v1, v54, v145
	v_fmac_f32_e32 v2, v54, v146
	v_fmac_f32_e32 v3, v54, v147
	v_fmac_f32_e32 v4, v54, v148
	v_fmac_f32_e32 v5, v54, v149
	v_fmac_f32_e32 v6, v54, v150
	v_fmac_f32_e32 v7, v54, v151
	v_fmac_f32_e32 v8, v54, v152
	v_fmac_f32_e32 v9, v54, v153
	v_fmac_f32_e32 v10, v54, v154
	v_fmac_f32_e32 v11, v54, v155
	v_fmac_f32_e32 v12, v54, v156
	v_fmac_f32_e32 v13, v54, v157
	v_fmac_f32_e32 v14, v54, v158
	v_fmac_f32_e32 v15, v54, v159
	v_lshl_add_u32 v161, v38, 7, v160
	global_load_dwordx4 v[104:107], v161, s[14:15]
	s_waitcnt vmcnt(15)
; DI void phase_peer_b(const Params& p, int layer, const float* gnext, bool last) {
;     ...
;       for (int j = 0; j < 16; ++j) {
;         const int e = bt * 16 + j;
;         const int eidx = __builtin_amdgcn_readlane(e < 64 ? i0 : i1, e & 63);
;         vr[j] = *(const u32x4*)(EV + (size_t)eidx * DM + lane * 16);
;       }
; #pragma unroll
;       for (int j = 0; j < 16; ++j) {
;         const int e = bt * 16 + j;
;         const float wj = __int_as_float(__builtin_amdgcn_readlane(__float_as_int(e < 64 ? w0 : w1), e & 63));
; #pragma unroll
;         for (int w = 0; w < 4; ++w) {
;           const f32x2 lo = __builtin_amdgcn_cvt_pk_f32_fp8((int)vr[j][w], false);
;           const f32x2 hi = __builtin_amdgcn_cvt_pk_f32_fp8((int)vr[j][w], true);
;           acc[4 * w] += wj * lo[0]; acc[4 * w + 1] += wj * lo[1]; acc[4 * w + 2] += wj * hi[0]; acc[4 * w + 3] += wj * hi[1];
;         }
	v_cvt_pk_f32_fp8_e32 v[144:145], v108
	v_cvt_pk_f32_fp8_sdwa v[146:147], v108 src0_sel:WORD_1
	v_cvt_pk_f32_fp8_e32 v[148:149], v109
	v_cvt_pk_f32_fp8_sdwa v[150:151], v109 src0_sel:WORD_1
	v_cvt_pk_f32_fp8_e32 v[152:153], v110
	v_cvt_pk_f32_fp8_sdwa v[154:155], v110 src0_sel:WORD_1
	v_cvt_pk_f32_fp8_e32 v[156:157], v111
	v_cvt_pk_f32_fp8_sdwa v[158:159], v111 src0_sel:WORD_1
	v_fmac_f32_e32 v0, v55, v144
	v_fmac_f32_e32 v1, v55, v145
	v_fmac_f32_e32 v2, v55, v146
	v_fmac_f32_e32 v3, v55, v147
	v_fmac_f32_e32 v4, v55, v148
	v_fmac_f32_e32 v5, v55, v149
	v_fmac_f32_e32 v6, v55, v150
	v_fmac_f32_e32 v7, v55, v151
	v_fmac_f32_e32 v8, v55, v152
	v_fmac_f32_e32 v9, v55, v153
	v_fmac_f32_e32 v10, v55, v154
	v_fmac_f32_e32 v11, v55, v155
	v_fmac_f32_e32 v12, v55, v156
	v_fmac_f32_e32 v13, v55, v157
	v_fmac_f32_e32 v14, v55, v158
	v_fmac_f32_e32 v15, v55, v159
	v_lshl_add_u32 v161, v39, 7, v160
	global_load_dwordx4 v[108:111], v161, s[14:15]
	s_waitcnt vmcnt(15)
	v_cvt_pk_f32_fp8_e32 v[144:145], v112
	v_cvt_pk_f32_fp8_sdwa v[146:147], v112 src0_sel:WORD_1
	v_cvt_pk_f32_fp8_e32 v[148:149], v113
	v_cvt_pk_f32_fp8_sdwa v[150:151], v113 src0_sel:WORD_1
	v_cvt_pk_f32_fp8_e32 v[152:153], v114
	v_cvt_pk_f32_fp8_sdwa v[154:155], v114 src0_sel:WORD_1
	v_cvt_pk_f32_fp8_e32 v[156:157], v115
	v_cvt_pk_f32_fp8_sdwa v[158:159], v115 src0_sel:WORD_1
	v_fmac_f32_e32 v0, v56, v144
	v_fmac_f32_e32 v1, v56, v145
	v_fmac_f32_e32 v2, v56, v146
	v_fmac_f32_e32 v3, v56, v147
	v_fmac_f32_e32 v4, v56, v148
	v_fmac_f32_e32 v5, v56, v149
	v_fmac_f32_e32 v6, v56, v150
	v_fmac_f32_e32 v7, v56, v151
	v_fmac_f32_e32 v8, v56, v152
	v_fmac_f32_e32 v9, v56, v153
	v_fmac_f32_e32 v10, v56, v154
	v_fmac_f32_e32 v11, v56, v155
	v_fmac_f32_e32 v12, v56, v156
	v_fmac_f32_e32 v13, v56, v157
	v_fmac_f32_e32 v14, v56, v158
	v_fmac_f32_e32 v15, v56, v159
	v_lshl_add_u32 v161, v40, 7, v160
	global_load_dwordx4 v[112:115], v161, s[14:15]
	s_waitcnt vmcnt(15)
	v_cvt_pk_f32_fp8_e32 v[144:145], v116
	v_cvt_pk_f32_fp8_sdwa v[146:147], v116 src0_sel:WORD_1
	v_cvt_pk_f32_fp8_e32 v[148:149], v117
	v_cvt_pk_f32_fp8_sdwa v[150:151], v117 src0_sel:WORD_1
	v_cvt_pk_f32_fp8_e32 v[152:153], v118
	v_cvt_pk_f32_fp8_sdwa v[154:155], v118 src0_sel:WORD_1
	v_cvt_pk_f32_fp8_e32 v[156:157], v119
	v_cvt_pk_f32_fp8_sdwa v[158:159], v119 src0_sel:WORD_1
	v_fmac_f32_e32 v0, v57, v144
	v_fmac_f32_e32 v1, v57, v145
	v_fmac_f32_e32 v2, v57, v146
	v_fmac_f32_e32 v3, v57, v147
	v_fmac_f32_e32 v4, v57, v148
	v_fmac_f32_e32 v5, v57, v149
	v_fmac_f32_e32 v6, v57, v150
	v_fmac_f32_e32 v7, v57, v151
	v_fmac_f32_e32 v8, v57, v152
	v_fmac_f32_e32 v9, v57, v153
	v_fmac_f32_e32 v10, v57, v154
	v_fmac_f32_e32 v11, v57, v155
	v_fmac_f32_e32 v12, v57, v156
	v_fmac_f32_e32 v13, v57, v157
	v_fmac_f32_e32 v14, v57, v158
	v_fmac_f32_e32 v15, v57, v159
	v_lshl_add_u32 v161, v41, 7, v160
	global_load_dwordx4 v[116:119], v161, s[14:15]
	s_waitcnt vmcnt(15)
	v_cvt_pk_f32_fp8_e32 v[144:145], v120
	v_cvt_pk_f32_fp8_sdwa v[146:147], v120 src0_sel:WORD_1
	v_cvt_pk_f32_fp8_e32 v[148:149], v121
	v_cvt_pk_f32_fp8_sdwa v[150:151], v121 src0_sel:WORD_1
	v_cvt_pk_f32_fp8_e32 v[152:153], v122
	v_cvt_pk_f32_fp8_sdwa v[154:155], v122 src0_sel:WORD_1
	v_cvt_pk_f32_fp8_e32 v[156:157], v123
	v_cvt_pk_f32_fp8_sdwa v[158:159], v123 src0_sel:WORD_1
	v_fmac_f32_e32 v0, v58, v144
	v_fmac_f32_e32 v1, v58, v145
	v_fmac_f32_e32 v2, v58, v146
	v_fmac_f32_e32 v3, v58, v147
	v_fmac_f32_e32 v4, v58, v148
	v_fmac_f32_e32 v5, v58, v149
	v_fmac_f32_e32 v6, v58, v150
	v_fmac_f32_e32 v7, v58, v151
	v_fmac_f32_e32 v8, v58, v152
	v_fmac_f32_e32 v9, v58, v153
	v_fmac_f32_e32 v10, v58, v154
	v_fmac_f32_e32 v11, v58, v155
	v_fmac_f32_e32 v12, v58, v156
	v_fmac_f32_e32 v13, v58, v157
	v_fmac_f32_e32 v14, v58, v158
	v_fmac_f32_e32 v15, v58, v159
	v_lshl_add_u32 v161, v42, 7, v160
	global_load_dwordx4 v[120:123], v161, s[14:15]
	s_waitcnt vmcnt(15)
	v_cvt_pk_f32_fp8_e32 v[144:145], v124
	v_cvt_pk_f32_fp8_sdwa v[146:147], v124 src0_sel:WORD_1
	v_cvt_pk_f32_fp8_e32 v[148:149], v125
	v_cvt_pk_f32_fp8_sdwa v[150:151], v125 src0_sel:WORD_1
	v_cvt_pk_f32_fp8_e32 v[152:153], v126
	v_cvt_pk_f32_fp8_sdwa v[154:155], v126 src0_sel:WORD_1
	v_cvt_pk_f32_fp8_e32 v[156:157], v127
	v_cvt_pk_f32_fp8_sdwa v[158:159], v127 src0_sel:WORD_1
	v_fmac_f32_e32 v0, v59, v144
	v_fmac_f32_e32 v1, v59, v145
	v_fmac_f32_e32 v2, v59, v146
	v_fmac_f32_e32 v3, v59, v147
	v_fmac_f32_e32 v4, v59, v148
	v_fmac_f32_e32 v5, v59, v149
	v_fmac_f32_e32 v6, v59, v150
	v_fmac_f32_e32 v7, v59, v151
	v_fmac_f32_e32 v8, v59, v152
	v_fmac_f32_e32 v9, v59, v153
	v_fmac_f32_e32 v10, v59, v154
	v_fmac_f32_e32 v11, v59, v155
	v_fmac_f32_e32 v12, v59, v156
	v_fmac_f32_e32 v13, v59, v157
	v_fmac_f32_e32 v14, v59, v158
	v_fmac_f32_e32 v15, v59, v159
	v_lshl_add_u32 v161, v43, 7, v160
	global_load_dwordx4 v[124:127], v161, s[14:15]
	s_waitcnt vmcnt(15)
	v_cvt_pk_f32_fp8_e32 v[144:145], v128
	v_cvt_pk_f32_fp8_sdwa v[146:147], v128 src0_sel:WORD_1
	v_cvt_pk_f32_fp8_e32 v[148:149], v129
	v_cvt_pk_f32_fp8_sdwa v[150:151], v129 src0_sel:WORD_1
	v_cvt_pk_f32_fp8_e32 v[152:153], v130
	v_cvt_pk_f32_fp8_sdwa v[154:155], v130 src0_sel:WORD_1
	v_cvt_pk_f32_fp8_e32 v[156:157], v131
	v_cvt_pk_f32_fp8_sdwa v[158:159], v131 src0_sel:WORD_1
	v_fmac_f32_e32 v0, v60, v144
	v_fmac_f32_e32 v1, v60, v145
	v_fmac_f32_e32 v2, v60, v146
	v_fmac_f32_e32 v3, v60, v147
	v_fmac_f32_e32 v4, v60, v148
	v_fmac_f32_e32 v5, v60, v149
	v_fmac_f32_e32 v6, v60, v150
	v_fmac_f32_e32 v7, v60, v151
	v_fmac_f32_e32 v8, v60, v152
	v_fmac_f32_e32 v9, v60, v153
	v_fmac_f32_e32 v10, v60, v154
	v_fmac_f32_e32 v11, v60, v155
	v_fmac_f32_e32 v12, v60, v156
	v_fmac_f32_e32 v13, v60, v157
	v_fmac_f32_e32 v14, v60, v158
	v_fmac_f32_e32 v15, v60, v159
	v_lshl_add_u32 v161, v44, 7, v160
	global_load_dwordx4 v[128:131], v161, s[14:15]
	s_waitcnt vmcnt(15)
; DI void phase_peer_b(const Params& p, int layer, const float* gnext, bool last) {
;     ...
;       u32x4 vr[16];
; #pragma unroll
;       for (int j = 0; j < 16; ++j) {
;         const int e = bt * 16 + j;
;         const int eidx = __builtin_amdgcn_readlane(e < 64 ? i0 : i1, e & 63);
;         vr[j] = *(const u32x4*)(EV + (size_t)eidx * DM + lane * 16);
;       }
; #pragma unroll
;       for (int j = 0; j < 16; ++j) {
;         const int e = bt * 16 + j;
;         const float wj = __int_as_float(__builtin_amdgcn_readlane(__float_as_int(e < 64 ? w0 : w1), e & 63));
; #pragma unroll
;         for (int w = 0; w < 4; ++w) {
;           const f32x2 lo = __builtin_amdgcn_cvt_pk_f32_fp8((int)vr[j][w], false);
;           const f32x2 hi = __builtin_amdgcn_cvt_pk_f32_fp8((int)vr[j][w], true);
;           acc[4 * w] += wj * lo[0]; acc[4 * w + 1] += wj * lo[1]; acc[4 * w + 2] += wj * hi[0]; acc[4 * w + 3] += wj * hi[1];
;         }
	v_cvt_pk_f32_fp8_e32 v[144:145], v132
	v_cvt_pk_f32_fp8_sdwa v[146:147], v132 src0_sel:WORD_1
	v_cvt_pk_f32_fp8_e32 v[148:149], v133
	v_cvt_pk_f32_fp8_sdwa v[150:151], v133 src0_sel:WORD_1
	v_cvt_pk_f32_fp8_e32 v[152:153], v134
	v_cvt_pk_f32_fp8_sdwa v[154:155], v134 src0_sel:WORD_1
	v_cvt_pk_f32_fp8_e32 v[156:157], v135
	v_cvt_pk_f32_fp8_sdwa v[158:159], v135 src0_sel:WORD_1
	v_fmac_f32_e32 v0, v61, v144
	v_fmac_f32_e32 v1, v61, v145
	v_fmac_f32_e32 v2, v61, v146
	v_fmac_f32_e32 v3, v61, v147
	v_fmac_f32_e32 v4, v61, v148
	v_fmac_f32_e32 v5, v61, v149
	v_fmac_f32_e32 v6, v61, v150
	v_fmac_f32_e32 v7, v61, v151
	v_fmac_f32_e32 v8, v61, v152
	v_fmac_f32_e32 v9, v61, v153
	v_fmac_f32_e32 v10, v61, v154
	v_fmac_f32_e32 v11, v61, v155
	v_fmac_f32_e32 v12, v61, v156
	v_fmac_f32_e32 v13, v61, v157
	v_fmac_f32_e32 v14, v61, v158
	v_fmac_f32_e32 v15, v61, v159
	v_lshl_add_u32 v161, v45, 7, v160
	global_load_dwordx4 v[132:135], v161, s[14:15]
	s_waitcnt vmcnt(15)
	v_cvt_pk_f32_fp8_e32 v[144:145], v136
	v_cvt_pk_f32_fp8_sdwa v[146:147], v136 src0_sel:WORD_1
	v_cvt_pk_f32_fp8_e32 v[148:149], v137
	v_cvt_pk_f32_fp8_sdwa v[150:151], v137 src0_sel:WORD_1
	v_cvt_pk_f32_fp8_e32 v[152:153], v138
	v_cvt_pk_f32_fp8_sdwa v[154:155], v138 src0_sel:WORD_1
	v_cvt_pk_f32_fp8_e32 v[156:157], v139
	v_cvt_pk_f32_fp8_sdwa v[158:159], v139 src0_sel:WORD_1
	v_fmac_f32_e32 v0, v62, v144
	v_fmac_f32_e32 v1, v62, v145
	v_fmac_f32_e32 v2, v62, v146
	v_fmac_f32_e32 v3, v62, v147
	v_fmac_f32_e32 v4, v62, v148
	v_fmac_f32_e32 v5, v62, v149
	v_fmac_f32_e32 v6, v62, v150
	v_fmac_f32_e32 v7, v62, v151
	v_fmac_f32_e32 v8, v62, v152
	v_fmac_f32_e32 v9, v62, v153
	v_fmac_f32_e32 v10, v62, v154
	v_fmac_f32_e32 v11, v62, v155
	v_fmac_f32_e32 v12, v62, v156
	v_fmac_f32_e32 v13, v62, v157
	v_fmac_f32_e32 v14, v62, v158
	v_fmac_f32_e32 v15, v62, v159
	v_lshl_add_u32 v161, v46, 7, v160
	global_load_dwordx4 v[136:139], v161, s[14:15]
	s_waitcnt vmcnt(15)
	v_cvt_pk_f32_fp8_e32 v[144:145], v140
	v_cvt_pk_f32_fp8_sdwa v[146:147], v140 src0_sel:WORD_1
	v_cvt_pk_f32_fp8_e32 v[148:149], v141
	v_cvt_pk_f32_fp8_sdwa v[150:151], v141 src0_sel:WORD_1
	v_cvt_pk_f32_fp8_e32 v[152:153], v142
	v_cvt_pk_f32_fp8_sdwa v[154:155], v142 src0_sel:WORD_1
	v_cvt_pk_f32_fp8_e32 v[156:157], v143
	v_cvt_pk_f32_fp8_sdwa v[158:159], v143 src0_sel:WORD_1
	v_fmac_f32_e32 v0, v63, v144
	v_fmac_f32_e32 v1, v63, v145
	v_fmac_f32_e32 v2, v63, v146
	v_fmac_f32_e32 v3, v63, v147
	v_fmac_f32_e32 v4, v63, v148
	v_fmac_f32_e32 v5, v63, v149
	v_fmac_f32_e32 v6, v63, v150
	v_fmac_f32_e32 v7, v63, v151
	v_fmac_f32_e32 v8, v63, v152
	v_fmac_f32_e32 v9, v63, v153
	v_fmac_f32_e32 v10, v63, v154
	v_fmac_f32_e32 v11, v63, v155
	v_fmac_f32_e32 v12, v63, v156
	v_fmac_f32_e32 v13, v63, v157
	v_fmac_f32_e32 v14, v63, v158
	v_fmac_f32_e32 v15, v63, v159
	v_lshl_add_u32 v161, v47, 7, v160
	global_load_dwordx4 v[140:143], v161, s[14:15]
	s_waitcnt lgkmcnt(0)
	ds_read_b128 v[32:35], v163 offset:448
	ds_read_b128 v[36:39], v163 offset:464
	ds_read_b128 v[40:43], v163 offset:480
	ds_read_b128 v[44:47], v163 offset:496
	ds_read_b128 v[48:51], v163 offset:4608
	ds_read_b128 v[52:55], v163 offset:4624
	ds_read_b128 v[56:59], v163 offset:4640
	ds_read_b128 v[60:63], v163 offset:4656
	s_waitcnt vmcnt(15)
	v_cvt_pk_f32_fp8_e32 v[144:145], v80
	v_cvt_pk_f32_fp8_sdwa v[146:147], v80 src0_sel:WORD_1
	v_cvt_pk_f32_fp8_e32 v[148:149], v81
	v_cvt_pk_f32_fp8_sdwa v[150:151], v81 src0_sel:WORD_1
	v_cvt_pk_f32_fp8_e32 v[152:153], v82
	v_cvt_pk_f32_fp8_sdwa v[154:155], v82 src0_sel:WORD_1
	v_cvt_pk_f32_fp8_e32 v[156:157], v83
	v_cvt_pk_f32_fp8_sdwa v[158:159], v83 src0_sel:WORD_1
	v_fmac_f32_e32 v0, v64, v144
	v_fmac_f32_e32 v1, v64, v145
	v_fmac_f32_e32 v2, v64, v146
	v_fmac_f32_e32 v3, v64, v147
	v_fmac_f32_e32 v4, v64, v148
	v_fmac_f32_e32 v5, v64, v149
	v_fmac_f32_e32 v6, v64, v150
	v_fmac_f32_e32 v7, v64, v151
	v_fmac_f32_e32 v8, v64, v152
	v_fmac_f32_e32 v9, v64, v153
	v_fmac_f32_e32 v10, v64, v154
	v_fmac_f32_e32 v11, v64, v155
	v_fmac_f32_e32 v12, v64, v156
	v_fmac_f32_e32 v13, v64, v157
	v_fmac_f32_e32 v14, v64, v158
	v_fmac_f32_e32 v15, v64, v159
	v_lshl_add_u32 v161, v16, 7, v160
	global_load_dwordx4 v[80:83], v161, s[14:15]
	s_waitcnt vmcnt(15)
	v_cvt_pk_f32_fp8_e32 v[144:145], v84
	v_cvt_pk_f32_fp8_sdwa v[146:147], v84 src0_sel:WORD_1
	v_cvt_pk_f32_fp8_e32 v[148:149], v85
	v_cvt_pk_f32_fp8_sdwa v[150:151], v85 src0_sel:WORD_1
	v_cvt_pk_f32_fp8_e32 v[152:153], v86
	v_cvt_pk_f32_fp8_sdwa v[154:155], v86 src0_sel:WORD_1
	v_cvt_pk_f32_fp8_e32 v[156:157], v87
	v_cvt_pk_f32_fp8_sdwa v[158:159], v87 src0_sel:WORD_1
	v_fmac_f32_e32 v0, v65, v144
	v_fmac_f32_e32 v1, v65, v145
	v_fmac_f32_e32 v2, v65, v146
	v_fmac_f32_e32 v3, v65, v147
	v_fmac_f32_e32 v4, v65, v148
	v_fmac_f32_e32 v5, v65, v149
	v_fmac_f32_e32 v6, v65, v150
	v_fmac_f32_e32 v7, v65, v151
	v_fmac_f32_e32 v8, v65, v152
	v_fmac_f32_e32 v9, v65, v153
	v_fmac_f32_e32 v10, v65, v154
	v_fmac_f32_e32 v11, v65, v155
	v_fmac_f32_e32 v12, v65, v156
	v_fmac_f32_e32 v13, v65, v157
	v_fmac_f32_e32 v14, v65, v158
	v_fmac_f32_e32 v15, v65, v159
	v_lshl_add_u32 v161, v17, 7, v160
	global_load_dwordx4 v[84:87], v161, s[14:15]
	s_waitcnt vmcnt(15)
; DI void phase_peer_b(const Params& p, int layer, const float* gnext, bool last) {
;     ...
; #pragma unroll
;       for (int j = 0; j < 16; ++j) {
;         const int e = bt * 16 + j;
;         const float wj = __int_as_float(__builtin_amdgcn_readlane(__float_as_int(e < 64 ? w0 : w1), e & 63));
; #pragma unroll
;         for (int w = 0; w < 4; ++w) {
;           const f32x2 lo = __builtin_amdgcn_cvt_pk_f32_fp8((int)vr[j][w], false);
;           const f32x2 hi = __builtin_amdgcn_cvt_pk_f32_fp8((int)vr[j][w], true);
;           acc[4 * w] += wj * lo[0]; acc[4 * w + 1] += wj * lo[1]; acc[4 * w + 2] += wj * hi[0]; acc[4 * w + 3] += wj * hi[1];
;         }
;       }
	v_cvt_pk_f32_fp8_e32 v[144:145], v88
	v_cvt_pk_f32_fp8_sdwa v[146:147], v88 src0_sel:WORD_1
	v_cvt_pk_f32_fp8_e32 v[148:149], v89
	v_cvt_pk_f32_fp8_sdwa v[150:151], v89 src0_sel:WORD_1
	v_cvt_pk_f32_fp8_e32 v[152:153], v90
	v_cvt_pk_f32_fp8_sdwa v[154:155], v90 src0_sel:WORD_1
	v_cvt_pk_f32_fp8_e32 v[156:157], v91
	v_cvt_pk_f32_fp8_sdwa v[158:159], v91 src0_sel:WORD_1
	v_fmac_f32_e32 v0, v66, v144
	v_fmac_f32_e32 v1, v66, v145
	v_fmac_f32_e32 v2, v66, v146
	v_fmac_f32_e32 v3, v66, v147
	v_fmac_f32_e32 v4, v66, v148
	v_fmac_f32_e32 v5, v66, v149
	v_fmac_f32_e32 v6, v66, v150
	v_fmac_f32_e32 v7, v66, v151
	v_fmac_f32_e32 v8, v66, v152
	v_fmac_f32_e32 v9, v66, v153
	v_fmac_f32_e32 v10, v66, v154
	v_fmac_f32_e32 v11, v66, v155
	v_fmac_f32_e32 v12, v66, v156
	v_fmac_f32_e32 v13, v66, v157
	v_fmac_f32_e32 v14, v66, v158
	v_fmac_f32_e32 v15, v66, v159
	v_lshl_add_u32 v161, v18, 7, v160
	global_load_dwordx4 v[88:91], v161, s[14:15]
	s_waitcnt vmcnt(15)
	v_cvt_pk_f32_fp8_e32 v[144:145], v92
	v_cvt_pk_f32_fp8_sdwa v[146:147], v92 src0_sel:WORD_1
	v_cvt_pk_f32_fp8_e32 v[148:149], v93
	v_cvt_pk_f32_fp8_sdwa v[150:151], v93 src0_sel:WORD_1
	v_cvt_pk_f32_fp8_e32 v[152:153], v94
	v_cvt_pk_f32_fp8_sdwa v[154:155], v94 src0_sel:WORD_1
	v_cvt_pk_f32_fp8_e32 v[156:157], v95
	v_cvt_pk_f32_fp8_sdwa v[158:159], v95 src0_sel:WORD_1
	v_fmac_f32_e32 v0, v67, v144
	v_fmac_f32_e32 v1, v67, v145
	v_fmac_f32_e32 v2, v67, v146
	v_fmac_f32_e32 v3, v67, v147
	v_fmac_f32_e32 v4, v67, v148
	v_fmac_f32_e32 v5, v67, v149
	v_fmac_f32_e32 v6, v67, v150
	v_fmac_f32_e32 v7, v67, v151
	v_fmac_f32_e32 v8, v67, v152
	v_fmac_f32_e32 v9, v67, v153
	v_fmac_f32_e32 v10, v67, v154
	v_fmac_f32_e32 v11, v67, v155
	v_fmac_f32_e32 v12, v67, v156
	v_fmac_f32_e32 v13, v67, v157
	v_fmac_f32_e32 v14, v67, v158
	v_fmac_f32_e32 v15, v67, v159
	v_lshl_add_u32 v161, v19, 7, v160
	global_load_dwordx4 v[92:95], v161, s[14:15]
	s_waitcnt vmcnt(15)
	v_cvt_pk_f32_fp8_e32 v[144:145], v96
	v_cvt_pk_f32_fp8_sdwa v[146:147], v96 src0_sel:WORD_1
	v_cvt_pk_f32_fp8_e32 v[148:149], v97
	v_cvt_pk_f32_fp8_sdwa v[150:151], v97 src0_sel:WORD_1
	v_cvt_pk_f32_fp8_e32 v[152:153], v98
	v_cvt_pk_f32_fp8_sdwa v[154:155], v98 src0_sel:WORD_1
	v_cvt_pk_f32_fp8_e32 v[156:157], v99
	v_cvt_pk_f32_fp8_sdwa v[158:159], v99 src0_sel:WORD_1
	v_fmac_f32_e32 v0, v68, v144
	v_fmac_f32_e32 v1, v68, v145
	v_fmac_f32_e32 v2, v68, v146
	v_fmac_f32_e32 v3, v68, v147
	v_fmac_f32_e32 v4, v68, v148
	v_fmac_f32_e32 v5, v68, v149
	v_fmac_f32_e32 v6, v68, v150
	v_fmac_f32_e32 v7, v68, v151
	v_fmac_f32_e32 v8, v68, v152
	v_fmac_f32_e32 v9, v68, v153
	v_fmac_f32_e32 v10, v68, v154
	v_fmac_f32_e32 v11, v68, v155
	v_fmac_f32_e32 v12, v68, v156
	v_fmac_f32_e32 v13, v68, v157
	v_fmac_f32_e32 v14, v68, v158
	v_fmac_f32_e32 v15, v68, v159
	v_lshl_add_u32 v161, v20, 7, v160
	global_load_dwordx4 v[96:99], v161, s[14:15]
	s_waitcnt vmcnt(15)
	v_cvt_pk_f32_fp8_e32 v[144:145], v100
	v_cvt_pk_f32_fp8_sdwa v[146:147], v100 src0_sel:WORD_1
	v_cvt_pk_f32_fp8_e32 v[148:149], v101
	v_cvt_pk_f32_fp8_sdwa v[150:151], v101 src0_sel:WORD_1
	v_cvt_pk_f32_fp8_e32 v[152:153], v102
	v_cvt_pk_f32_fp8_sdwa v[154:155], v102 src0_sel:WORD_1
	v_cvt_pk_f32_fp8_e32 v[156:157], v103
	v_cvt_pk_f32_fp8_sdwa v[158:159], v103 src0_sel:WORD_1
	v_fmac_f32_e32 v0, v69, v144
	v_fmac_f32_e32 v1, v69, v145
	v_fmac_f32_e32 v2, v69, v146
	v_fmac_f32_e32 v3, v69, v147
	v_fmac_f32_e32 v4, v69, v148
	v_fmac_f32_e32 v5, v69, v149
	v_fmac_f32_e32 v6, v69, v150
	v_fmac_f32_e32 v7, v69, v151
	v_fmac_f32_e32 v8, v69, v152
	v_fmac_f32_e32 v9, v69, v153
	v_fmac_f32_e32 v10, v69, v154
	v_fmac_f32_e32 v11, v69, v155
	v_fmac_f32_e32 v12, v69, v156
	v_fmac_f32_e32 v13, v69, v157
	v_fmac_f32_e32 v14, v69, v158
	v_fmac_f32_e32 v15, v69, v159
	v_lshl_add_u32 v161, v21, 7, v160
	global_load_dwordx4 v[100:103], v161, s[14:15]
	s_waitcnt vmcnt(15)
	v_cvt_pk_f32_fp8_e32 v[144:145], v104
	v_cvt_pk_f32_fp8_sdwa v[146:147], v104 src0_sel:WORD_1
	v_cvt_pk_f32_fp8_e32 v[148:149], v105
	v_cvt_pk_f32_fp8_sdwa v[150:151], v105 src0_sel:WORD_1
	v_cvt_pk_f32_fp8_e32 v[152:153], v106
	v_cvt_pk_f32_fp8_sdwa v[154:155], v106 src0_sel:WORD_1
	v_cvt_pk_f32_fp8_e32 v[156:157], v107
	v_cvt_pk_f32_fp8_sdwa v[158:159], v107 src0_sel:WORD_1
	v_fmac_f32_e32 v0, v70, v144
	v_fmac_f32_e32 v1, v70, v145
	v_fmac_f32_e32 v2, v70, v146
	v_fmac_f32_e32 v3, v70, v147
	v_fmac_f32_e32 v4, v70, v148
	v_fmac_f32_e32 v5, v70, v149
	v_fmac_f32_e32 v6, v70, v150
	v_fmac_f32_e32 v7, v70, v151
	v_fmac_f32_e32 v8, v70, v152
	v_fmac_f32_e32 v9, v70, v153
	v_fmac_f32_e32 v10, v70, v154
	v_fmac_f32_e32 v11, v70, v155
	v_fmac_f32_e32 v12, v70, v156
	v_fmac_f32_e32 v13, v70, v157
	v_fmac_f32_e32 v14, v70, v158
	v_fmac_f32_e32 v15, v70, v159
	v_lshl_add_u32 v161, v22, 7, v160
	global_load_dwordx4 v[104:107], v161, s[14:15]
	s_waitcnt vmcnt(15)
	v_cvt_pk_f32_fp8_e32 v[144:145], v108
	v_cvt_pk_f32_fp8_sdwa v[146:147], v108 src0_sel:WORD_1
	v_cvt_pk_f32_fp8_e32 v[148:149], v109
	v_cvt_pk_f32_fp8_sdwa v[150:151], v109 src0_sel:WORD_1
	v_cvt_pk_f32_fp8_e32 v[152:153], v110
	v_cvt_pk_f32_fp8_sdwa v[154:155], v110 src0_sel:WORD_1
	v_cvt_pk_f32_fp8_e32 v[156:157], v111
	v_cvt_pk_f32_fp8_sdwa v[158:159], v111 src0_sel:WORD_1
	v_fmac_f32_e32 v0, v71, v144
	v_fmac_f32_e32 v1, v71, v145
	v_fmac_f32_e32 v2, v71, v146
	v_fmac_f32_e32 v3, v71, v147
	v_fmac_f32_e32 v4, v71, v148
	v_fmac_f32_e32 v5, v71, v149
	v_fmac_f32_e32 v6, v71, v150
	v_fmac_f32_e32 v7, v71, v151
	v_fmac_f32_e32 v8, v71, v152
	v_fmac_f32_e32 v9, v71, v153
	v_fmac_f32_e32 v10, v71, v154
	v_fmac_f32_e32 v11, v71, v155
	v_fmac_f32_e32 v12, v71, v156
	v_fmac_f32_e32 v13, v71, v157
	v_fmac_f32_e32 v14, v71, v158
	v_fmac_f32_e32 v15, v71, v159
	v_lshl_add_u32 v161, v23, 7, v160
	global_load_dwordx4 v[108:111], v161, s[14:15]
	s_waitcnt vmcnt(15)
; DI void phase_peer_b(const Params& p, int layer, const float* gnext, bool last) {
;     ...
; #pragma unroll
;       for (int j = 0; j < 16; ++j) {
;         const int e = bt * 16 + j;
;         const float wj = __int_as_float(__builtin_amdgcn_readlane(__float_as_int(e < 64 ? w0 : w1), e & 63));
; #pragma unroll
;         for (int w = 0; w < 4; ++w) {
;           const f32x2 lo = __builtin_amdgcn_cvt_pk_f32_fp8((int)vr[j][w], false);
;           const f32x2 hi = __builtin_amdgcn_cvt_pk_f32_fp8((int)vr[j][w], true);
;           acc[4 * w] += wj * lo[0]; acc[4 * w + 1] += wj * lo[1]; acc[4 * w + 2] += wj * hi[0]; acc[4 * w + 3] += wj * hi[1];
;         }
;       }
	v_cvt_pk_f32_fp8_e32 v[144:145], v112
	v_cvt_pk_f32_fp8_sdwa v[146:147], v112 src0_sel:WORD_1
	v_cvt_pk_f32_fp8_e32 v[148:149], v113
	v_cvt_pk_f32_fp8_sdwa v[150:151], v113 src0_sel:WORD_1
	v_cvt_pk_f32_fp8_e32 v[152:153], v114
	v_cvt_pk_f32_fp8_sdwa v[154:155], v114 src0_sel:WORD_1
	v_cvt_pk_f32_fp8_e32 v[156:157], v115
	v_cvt_pk_f32_fp8_sdwa v[158:159], v115 src0_sel:WORD_1
	v_fmac_f32_e32 v0, v72, v144
	v_fmac_f32_e32 v1, v72, v145
	v_fmac_f32_e32 v2, v72, v146
	v_fmac_f32_e32 v3, v72, v147
	v_fmac_f32_e32 v4, v72, v148
	v_fmac_f32_e32 v5, v72, v149
	v_fmac_f32_e32 v6, v72, v150
	v_fmac_f32_e32 v7, v72, v151
	v_fmac_f32_e32 v8, v72, v152
	v_fmac_f32_e32 v9, v72, v153
	v_fmac_f32_e32 v10, v72, v154
	v_fmac_f32_e32 v11, v72, v155
	v_fmac_f32_e32 v12, v72, v156
	v_fmac_f32_e32 v13, v72, v157
	v_fmac_f32_e32 v14, v72, v158
	v_fmac_f32_e32 v15, v72, v159
	v_lshl_add_u32 v161, v24, 7, v160
	global_load_dwordx4 v[112:115], v161, s[14:15]
	s_waitcnt vmcnt(15)
	v_cvt_pk_f32_fp8_e32 v[144:145], v116
	v_cvt_pk_f32_fp8_sdwa v[146:147], v116 src0_sel:WORD_1
	v_cvt_pk_f32_fp8_e32 v[148:149], v117
	v_cvt_pk_f32_fp8_sdwa v[150:151], v117 src0_sel:WORD_1
	v_cvt_pk_f32_fp8_e32 v[152:153], v118
	v_cvt_pk_f32_fp8_sdwa v[154:155], v118 src0_sel:WORD_1
	v_cvt_pk_f32_fp8_e32 v[156:157], v119
	v_cvt_pk_f32_fp8_sdwa v[158:159], v119 src0_sel:WORD_1
	v_fmac_f32_e32 v0, v73, v144
	v_fmac_f32_e32 v1, v73, v145
	v_fmac_f32_e32 v2, v73, v146
	v_fmac_f32_e32 v3, v73, v147
	v_fmac_f32_e32 v4, v73, v148
	v_fmac_f32_e32 v5, v73, v149
	v_fmac_f32_e32 v6, v73, v150
	v_fmac_f32_e32 v7, v73, v151
	v_fmac_f32_e32 v8, v73, v152
	v_fmac_f32_e32 v9, v73, v153
	v_fmac_f32_e32 v10, v73, v154
	v_fmac_f32_e32 v11, v73, v155
	v_fmac_f32_e32 v12, v73, v156
	v_fmac_f32_e32 v13, v73, v157
	v_fmac_f32_e32 v14, v73, v158
	v_fmac_f32_e32 v15, v73, v159
	v_lshl_add_u32 v161, v25, 7, v160
	global_load_dwordx4 v[116:119], v161, s[14:15]
	s_waitcnt vmcnt(15)
	v_cvt_pk_f32_fp8_e32 v[144:145], v120
	v_cvt_pk_f32_fp8_sdwa v[146:147], v120 src0_sel:WORD_1
	v_cvt_pk_f32_fp8_e32 v[148:149], v121
	v_cvt_pk_f32_fp8_sdwa v[150:151], v121 src0_sel:WORD_1
	v_cvt_pk_f32_fp8_e32 v[152:153], v122
	v_cvt_pk_f32_fp8_sdwa v[154:155], v122 src0_sel:WORD_1
	v_cvt_pk_f32_fp8_e32 v[156:157], v123
	v_cvt_pk_f32_fp8_sdwa v[158:159], v123 src0_sel:WORD_1
	v_fmac_f32_e32 v0, v74, v144
	v_fmac_f32_e32 v1, v74, v145
	v_fmac_f32_e32 v2, v74, v146
	v_fmac_f32_e32 v3, v74, v147
	v_fmac_f32_e32 v4, v74, v148
	v_fmac_f32_e32 v5, v74, v149
	v_fmac_f32_e32 v6, v74, v150
	v_fmac_f32_e32 v7, v74, v151
	v_fmac_f32_e32 v8, v74, v152
	v_fmac_f32_e32 v9, v74, v153
	v_fmac_f32_e32 v10, v74, v154
	v_fmac_f32_e32 v11, v74, v155
	v_fmac_f32_e32 v12, v74, v156
	v_fmac_f32_e32 v13, v74, v157
	v_fmac_f32_e32 v14, v74, v158
	v_fmac_f32_e32 v15, v74, v159
	v_lshl_add_u32 v161, v26, 7, v160
	global_load_dwordx4 v[120:123], v161, s[14:15]
	s_waitcnt vmcnt(15)
	v_cvt_pk_f32_fp8_e32 v[144:145], v124
	v_cvt_pk_f32_fp8_sdwa v[146:147], v124 src0_sel:WORD_1
	v_cvt_pk_f32_fp8_e32 v[148:149], v125
	v_cvt_pk_f32_fp8_sdwa v[150:151], v125 src0_sel:WORD_1
	v_cvt_pk_f32_fp8_e32 v[152:153], v126
	v_cvt_pk_f32_fp8_sdwa v[154:155], v126 src0_sel:WORD_1
	v_cvt_pk_f32_fp8_e32 v[156:157], v127
	v_cvt_pk_f32_fp8_sdwa v[158:159], v127 src0_sel:WORD_1
	v_fmac_f32_e32 v0, v75, v144
	v_fmac_f32_e32 v1, v75, v145
	v_fmac_f32_e32 v2, v75, v146
	v_fmac_f32_e32 v3, v75, v147
	v_fmac_f32_e32 v4, v75, v148
	v_fmac_f32_e32 v5, v75, v149
	v_fmac_f32_e32 v6, v75, v150
	v_fmac_f32_e32 v7, v75, v151
	v_fmac_f32_e32 v8, v75, v152
	v_fmac_f32_e32 v9, v75, v153
	v_fmac_f32_e32 v10, v75, v154
	v_fmac_f32_e32 v11, v75, v155
	v_fmac_f32_e32 v12, v75, v156
	v_fmac_f32_e32 v13, v75, v157
	v_fmac_f32_e32 v14, v75, v158
	v_fmac_f32_e32 v15, v75, v159
	v_lshl_add_u32 v161, v27, 7, v160
	global_load_dwordx4 v[124:127], v161, s[14:15]
	s_waitcnt vmcnt(15)
	v_cvt_pk_f32_fp8_e32 v[144:145], v128
	v_cvt_pk_f32_fp8_sdwa v[146:147], v128 src0_sel:WORD_1
	v_cvt_pk_f32_fp8_e32 v[148:149], v129
	v_cvt_pk_f32_fp8_sdwa v[150:151], v129 src0_sel:WORD_1
	v_cvt_pk_f32_fp8_e32 v[152:153], v130
	v_cvt_pk_f32_fp8_sdwa v[154:155], v130 src0_sel:WORD_1
	v_cvt_pk_f32_fp8_e32 v[156:157], v131
	v_cvt_pk_f32_fp8_sdwa v[158:159], v131 src0_sel:WORD_1
	v_fmac_f32_e32 v0, v76, v144
	v_fmac_f32_e32 v1, v76, v145
	v_fmac_f32_e32 v2, v76, v146
	v_fmac_f32_e32 v3, v76, v147
	v_fmac_f32_e32 v4, v76, v148
	v_fmac_f32_e32 v5, v76, v149
	v_fmac_f32_e32 v6, v76, v150
	v_fmac_f32_e32 v7, v76, v151
	v_fmac_f32_e32 v8, v76, v152
	v_fmac_f32_e32 v9, v76, v153
	v_fmac_f32_e32 v10, v76, v154
	v_fmac_f32_e32 v11, v76, v155
	v_fmac_f32_e32 v12, v76, v156
	v_fmac_f32_e32 v13, v76, v157
	v_fmac_f32_e32 v14, v76, v158
	v_fmac_f32_e32 v15, v76, v159
	v_lshl_add_u32 v161, v28, 7, v160
	global_load_dwordx4 v[128:131], v161, s[14:15]
	s_waitcnt vmcnt(15)
	v_cvt_pk_f32_fp8_e32 v[144:145], v132
	v_cvt_pk_f32_fp8_sdwa v[146:147], v132 src0_sel:WORD_1
	v_cvt_pk_f32_fp8_e32 v[148:149], v133
	v_cvt_pk_f32_fp8_sdwa v[150:151], v133 src0_sel:WORD_1
	v_cvt_pk_f32_fp8_e32 v[152:153], v134
	v_cvt_pk_f32_fp8_sdwa v[154:155], v134 src0_sel:WORD_1
	v_cvt_pk_f32_fp8_e32 v[156:157], v135
	v_cvt_pk_f32_fp8_sdwa v[158:159], v135 src0_sel:WORD_1
	v_fmac_f32_e32 v0, v77, v144
	v_fmac_f32_e32 v1, v77, v145
	v_fmac_f32_e32 v2, v77, v146
	v_fmac_f32_e32 v3, v77, v147
	v_fmac_f32_e32 v4, v77, v148
	v_fmac_f32_e32 v5, v77, v149
	v_fmac_f32_e32 v6, v77, v150
	v_fmac_f32_e32 v7, v77, v151
	v_fmac_f32_e32 v8, v77, v152
	v_fmac_f32_e32 v9, v77, v153
	v_fmac_f32_e32 v10, v77, v154
	v_fmac_f32_e32 v11, v77, v155
	v_fmac_f32_e32 v12, v77, v156
	v_fmac_f32_e32 v13, v77, v157
	v_fmac_f32_e32 v14, v77, v158
	v_fmac_f32_e32 v15, v77, v159
	v_lshl_add_u32 v161, v29, 7, v160
	global_load_dwordx4 v[132:135], v161, s[14:15]
	s_waitcnt vmcnt(15)
; DI void phase_peer_b(const Params& p, int layer, const float* gnext, bool last) {
;     ...
;     for (int bt = 0; bt < 8; ++bt) {
;       u32x4 vr[16];
; #pragma unroll
;       for (int j = 0; j < 16; ++j) {
;         const int e = bt * 16 + j;
;         const int eidx = __builtin_amdgcn_readlane(e < 64 ? i0 : i1, e & 63);
;         vr[j] = *(const u32x4*)(EV + (size_t)eidx * DM + lane * 16);
;       }
; #pragma unroll
;       for (int j = 0; j < 16; ++j) {
;         const int e = bt * 16 + j;
;         const float wj = __int_as_float(__builtin_amdgcn_readlane(__float_as_int(e < 64 ? w0 : w1), e & 63));
; #pragma unroll
;         for (int w = 0; w < 4; ++w) {
;           const f32x2 lo = __builtin_amdgcn_cvt_pk_f32_fp8((int)vr[j][w], false);
;           const f32x2 hi = __builtin_amdgcn_cvt_pk_f32_fp8((int)vr[j][w], true);
;           acc[4 * w] += wj * lo[0]; acc[4 * w + 1] += wj * lo[1]; acc[4 * w + 2] += wj * hi[0]; acc[4 * w + 3] += wj * hi[1];
;         }
;       }
	v_cvt_pk_f32_fp8_e32 v[144:145], v136
	v_cvt_pk_f32_fp8_sdwa v[146:147], v136 src0_sel:WORD_1
	v_cvt_pk_f32_fp8_e32 v[148:149], v137
	v_cvt_pk_f32_fp8_sdwa v[150:151], v137 src0_sel:WORD_1
	v_cvt_pk_f32_fp8_e32 v[152:153], v138
	v_cvt_pk_f32_fp8_sdwa v[154:155], v138 src0_sel:WORD_1
	v_cvt_pk_f32_fp8_e32 v[156:157], v139
	v_cvt_pk_f32_fp8_sdwa v[158:159], v139 src0_sel:WORD_1
	v_fmac_f32_e32 v0, v78, v144
	v_fmac_f32_e32 v1, v78, v145
	v_fmac_f32_e32 v2, v78, v146
	v_fmac_f32_e32 v3, v78, v147
	v_fmac_f32_e32 v4, v78, v148
	v_fmac_f32_e32 v5, v78, v149
	v_fmac_f32_e32 v6, v78, v150
	v_fmac_f32_e32 v7, v78, v151
	v_fmac_f32_e32 v8, v78, v152
	v_fmac_f32_e32 v9, v78, v153
	v_fmac_f32_e32 v10, v78, v154
	v_fmac_f32_e32 v11, v78, v155
	v_fmac_f32_e32 v12, v78, v156
	v_fmac_f32_e32 v13, v78, v157
	v_fmac_f32_e32 v14, v78, v158
	v_fmac_f32_e32 v15, v78, v159
	v_lshl_add_u32 v161, v30, 7, v160
	global_load_dwordx4 v[136:139], v161, s[14:15]
	s_waitcnt vmcnt(15)
	v_cvt_pk_f32_fp8_e32 v[144:145], v140
	v_cvt_pk_f32_fp8_sdwa v[146:147], v140 src0_sel:WORD_1
	v_cvt_pk_f32_fp8_e32 v[148:149], v141
	v_cvt_pk_f32_fp8_sdwa v[150:151], v141 src0_sel:WORD_1
	v_cvt_pk_f32_fp8_e32 v[152:153], v142
	v_cvt_pk_f32_fp8_sdwa v[154:155], v142 src0_sel:WORD_1
	v_cvt_pk_f32_fp8_e32 v[156:157], v143
	v_cvt_pk_f32_fp8_sdwa v[158:159], v143 src0_sel:WORD_1
	v_fmac_f32_e32 v0, v79, v144
	v_fmac_f32_e32 v1, v79, v145
	v_fmac_f32_e32 v2, v79, v146
	v_fmac_f32_e32 v3, v79, v147
	v_fmac_f32_e32 v4, v79, v148
	v_fmac_f32_e32 v5, v79, v149
	v_fmac_f32_e32 v6, v79, v150
	v_fmac_f32_e32 v7, v79, v151
	v_fmac_f32_e32 v8, v79, v152
	v_fmac_f32_e32 v9, v79, v153
	v_fmac_f32_e32 v10, v79, v154
	v_fmac_f32_e32 v11, v79, v155
	v_fmac_f32_e32 v12, v79, v156
	v_fmac_f32_e32 v13, v79, v157
	v_fmac_f32_e32 v14, v79, v158
	v_fmac_f32_e32 v15, v79, v159
	v_lshl_add_u32 v161, v31, 7, v160
	global_load_dwordx4 v[140:143], v161, s[14:15]
	s_waitcnt lgkmcnt(0)
	ds_read_b128 v[64:67], v163 offset:4672
	ds_read_b128 v[68:71], v163 offset:4688
	ds_read_b128 v[72:75], v163 offset:4704
	ds_read_b128 v[76:79], v163 offset:4720
	s_add_u32 s24, s22, s23
	s_min_u32 s24, s24, 0x200f
	s_lshl_b32 s24, s24, 12
	v_add_u32_e32 v172, s24, v168
	global_load_dwordx4 v[200:203], v172, s[16:17]
	global_load_dwordx4 v[204:207], v172, s[16:17] offset:1024
	global_load_dwordx4 v[208:211], v172, s[16:17] offset:2048
	global_load_dwordx4 v[246:249], v172, s[16:17] offset:3072
	s_waitcnt vmcnt(19)
	v_cvt_pk_f32_fp8_e32 v[144:145], v80
	v_cvt_pk_f32_fp8_sdwa v[146:147], v80 src0_sel:WORD_1
	v_cvt_pk_f32_fp8_e32 v[148:149], v81
	v_cvt_pk_f32_fp8_sdwa v[150:151], v81 src0_sel:WORD_1
	v_cvt_pk_f32_fp8_e32 v[152:153], v82
	v_cvt_pk_f32_fp8_sdwa v[154:155], v82 src0_sel:WORD_1
	v_cvt_pk_f32_fp8_e32 v[156:157], v83
	v_cvt_pk_f32_fp8_sdwa v[158:159], v83 src0_sel:WORD_1
	v_fmac_f32_e32 v0, v48, v144
	v_fmac_f32_e32 v1, v48, v145
	v_fmac_f32_e32 v2, v48, v146
	v_fmac_f32_e32 v3, v48, v147
	v_fmac_f32_e32 v4, v48, v148
	v_fmac_f32_e32 v5, v48, v149
	v_fmac_f32_e32 v6, v48, v150
	v_fmac_f32_e32 v7, v48, v151
	v_fmac_f32_e32 v8, v48, v152
	v_fmac_f32_e32 v9, v48, v153
	v_fmac_f32_e32 v10, v48, v154
	v_fmac_f32_e32 v11, v48, v155
	v_fmac_f32_e32 v12, v48, v156
	v_fmac_f32_e32 v13, v48, v157
	v_fmac_f32_e32 v14, v48, v158
	v_fmac_f32_e32 v15, v48, v159
	v_lshl_add_u32 v161, v32, 7, v160
	global_load_dwordx4 v[80:83], v161, s[14:15]
	s_waitcnt vmcnt(19)
	v_cvt_pk_f32_fp8_e32 v[144:145], v84
	v_cvt_pk_f32_fp8_sdwa v[146:147], v84 src0_sel:WORD_1
	v_cvt_pk_f32_fp8_e32 v[148:149], v85
	v_cvt_pk_f32_fp8_sdwa v[150:151], v85 src0_sel:WORD_1
	v_cvt_pk_f32_fp8_e32 v[152:153], v86
	v_cvt_pk_f32_fp8_sdwa v[154:155], v86 src0_sel:WORD_1
	v_cvt_pk_f32_fp8_e32 v[156:157], v87
	v_cvt_pk_f32_fp8_sdwa v[158:159], v87 src0_sel:WORD_1
	v_fmac_f32_e32 v0, v49, v144
	v_fmac_f32_e32 v1, v49, v145
	v_fmac_f32_e32 v2, v49, v146
	v_fmac_f32_e32 v3, v49, v147
	v_fmac_f32_e32 v4, v49, v148
	v_fmac_f32_e32 v5, v49, v149
	v_fmac_f32_e32 v6, v49, v150
	v_fmac_f32_e32 v7, v49, v151
	v_fmac_f32_e32 v8, v49, v152
	v_fmac_f32_e32 v9, v49, v153
	v_fmac_f32_e32 v10, v49, v154
	v_fmac_f32_e32 v11, v49, v155
	v_fmac_f32_e32 v12, v49, v156
	v_fmac_f32_e32 v13, v49, v157
	v_fmac_f32_e32 v14, v49, v158
	v_fmac_f32_e32 v15, v49, v159
	v_lshl_add_u32 v161, v33, 7, v160
	global_load_dwordx4 v[84:87], v161, s[14:15]
	s_waitcnt vmcnt(19)
	v_cvt_pk_f32_fp8_e32 v[144:145], v88
	v_cvt_pk_f32_fp8_sdwa v[146:147], v88 src0_sel:WORD_1
	v_cvt_pk_f32_fp8_e32 v[148:149], v89
	v_cvt_pk_f32_fp8_sdwa v[150:151], v89 src0_sel:WORD_1
	v_cvt_pk_f32_fp8_e32 v[152:153], v90
	v_cvt_pk_f32_fp8_sdwa v[154:155], v90 src0_sel:WORD_1
	v_cvt_pk_f32_fp8_e32 v[156:157], v91
	v_cvt_pk_f32_fp8_sdwa v[158:159], v91 src0_sel:WORD_1
	v_fmac_f32_e32 v0, v50, v144
	v_fmac_f32_e32 v1, v50, v145
	v_fmac_f32_e32 v2, v50, v146
	v_fmac_f32_e32 v3, v50, v147
	v_fmac_f32_e32 v4, v50, v148
	v_fmac_f32_e32 v5, v50, v149
	v_fmac_f32_e32 v6, v50, v150
	v_fmac_f32_e32 v7, v50, v151
	v_fmac_f32_e32 v8, v50, v152
	v_fmac_f32_e32 v9, v50, v153
	v_fmac_f32_e32 v10, v50, v154
	v_fmac_f32_e32 v11, v50, v155
	v_fmac_f32_e32 v12, v50, v156
	v_fmac_f32_e32 v13, v50, v157
	v_fmac_f32_e32 v14, v50, v158
	v_fmac_f32_e32 v15, v50, v159
	v_lshl_add_u32 v161, v34, 7, v160
	global_load_dwordx4 v[88:91], v161, s[14:15]
	s_waitcnt vmcnt(19)
; DI void phase_peer_b(const Params& p, int layer, const float* gnext, bool last) {
;     ...
; #pragma unroll
;       for (int j = 0; j < 16; ++j) {
;         const int e = bt * 16 + j;
;         const float wj = __int_as_float(__builtin_amdgcn_readlane(__float_as_int(e < 64 ? w0 : w1), e & 63));
; #pragma unroll
;         for (int w = 0; w < 4; ++w) {
;           const f32x2 lo = __builtin_amdgcn_cvt_pk_f32_fp8((int)vr[j][w], false);
;           const f32x2 hi = __builtin_amdgcn_cvt_pk_f32_fp8((int)vr[j][w], true);
;           acc[4 * w] += wj * lo[0]; acc[4 * w + 1] += wj * lo[1]; acc[4 * w + 2] += wj * hi[0]; acc[4 * w + 3] += wj * hi[1];
;         }
;       }
	v_cvt_pk_f32_fp8_e32 v[144:145], v92
	v_cvt_pk_f32_fp8_sdwa v[146:147], v92 src0_sel:WORD_1
	v_cvt_pk_f32_fp8_e32 v[148:149], v93
	v_cvt_pk_f32_fp8_sdwa v[150:151], v93 src0_sel:WORD_1
	v_cvt_pk_f32_fp8_e32 v[152:153], v94
	v_cvt_pk_f32_fp8_sdwa v[154:155], v94 src0_sel:WORD_1
	v_cvt_pk_f32_fp8_e32 v[156:157], v95
	v_cvt_pk_f32_fp8_sdwa v[158:159], v95 src0_sel:WORD_1
	v_fmac_f32_e32 v0, v51, v144
	v_fmac_f32_e32 v1, v51, v145
	v_fmac_f32_e32 v2, v51, v146
	v_fmac_f32_e32 v3, v51, v147
	v_fmac_f32_e32 v4, v51, v148
	v_fmac_f32_e32 v5, v51, v149
	v_fmac_f32_e32 v6, v51, v150
	v_fmac_f32_e32 v7, v51, v151
	v_fmac_f32_e32 v8, v51, v152
	v_fmac_f32_e32 v9, v51, v153
	v_fmac_f32_e32 v10, v51, v154
	v_fmac_f32_e32 v11, v51, v155
	v_fmac_f32_e32 v12, v51, v156
	v_fmac_f32_e32 v13, v51, v157
	v_fmac_f32_e32 v14, v51, v158
	v_fmac_f32_e32 v15, v51, v159
	v_lshl_add_u32 v161, v35, 7, v160
	global_load_dwordx4 v[92:95], v161, s[14:15]
	s_waitcnt vmcnt(19)
	v_cvt_pk_f32_fp8_e32 v[144:145], v96
	v_cvt_pk_f32_fp8_sdwa v[146:147], v96 src0_sel:WORD_1
	v_cvt_pk_f32_fp8_e32 v[148:149], v97
	v_cvt_pk_f32_fp8_sdwa v[150:151], v97 src0_sel:WORD_1
	v_cvt_pk_f32_fp8_e32 v[152:153], v98
	v_cvt_pk_f32_fp8_sdwa v[154:155], v98 src0_sel:WORD_1
	v_cvt_pk_f32_fp8_e32 v[156:157], v99
	v_cvt_pk_f32_fp8_sdwa v[158:159], v99 src0_sel:WORD_1
	v_fmac_f32_e32 v0, v52, v144
	v_fmac_f32_e32 v1, v52, v145
	v_fmac_f32_e32 v2, v52, v146
	v_fmac_f32_e32 v3, v52, v147
	v_fmac_f32_e32 v4, v52, v148
	v_fmac_f32_e32 v5, v52, v149
	v_fmac_f32_e32 v6, v52, v150
	v_fmac_f32_e32 v7, v52, v151
	v_fmac_f32_e32 v8, v52, v152
	v_fmac_f32_e32 v9, v52, v153
	v_fmac_f32_e32 v10, v52, v154
	v_fmac_f32_e32 v11, v52, v155
	v_fmac_f32_e32 v12, v52, v156
	v_fmac_f32_e32 v13, v52, v157
	v_fmac_f32_e32 v14, v52, v158
	v_fmac_f32_e32 v15, v52, v159
	v_lshl_add_u32 v161, v36, 7, v160
	global_load_dwordx4 v[96:99], v161, s[14:15]
	s_waitcnt vmcnt(19)
	v_cvt_pk_f32_fp8_e32 v[144:145], v100
	v_cvt_pk_f32_fp8_sdwa v[146:147], v100 src0_sel:WORD_1
	v_cvt_pk_f32_fp8_e32 v[148:149], v101
	v_cvt_pk_f32_fp8_sdwa v[150:151], v101 src0_sel:WORD_1
	v_cvt_pk_f32_fp8_e32 v[152:153], v102
	v_cvt_pk_f32_fp8_sdwa v[154:155], v102 src0_sel:WORD_1
	v_cvt_pk_f32_fp8_e32 v[156:157], v103
	v_cvt_pk_f32_fp8_sdwa v[158:159], v103 src0_sel:WORD_1
	v_fmac_f32_e32 v0, v53, v144
	v_fmac_f32_e32 v1, v53, v145
	v_fmac_f32_e32 v2, v53, v146
	v_fmac_f32_e32 v3, v53, v147
	v_fmac_f32_e32 v4, v53, v148
	v_fmac_f32_e32 v5, v53, v149
	v_fmac_f32_e32 v6, v53, v150
	v_fmac_f32_e32 v7, v53, v151
	v_fmac_f32_e32 v8, v53, v152
	v_fmac_f32_e32 v9, v53, v153
	v_fmac_f32_e32 v10, v53, v154
	v_fmac_f32_e32 v11, v53, v155
	v_fmac_f32_e32 v12, v53, v156
	v_fmac_f32_e32 v13, v53, v157
	v_fmac_f32_e32 v14, v53, v158
	v_fmac_f32_e32 v15, v53, v159
	v_lshl_add_u32 v161, v37, 7, v160
	global_load_dwordx4 v[100:103], v161, s[14:15]
	s_waitcnt vmcnt(19)
	v_cvt_pk_f32_fp8_e32 v[144:145], v104
	v_cvt_pk_f32_fp8_sdwa v[146:147], v104 src0_sel:WORD_1
	v_cvt_pk_f32_fp8_e32 v[148:149], v105
	v_cvt_pk_f32_fp8_sdwa v[150:151], v105 src0_sel:WORD_1
	v_cvt_pk_f32_fp8_e32 v[152:153], v106
	v_cvt_pk_f32_fp8_sdwa v[154:155], v106 src0_sel:WORD_1
	v_cvt_pk_f32_fp8_e32 v[156:157], v107
	v_cvt_pk_f32_fp8_sdwa v[158:159], v107 src0_sel:WORD_1
	v_fmac_f32_e32 v0, v54, v144
	v_fmac_f32_e32 v1, v54, v145
	v_fmac_f32_e32 v2, v54, v146
	v_fmac_f32_e32 v3, v54, v147
	v_fmac_f32_e32 v4, v54, v148
	v_fmac_f32_e32 v5, v54, v149
	v_fmac_f32_e32 v6, v54, v150
	v_fmac_f32_e32 v7, v54, v151
	v_fmac_f32_e32 v8, v54, v152
	v_fmac_f32_e32 v9, v54, v153
	v_fmac_f32_e32 v10, v54, v154
	v_fmac_f32_e32 v11, v54, v155
	v_fmac_f32_e32 v12, v54, v156
	v_fmac_f32_e32 v13, v54, v157
	v_fmac_f32_e32 v14, v54, v158
	v_fmac_f32_e32 v15, v54, v159
	v_lshl_add_u32 v161, v38, 7, v160
	global_load_dwordx4 v[104:107], v161, s[14:15]
	s_waitcnt vmcnt(19)
	v_cvt_pk_f32_fp8_e32 v[144:145], v108
	v_cvt_pk_f32_fp8_sdwa v[146:147], v108 src0_sel:WORD_1
	v_cvt_pk_f32_fp8_e32 v[148:149], v109
	v_cvt_pk_f32_fp8_sdwa v[150:151], v109 src0_sel:WORD_1
	v_cvt_pk_f32_fp8_e32 v[152:153], v110
	v_cvt_pk_f32_fp8_sdwa v[154:155], v110 src0_sel:WORD_1
	v_cvt_pk_f32_fp8_e32 v[156:157], v111
	v_cvt_pk_f32_fp8_sdwa v[158:159], v111 src0_sel:WORD_1
	v_fmac_f32_e32 v0, v55, v144
	v_fmac_f32_e32 v1, v55, v145
	v_fmac_f32_e32 v2, v55, v146
	v_fmac_f32_e32 v3, v55, v147
	v_fmac_f32_e32 v4, v55, v148
	v_fmac_f32_e32 v5, v55, v149
	v_fmac_f32_e32 v6, v55, v150
	v_fmac_f32_e32 v7, v55, v151
	v_fmac_f32_e32 v8, v55, v152
	v_fmac_f32_e32 v9, v55, v153
	v_fmac_f32_e32 v10, v55, v154
	v_fmac_f32_e32 v11, v55, v155
	v_fmac_f32_e32 v12, v55, v156
	v_fmac_f32_e32 v13, v55, v157
	v_fmac_f32_e32 v14, v55, v158
	v_fmac_f32_e32 v15, v55, v159
	v_lshl_add_u32 v161, v39, 7, v160
	global_load_dwordx4 v[108:111], v161, s[14:15]
	s_waitcnt vmcnt(19)
	v_cvt_pk_f32_fp8_e32 v[144:145], v112
	v_cvt_pk_f32_fp8_sdwa v[146:147], v112 src0_sel:WORD_1
	v_cvt_pk_f32_fp8_e32 v[148:149], v113
	v_cvt_pk_f32_fp8_sdwa v[150:151], v113 src0_sel:WORD_1
	v_cvt_pk_f32_fp8_e32 v[152:153], v114
	v_cvt_pk_f32_fp8_sdwa v[154:155], v114 src0_sel:WORD_1
	v_cvt_pk_f32_fp8_e32 v[156:157], v115
	v_cvt_pk_f32_fp8_sdwa v[158:159], v115 src0_sel:WORD_1
	v_fmac_f32_e32 v0, v56, v144
	v_fmac_f32_e32 v1, v56, v145
	v_fmac_f32_e32 v2, v56, v146
	v_fmac_f32_e32 v3, v56, v147
	v_fmac_f32_e32 v4, v56, v148
	v_fmac_f32_e32 v5, v56, v149
	v_fmac_f32_e32 v6, v56, v150
	v_fmac_f32_e32 v7, v56, v151
	v_fmac_f32_e32 v8, v56, v152
	v_fmac_f32_e32 v9, v56, v153
	v_fmac_f32_e32 v10, v56, v154
	v_fmac_f32_e32 v11, v56, v155
	v_fmac_f32_e32 v12, v56, v156
	v_fmac_f32_e32 v13, v56, v157
	v_fmac_f32_e32 v14, v56, v158
	v_fmac_f32_e32 v15, v56, v159
	v_lshl_add_u32 v161, v40, 7, v160
	global_load_dwordx4 v[112:115], v161, s[14:15]
	s_waitcnt vmcnt(19)
; DI void phase_peer_b(const Params& p, int layer, const float* gnext, bool last) {
;     ...
; #pragma unroll
;       for (int j = 0; j < 16; ++j) {
;         const int e = bt * 16 + j;
;         const float wj = __int_as_float(__builtin_amdgcn_readlane(__float_as_int(e < 64 ? w0 : w1), e & 63));
; #pragma unroll
;         for (int w = 0; w < 4; ++w) {
;           const f32x2 lo = __builtin_amdgcn_cvt_pk_f32_fp8((int)vr[j][w], false);
;           const f32x2 hi = __builtin_amdgcn_cvt_pk_f32_fp8((int)vr[j][w], true);
;           acc[4 * w] += wj * lo[0]; acc[4 * w + 1] += wj * lo[1]; acc[4 * w + 2] += wj * hi[0]; acc[4 * w + 3] += wj * hi[1];
;         }
;       }
	v_cvt_pk_f32_fp8_e32 v[144:145], v116
	v_cvt_pk_f32_fp8_sdwa v[146:147], v116 src0_sel:WORD_1
	v_cvt_pk_f32_fp8_e32 v[148:149], v117
	v_cvt_pk_f32_fp8_sdwa v[150:151], v117 src0_sel:WORD_1
	v_cvt_pk_f32_fp8_e32 v[152:153], v118
	v_cvt_pk_f32_fp8_sdwa v[154:155], v118 src0_sel:WORD_1
	v_cvt_pk_f32_fp8_e32 v[156:157], v119
	v_cvt_pk_f32_fp8_sdwa v[158:159], v119 src0_sel:WORD_1
	v_fmac_f32_e32 v0, v57, v144
	v_fmac_f32_e32 v1, v57, v145
	v_fmac_f32_e32 v2, v57, v146
	v_fmac_f32_e32 v3, v57, v147
	v_fmac_f32_e32 v4, v57, v148
	v_fmac_f32_e32 v5, v57, v149
	v_fmac_f32_e32 v6, v57, v150
	v_fmac_f32_e32 v7, v57, v151
	v_fmac_f32_e32 v8, v57, v152
	v_fmac_f32_e32 v9, v57, v153
	v_fmac_f32_e32 v10, v57, v154
	v_fmac_f32_e32 v11, v57, v155
	v_fmac_f32_e32 v12, v57, v156
	v_fmac_f32_e32 v13, v57, v157
	v_fmac_f32_e32 v14, v57, v158
	v_fmac_f32_e32 v15, v57, v159
	v_lshl_add_u32 v161, v41, 7, v160
	global_load_dwordx4 v[116:119], v161, s[14:15]
	s_waitcnt vmcnt(19)
	v_cvt_pk_f32_fp8_e32 v[144:145], v120
	v_cvt_pk_f32_fp8_sdwa v[146:147], v120 src0_sel:WORD_1
	v_cvt_pk_f32_fp8_e32 v[148:149], v121
	v_cvt_pk_f32_fp8_sdwa v[150:151], v121 src0_sel:WORD_1
	v_cvt_pk_f32_fp8_e32 v[152:153], v122
	v_cvt_pk_f32_fp8_sdwa v[154:155], v122 src0_sel:WORD_1
	v_cvt_pk_f32_fp8_e32 v[156:157], v123
	v_cvt_pk_f32_fp8_sdwa v[158:159], v123 src0_sel:WORD_1
	v_fmac_f32_e32 v0, v58, v144
	v_fmac_f32_e32 v1, v58, v145
	v_fmac_f32_e32 v2, v58, v146
	v_fmac_f32_e32 v3, v58, v147
	v_fmac_f32_e32 v4, v58, v148
	v_fmac_f32_e32 v5, v58, v149
	v_fmac_f32_e32 v6, v58, v150
	v_fmac_f32_e32 v7, v58, v151
	v_fmac_f32_e32 v8, v58, v152
	v_fmac_f32_e32 v9, v58, v153
	v_fmac_f32_e32 v10, v58, v154
	v_fmac_f32_e32 v11, v58, v155
	v_fmac_f32_e32 v12, v58, v156
	v_fmac_f32_e32 v13, v58, v157
	v_fmac_f32_e32 v14, v58, v158
	v_fmac_f32_e32 v15, v58, v159
	v_lshl_add_u32 v161, v42, 7, v160
	global_load_dwordx4 v[120:123], v161, s[14:15]
	s_waitcnt vmcnt(19)
	v_cvt_pk_f32_fp8_e32 v[144:145], v124
	v_cvt_pk_f32_fp8_sdwa v[146:147], v124 src0_sel:WORD_1
	v_cvt_pk_f32_fp8_e32 v[148:149], v125
	v_cvt_pk_f32_fp8_sdwa v[150:151], v125 src0_sel:WORD_1
	v_cvt_pk_f32_fp8_e32 v[152:153], v126
	v_cvt_pk_f32_fp8_sdwa v[154:155], v126 src0_sel:WORD_1
	v_cvt_pk_f32_fp8_e32 v[156:157], v127
	v_cvt_pk_f32_fp8_sdwa v[158:159], v127 src0_sel:WORD_1
	v_fmac_f32_e32 v0, v59, v144
	v_fmac_f32_e32 v1, v59, v145
	v_fmac_f32_e32 v2, v59, v146
	v_fmac_f32_e32 v3, v59, v147
	v_fmac_f32_e32 v4, v59, v148
	v_fmac_f32_e32 v5, v59, v149
	v_fmac_f32_e32 v6, v59, v150
	v_fmac_f32_e32 v7, v59, v151
	v_fmac_f32_e32 v8, v59, v152
	v_fmac_f32_e32 v9, v59, v153
	v_fmac_f32_e32 v10, v59, v154
	v_fmac_f32_e32 v11, v59, v155
	v_fmac_f32_e32 v12, v59, v156
	v_fmac_f32_e32 v13, v59, v157
	v_fmac_f32_e32 v14, v59, v158
	v_fmac_f32_e32 v15, v59, v159
	v_lshl_add_u32 v161, v43, 7, v160
	global_load_dwordx4 v[124:127], v161, s[14:15]
	s_waitcnt vmcnt(19)
	v_cvt_pk_f32_fp8_e32 v[144:145], v128
	v_cvt_pk_f32_fp8_sdwa v[146:147], v128 src0_sel:WORD_1
	v_cvt_pk_f32_fp8_e32 v[148:149], v129
	v_cvt_pk_f32_fp8_sdwa v[150:151], v129 src0_sel:WORD_1
	v_cvt_pk_f32_fp8_e32 v[152:153], v130
	v_cvt_pk_f32_fp8_sdwa v[154:155], v130 src0_sel:WORD_1
	v_cvt_pk_f32_fp8_e32 v[156:157], v131
	v_cvt_pk_f32_fp8_sdwa v[158:159], v131 src0_sel:WORD_1
	v_fmac_f32_e32 v0, v60, v144
	v_fmac_f32_e32 v1, v60, v145
	v_fmac_f32_e32 v2, v60, v146
	v_fmac_f32_e32 v3, v60, v147
	v_fmac_f32_e32 v4, v60, v148
	v_fmac_f32_e32 v5, v60, v149
	v_fmac_f32_e32 v6, v60, v150
	v_fmac_f32_e32 v7, v60, v151
	v_fmac_f32_e32 v8, v60, v152
	v_fmac_f32_e32 v9, v60, v153
	v_fmac_f32_e32 v10, v60, v154
	v_fmac_f32_e32 v11, v60, v155
	v_fmac_f32_e32 v12, v60, v156
	v_fmac_f32_e32 v13, v60, v157
	v_fmac_f32_e32 v14, v60, v158
	v_fmac_f32_e32 v15, v60, v159
	v_lshl_add_u32 v161, v44, 7, v160
	global_load_dwordx4 v[128:131], v161, s[14:15]
	s_waitcnt vmcnt(19)
	v_cvt_pk_f32_fp8_e32 v[144:145], v132
	v_cvt_pk_f32_fp8_sdwa v[146:147], v132 src0_sel:WORD_1
	v_cvt_pk_f32_fp8_e32 v[148:149], v133
	v_cvt_pk_f32_fp8_sdwa v[150:151], v133 src0_sel:WORD_1
	v_cvt_pk_f32_fp8_e32 v[152:153], v134
	v_cvt_pk_f32_fp8_sdwa v[154:155], v134 src0_sel:WORD_1
	v_cvt_pk_f32_fp8_e32 v[156:157], v135
	v_cvt_pk_f32_fp8_sdwa v[158:159], v135 src0_sel:WORD_1
	v_fmac_f32_e32 v0, v61, v144
	v_fmac_f32_e32 v1, v61, v145
	v_fmac_f32_e32 v2, v61, v146
	v_fmac_f32_e32 v3, v61, v147
	v_fmac_f32_e32 v4, v61, v148
	v_fmac_f32_e32 v5, v61, v149
	v_fmac_f32_e32 v6, v61, v150
	v_fmac_f32_e32 v7, v61, v151
	v_fmac_f32_e32 v8, v61, v152
	v_fmac_f32_e32 v9, v61, v153
	v_fmac_f32_e32 v10, v61, v154
	v_fmac_f32_e32 v11, v61, v155
	v_fmac_f32_e32 v12, v61, v156
	v_fmac_f32_e32 v13, v61, v157
	v_fmac_f32_e32 v14, v61, v158
	v_fmac_f32_e32 v15, v61, v159
	v_lshl_add_u32 v161, v45, 7, v160
	global_load_dwordx4 v[132:135], v161, s[14:15]
	s_waitcnt vmcnt(19)
	v_cvt_pk_f32_fp8_e32 v[144:145], v136
	v_cvt_pk_f32_fp8_sdwa v[146:147], v136 src0_sel:WORD_1
	v_cvt_pk_f32_fp8_e32 v[148:149], v137
	v_cvt_pk_f32_fp8_sdwa v[150:151], v137 src0_sel:WORD_1
	v_cvt_pk_f32_fp8_e32 v[152:153], v138
	v_cvt_pk_f32_fp8_sdwa v[154:155], v138 src0_sel:WORD_1
	v_cvt_pk_f32_fp8_e32 v[156:157], v139
	v_cvt_pk_f32_fp8_sdwa v[158:159], v139 src0_sel:WORD_1
	v_fmac_f32_e32 v0, v62, v144
	v_fmac_f32_e32 v1, v62, v145
	v_fmac_f32_e32 v2, v62, v146
	v_fmac_f32_e32 v3, v62, v147
	v_fmac_f32_e32 v4, v62, v148
	v_fmac_f32_e32 v5, v62, v149
	v_fmac_f32_e32 v6, v62, v150
	v_fmac_f32_e32 v7, v62, v151
	v_fmac_f32_e32 v8, v62, v152
	v_fmac_f32_e32 v9, v62, v153
	v_fmac_f32_e32 v10, v62, v154
	v_fmac_f32_e32 v11, v62, v155
	v_fmac_f32_e32 v12, v62, v156
	v_fmac_f32_e32 v13, v62, v157
	v_fmac_f32_e32 v14, v62, v158
	v_fmac_f32_e32 v15, v62, v159
	v_lshl_add_u32 v161, v46, 7, v160
	global_load_dwordx4 v[136:139], v161, s[14:15]
	s_waitcnt vmcnt(19)
; DI void phase_peer_b(const Params& p, int layer, const float* gnext, bool last) {
;     ...
;     const int i0 = ibuf[row * 128 + lane], i1 = ibuf[row * 128 + 64 + lane];
;     const float w0 = wbuf[row * 128 + lane], w1 = wbuf[row * 128 + 64 + lane];
;     float acc[16];
; #pragma unroll
;     for (int i = 0; i < 16; ++i) acc[i] = 0.f;
; #pragma unroll 1
;     for (int bt = 0; bt < 8; ++bt) {
;       u32x4 vr[16];
; #pragma unroll
;       for (int j = 0; j < 16; ++j) {
;         const int e = bt * 16 + j;
;         const int eidx = __builtin_amdgcn_readlane(e < 64 ? i0 : i1, e & 63);
;         vr[j] = *(const u32x4*)(EV + (size_t)eidx * DM + lane * 16);
;       }
; #pragma unroll
;       for (int j = 0; j < 16; ++j) {
;         const int e = bt * 16 + j;
;         const float wj = __int_as_float(__builtin_amdgcn_readlane(__float_as_int(e < 64 ? w0 : w1), e & 63));
; #pragma unroll
;         for (int w = 0; w < 4; ++w) {
;           const f32x2 lo = __builtin_amdgcn_cvt_pk_f32_fp8((int)vr[j][w], false);
;           const f32x2 hi = __builtin_amdgcn_cvt_pk_f32_fp8((int)vr[j][w], true);
;           acc[4 * w] += wj * lo[0]; acc[4 * w + 1] += wj * lo[1]; acc[4 * w + 2] += wj * hi[0]; acc[4 * w + 3] += wj * hi[1];
;         }
;       }
;     }
;       float* hp = hbuf + row * DM;
;       float hn[16];
; #pragma unroll
;       for (int q = 0; q < 2; ++q) {
;         const float4 a = *(const float4*)(hp + lane * 16 + q * 8);
;         const float4 bq = *(const float4*)(hp + lane * 16 + q * 8 + 4);
	v_cvt_pk_f32_fp8_e32 v[144:145], v140
	v_cvt_pk_f32_fp8_sdwa v[146:147], v140 src0_sel:WORD_1
	v_cvt_pk_f32_fp8_e32 v[148:149], v141
	v_cvt_pk_f32_fp8_sdwa v[150:151], v141 src0_sel:WORD_1
	v_cvt_pk_f32_fp8_e32 v[152:153], v142
	v_cvt_pk_f32_fp8_sdwa v[154:155], v142 src0_sel:WORD_1
	v_cvt_pk_f32_fp8_e32 v[156:157], v143
	v_cvt_pk_f32_fp8_sdwa v[158:159], v143 src0_sel:WORD_1
	v_fmac_f32_e32 v0, v63, v144
	v_fmac_f32_e32 v1, v63, v145
	v_fmac_f32_e32 v2, v63, v146
	v_fmac_f32_e32 v3, v63, v147
	v_fmac_f32_e32 v4, v63, v148
	v_fmac_f32_e32 v5, v63, v149
	v_fmac_f32_e32 v6, v63, v150
	v_fmac_f32_e32 v7, v63, v151
	v_fmac_f32_e32 v8, v63, v152
	v_fmac_f32_e32 v9, v63, v153
	v_fmac_f32_e32 v10, v63, v154
	v_fmac_f32_e32 v11, v63, v155
	v_fmac_f32_e32 v12, v63, v156
	v_fmac_f32_e32 v13, v63, v157
	v_fmac_f32_e32 v14, v63, v158
	v_fmac_f32_e32 v15, v63, v159
	v_lshl_add_u32 v161, v47, 7, v160
	global_load_dwordx4 v[140:143], v161, s[14:15]
	s_waitcnt lgkmcnt(0)
	s_waitcnt vmcnt(16)
	ds_write_b128 v162, v[200:203]
	ds_write_b128 v162, v[204:207] offset:1056
	ds_write_b128 v162, v[208:211] offset:2112
	ds_write_b128 v162, v[246:249] offset:3168
	global_load_dwordx4 v[230:233], v164, s[20:21]
	global_load_dwordx4 v[234:237], v164, s[20:21] offset:16
	global_load_dwordx4 v[238:241], v164, s[20:21] offset:32
	global_load_dwordx4 v[242:245], v164, s[20:21] offset:48
	global_load_dwordx4 v[48:51], v172, s[18:19]
	global_load_dwordx4 v[52:55], v172, s[18:19] offset:1024
	global_load_dwordx4 v[56:59], v172, s[18:19] offset:2048
	global_load_dwordx4 v[60:63], v172, s[18:19] offset:3072
	s_waitcnt lgkmcnt(0)
	ds_read_b128 v[16:19], v163
	ds_read_b128 v[20:23], v163 offset:16
	ds_read_b128 v[24:27], v163 offset:32
	ds_read_b128 v[28:31], v163 offset:48
	ds_read_b128 v[32:35], v163 offset:64
	ds_read_b128 v[36:39], v163 offset:80
	ds_read_b128 v[40:43], v163 offset:96
	ds_read_b128 v[44:47], v163 offset:112
	s_waitcnt lgkmcnt(0)
	s_waitcnt vmcnt(23)
	v_cvt_pk_f32_fp8_e32 v[144:145], v80
	v_cvt_pk_f32_fp8_sdwa v[146:147], v80 src0_sel:WORD_1
	v_cvt_pk_f32_fp8_e32 v[148:149], v81
	v_cvt_pk_f32_fp8_sdwa v[150:151], v81 src0_sel:WORD_1
	v_cvt_pk_f32_fp8_e32 v[152:153], v82
	v_cvt_pk_f32_fp8_sdwa v[154:155], v82 src0_sel:WORD_1
	v_cvt_pk_f32_fp8_e32 v[156:157], v83
	v_cvt_pk_f32_fp8_sdwa v[158:159], v83 src0_sel:WORD_1
	v_fmac_f32_e32 v0, v64, v144
	v_fmac_f32_e32 v1, v64, v145
	v_fmac_f32_e32 v2, v64, v146
	v_fmac_f32_e32 v3, v64, v147
	v_fmac_f32_e32 v4, v64, v148
	v_fmac_f32_e32 v5, v64, v149
	v_fmac_f32_e32 v6, v64, v150
	v_fmac_f32_e32 v7, v64, v151
	v_fmac_f32_e32 v8, v64, v152
	v_fmac_f32_e32 v9, v64, v153
	v_fmac_f32_e32 v10, v64, v154
	v_fmac_f32_e32 v11, v64, v155
	v_fmac_f32_e32 v12, v64, v156
	v_fmac_f32_e32 v13, v64, v157
	v_fmac_f32_e32 v14, v64, v158
	v_fmac_f32_e32 v15, v64, v159
	v_lshl_add_u32 v161, v16, 7, v160
	global_load_dwordx4 v[80:83], v161, s[14:15]
	s_waitcnt vmcnt(23)
	v_cvt_pk_f32_fp8_e32 v[144:145], v84
	v_cvt_pk_f32_fp8_sdwa v[146:147], v84 src0_sel:WORD_1
	v_cvt_pk_f32_fp8_e32 v[148:149], v85
	v_cvt_pk_f32_fp8_sdwa v[150:151], v85 src0_sel:WORD_1
	v_cvt_pk_f32_fp8_e32 v[152:153], v86
	v_cvt_pk_f32_fp8_sdwa v[154:155], v86 src0_sel:WORD_1
	v_cvt_pk_f32_fp8_e32 v[156:157], v87
	v_cvt_pk_f32_fp8_sdwa v[158:159], v87 src0_sel:WORD_1
	v_fmac_f32_e32 v0, v65, v144
	v_fmac_f32_e32 v1, v65, v145
	v_fmac_f32_e32 v2, v65, v146
	v_fmac_f32_e32 v3, v65, v147
	v_fmac_f32_e32 v4, v65, v148
	v_fmac_f32_e32 v5, v65, v149
	v_fmac_f32_e32 v6, v65, v150
	v_fmac_f32_e32 v7, v65, v151
	v_fmac_f32_e32 v8, v65, v152
	v_fmac_f32_e32 v9, v65, v153
	v_fmac_f32_e32 v10, v65, v154
	v_fmac_f32_e32 v11, v65, v155
	v_fmac_f32_e32 v12, v65, v156
	v_fmac_f32_e32 v13, v65, v157
	v_fmac_f32_e32 v14, v65, v158
	v_fmac_f32_e32 v15, v65, v159
	v_lshl_add_u32 v161, v17, 7, v160
	global_load_dwordx4 v[84:87], v161, s[14:15]
	s_waitcnt vmcnt(23)
	v_cvt_pk_f32_fp8_e32 v[144:145], v88
	v_cvt_pk_f32_fp8_sdwa v[146:147], v88 src0_sel:WORD_1
	v_cvt_pk_f32_fp8_e32 v[148:149], v89
	v_cvt_pk_f32_fp8_sdwa v[150:151], v89 src0_sel:WORD_1
	v_cvt_pk_f32_fp8_e32 v[152:153], v90
	v_cvt_pk_f32_fp8_sdwa v[154:155], v90 src0_sel:WORD_1
	v_cvt_pk_f32_fp8_e32 v[156:157], v91
	v_cvt_pk_f32_fp8_sdwa v[158:159], v91 src0_sel:WORD_1
	v_fmac_f32_e32 v0, v66, v144
	v_fmac_f32_e32 v1, v66, v145
	v_fmac_f32_e32 v2, v66, v146
	v_fmac_f32_e32 v3, v66, v147
	v_fmac_f32_e32 v4, v66, v148
	v_fmac_f32_e32 v5, v66, v149
	v_fmac_f32_e32 v6, v66, v150
	v_fmac_f32_e32 v7, v66, v151
	v_fmac_f32_e32 v8, v66, v152
	v_fmac_f32_e32 v9, v66, v153
	v_fmac_f32_e32 v10, v66, v154
	v_fmac_f32_e32 v11, v66, v155
	v_fmac_f32_e32 v12, v66, v156
	v_fmac_f32_e32 v13, v66, v157
	v_fmac_f32_e32 v14, v66, v158
	v_fmac_f32_e32 v15, v66, v159
	v_lshl_add_u32 v161, v18, 7, v160
	global_load_dwordx4 v[88:91], v161, s[14:15]
	s_waitcnt vmcnt(23)
	v_cvt_pk_f32_fp8_e32 v[144:145], v92
	v_cvt_pk_f32_fp8_sdwa v[146:147], v92 src0_sel:WORD_1
	v_cvt_pk_f32_fp8_e32 v[148:149], v93
	v_cvt_pk_f32_fp8_sdwa v[150:151], v93 src0_sel:WORD_1
	v_cvt_pk_f32_fp8_e32 v[152:153], v94
	v_cvt_pk_f32_fp8_sdwa v[154:155], v94 src0_sel:WORD_1
	v_cvt_pk_f32_fp8_e32 v[156:157], v95
	v_cvt_pk_f32_fp8_sdwa v[158:159], v95 src0_sel:WORD_1
	v_fmac_f32_e32 v0, v67, v144
	v_fmac_f32_e32 v1, v67, v145
	v_fmac_f32_e32 v2, v67, v146
	v_fmac_f32_e32 v3, v67, v147
	v_fmac_f32_e32 v4, v67, v148
	v_fmac_f32_e32 v5, v67, v149
	v_fmac_f32_e32 v6, v67, v150
	v_fmac_f32_e32 v7, v67, v151
	v_fmac_f32_e32 v8, v67, v152
	v_fmac_f32_e32 v9, v67, v153
	v_fmac_f32_e32 v10, v67, v154
	v_fmac_f32_e32 v11, v67, v155
	v_fmac_f32_e32 v12, v67, v156
	v_fmac_f32_e32 v13, v67, v157
	v_fmac_f32_e32 v14, v67, v158
	v_fmac_f32_e32 v15, v67, v159
	v_lshl_add_u32 v161, v19, 7, v160
	global_load_dwordx4 v[92:95], v161, s[14:15]
	s_waitcnt vmcnt(23)
; DI void phase_peer_b(const Params& p, int layer, const float* gnext, bool last) {
;     ...
;     for (int bt = 0; bt < 8; ++bt) {
;       u32x4 vr[16];
; #pragma unroll
;       for (int j = 0; j < 16; ++j) {
;         const int e = bt * 16 + j;
;         const int eidx = __builtin_amdgcn_readlane(e < 64 ? i0 : i1, e & 63);
;         vr[j] = *(const u32x4*)(EV + (size_t)eidx * DM + lane * 16);
;       }
; #pragma unroll
;       for (int j = 0; j < 16; ++j) {
;         const int e = bt * 16 + j;
;         const float wj = __int_as_float(__builtin_amdgcn_readlane(__float_as_int(e < 64 ? w0 : w1), e & 63));
; #pragma unroll
;         for (int w = 0; w < 4; ++w) {
;           const f32x2 lo = __builtin_amdgcn_cvt_pk_f32_fp8((int)vr[j][w], false);
;           const f32x2 hi = __builtin_amdgcn_cvt_pk_f32_fp8((int)vr[j][w], true);
;           acc[4 * w] += wj * lo[0]; acc[4 * w + 1] += wj * lo[1]; acc[4 * w + 2] += wj * hi[0]; acc[4 * w + 3] += wj * hi[1];
;         }
;       }
	v_cvt_pk_f32_fp8_e32 v[144:145], v96
	v_cvt_pk_f32_fp8_sdwa v[146:147], v96 src0_sel:WORD_1
	v_cvt_pk_f32_fp8_e32 v[148:149], v97
	v_cvt_pk_f32_fp8_sdwa v[150:151], v97 src0_sel:WORD_1
	v_cvt_pk_f32_fp8_e32 v[152:153], v98
	v_cvt_pk_f32_fp8_sdwa v[154:155], v98 src0_sel:WORD_1
	v_cvt_pk_f32_fp8_e32 v[156:157], v99
	v_cvt_pk_f32_fp8_sdwa v[158:159], v99 src0_sel:WORD_1
	v_fmac_f32_e32 v0, v68, v144
	v_fmac_f32_e32 v1, v68, v145
	v_fmac_f32_e32 v2, v68, v146
	v_fmac_f32_e32 v3, v68, v147
	v_fmac_f32_e32 v4, v68, v148
	v_fmac_f32_e32 v5, v68, v149
	v_fmac_f32_e32 v6, v68, v150
	v_fmac_f32_e32 v7, v68, v151
	v_fmac_f32_e32 v8, v68, v152
	v_fmac_f32_e32 v9, v68, v153
	v_fmac_f32_e32 v10, v68, v154
	v_fmac_f32_e32 v11, v68, v155
	v_fmac_f32_e32 v12, v68, v156
	v_fmac_f32_e32 v13, v68, v157
	v_fmac_f32_e32 v14, v68, v158
	v_fmac_f32_e32 v15, v68, v159
	v_lshl_add_u32 v161, v20, 7, v160
	global_load_dwordx4 v[96:99], v161, s[14:15]
	s_waitcnt vmcnt(23)
	v_cvt_pk_f32_fp8_e32 v[144:145], v100
	v_cvt_pk_f32_fp8_sdwa v[146:147], v100 src0_sel:WORD_1
	v_cvt_pk_f32_fp8_e32 v[148:149], v101
	v_cvt_pk_f32_fp8_sdwa v[150:151], v101 src0_sel:WORD_1
	v_cvt_pk_f32_fp8_e32 v[152:153], v102
	v_cvt_pk_f32_fp8_sdwa v[154:155], v102 src0_sel:WORD_1
	v_cvt_pk_f32_fp8_e32 v[156:157], v103
	v_cvt_pk_f32_fp8_sdwa v[158:159], v103 src0_sel:WORD_1
	v_fmac_f32_e32 v0, v69, v144
	v_fmac_f32_e32 v1, v69, v145
	v_fmac_f32_e32 v2, v69, v146
	v_fmac_f32_e32 v3, v69, v147
	v_fmac_f32_e32 v4, v69, v148
	v_fmac_f32_e32 v5, v69, v149
	v_fmac_f32_e32 v6, v69, v150
	v_fmac_f32_e32 v7, v69, v151
	v_fmac_f32_e32 v8, v69, v152
	v_fmac_f32_e32 v9, v69, v153
	v_fmac_f32_e32 v10, v69, v154
	v_fmac_f32_e32 v11, v69, v155
	v_fmac_f32_e32 v12, v69, v156
	v_fmac_f32_e32 v13, v69, v157
	v_fmac_f32_e32 v14, v69, v158
	v_fmac_f32_e32 v15, v69, v159
	v_lshl_add_u32 v161, v21, 7, v160
	global_load_dwordx4 v[100:103], v161, s[14:15]
	s_waitcnt vmcnt(23)
	v_cvt_pk_f32_fp8_e32 v[144:145], v104
	v_cvt_pk_f32_fp8_sdwa v[146:147], v104 src0_sel:WORD_1
	v_cvt_pk_f32_fp8_e32 v[148:149], v105
	v_cvt_pk_f32_fp8_sdwa v[150:151], v105 src0_sel:WORD_1
	v_cvt_pk_f32_fp8_e32 v[152:153], v106
	v_cvt_pk_f32_fp8_sdwa v[154:155], v106 src0_sel:WORD_1
	v_cvt_pk_f32_fp8_e32 v[156:157], v107
	v_cvt_pk_f32_fp8_sdwa v[158:159], v107 src0_sel:WORD_1
	v_fmac_f32_e32 v0, v70, v144
	v_fmac_f32_e32 v1, v70, v145
	v_fmac_f32_e32 v2, v70, v146
	v_fmac_f32_e32 v3, v70, v147
	v_fmac_f32_e32 v4, v70, v148
	v_fmac_f32_e32 v5, v70, v149
	v_fmac_f32_e32 v6, v70, v150
	v_fmac_f32_e32 v7, v70, v151
	v_fmac_f32_e32 v8, v70, v152
	v_fmac_f32_e32 v9, v70, v153
	v_fmac_f32_e32 v10, v70, v154
	v_fmac_f32_e32 v11, v70, v155
	v_fmac_f32_e32 v12, v70, v156
	v_fmac_f32_e32 v13, v70, v157
	v_fmac_f32_e32 v14, v70, v158
	v_fmac_f32_e32 v15, v70, v159
	v_lshl_add_u32 v161, v22, 7, v160
	global_load_dwordx4 v[104:107], v161, s[14:15]
	s_waitcnt vmcnt(23)
	v_cvt_pk_f32_fp8_e32 v[144:145], v108
	v_cvt_pk_f32_fp8_sdwa v[146:147], v108 src0_sel:WORD_1
	v_cvt_pk_f32_fp8_e32 v[148:149], v109
	v_cvt_pk_f32_fp8_sdwa v[150:151], v109 src0_sel:WORD_1
	v_cvt_pk_f32_fp8_e32 v[152:153], v110
	v_cvt_pk_f32_fp8_sdwa v[154:155], v110 src0_sel:WORD_1
	v_cvt_pk_f32_fp8_e32 v[156:157], v111
	v_cvt_pk_f32_fp8_sdwa v[158:159], v111 src0_sel:WORD_1
	v_fmac_f32_e32 v0, v71, v144
	v_fmac_f32_e32 v1, v71, v145
	v_fmac_f32_e32 v2, v71, v146
	v_fmac_f32_e32 v3, v71, v147
	v_fmac_f32_e32 v4, v71, v148
	v_fmac_f32_e32 v5, v71, v149
	v_fmac_f32_e32 v6, v71, v150
	v_fmac_f32_e32 v7, v71, v151
	v_fmac_f32_e32 v8, v71, v152
	v_fmac_f32_e32 v9, v71, v153
	v_fmac_f32_e32 v10, v71, v154
	v_fmac_f32_e32 v11, v71, v155
	v_fmac_f32_e32 v12, v71, v156
	v_fmac_f32_e32 v13, v71, v157
	v_fmac_f32_e32 v14, v71, v158
	v_fmac_f32_e32 v15, v71, v159
	v_lshl_add_u32 v161, v23, 7, v160
	global_load_dwordx4 v[108:111], v161, s[14:15]
	s_waitcnt vmcnt(23)
	v_cvt_pk_f32_fp8_e32 v[144:145], v112
	v_cvt_pk_f32_fp8_sdwa v[146:147], v112 src0_sel:WORD_1
	v_cvt_pk_f32_fp8_e32 v[148:149], v113
	v_cvt_pk_f32_fp8_sdwa v[150:151], v113 src0_sel:WORD_1
	v_cvt_pk_f32_fp8_e32 v[152:153], v114
	v_cvt_pk_f32_fp8_sdwa v[154:155], v114 src0_sel:WORD_1
	v_cvt_pk_f32_fp8_e32 v[156:157], v115
	v_cvt_pk_f32_fp8_sdwa v[158:159], v115 src0_sel:WORD_1
	v_fmac_f32_e32 v0, v72, v144
	v_fmac_f32_e32 v1, v72, v145
	v_fmac_f32_e32 v2, v72, v146
	v_fmac_f32_e32 v3, v72, v147
	v_fmac_f32_e32 v4, v72, v148
	v_fmac_f32_e32 v5, v72, v149
	v_fmac_f32_e32 v6, v72, v150
	v_fmac_f32_e32 v7, v72, v151
	v_fmac_f32_e32 v8, v72, v152
	v_fmac_f32_e32 v9, v72, v153
	v_fmac_f32_e32 v10, v72, v154
	v_fmac_f32_e32 v11, v72, v155
	v_fmac_f32_e32 v12, v72, v156
	v_fmac_f32_e32 v13, v72, v157
	v_fmac_f32_e32 v14, v72, v158
	v_fmac_f32_e32 v15, v72, v159
	v_lshl_add_u32 v161, v24, 7, v160
	global_load_dwordx4 v[112:115], v161, s[14:15]
	s_waitcnt vmcnt(23)
	v_cvt_pk_f32_fp8_e32 v[144:145], v116
	v_cvt_pk_f32_fp8_sdwa v[146:147], v116 src0_sel:WORD_1
	v_cvt_pk_f32_fp8_e32 v[148:149], v117
	v_cvt_pk_f32_fp8_sdwa v[150:151], v117 src0_sel:WORD_1
	v_cvt_pk_f32_fp8_e32 v[152:153], v118
	v_cvt_pk_f32_fp8_sdwa v[154:155], v118 src0_sel:WORD_1
	v_cvt_pk_f32_fp8_e32 v[156:157], v119
	v_cvt_pk_f32_fp8_sdwa v[158:159], v119 src0_sel:WORD_1
	v_fmac_f32_e32 v0, v73, v144
	v_fmac_f32_e32 v1, v73, v145
	v_fmac_f32_e32 v2, v73, v146
	v_fmac_f32_e32 v3, v73, v147
	v_fmac_f32_e32 v4, v73, v148
	v_fmac_f32_e32 v5, v73, v149
	v_fmac_f32_e32 v6, v73, v150
	v_fmac_f32_e32 v7, v73, v151
	v_fmac_f32_e32 v8, v73, v152
	v_fmac_f32_e32 v9, v73, v153
	v_fmac_f32_e32 v10, v73, v154
	v_fmac_f32_e32 v11, v73, v155
	v_fmac_f32_e32 v12, v73, v156
	v_fmac_f32_e32 v13, v73, v157
	v_fmac_f32_e32 v14, v73, v158
	v_fmac_f32_e32 v15, v73, v159
	v_lshl_add_u32 v161, v25, 7, v160
	global_load_dwordx4 v[116:119], v161, s[14:15]
	s_waitcnt vmcnt(23)
; DI void phase_peer_b(const Params& p, int layer, const float* gnext, bool last) {
;     ...
; #pragma unroll
;       for (int j = 0; j < 16; ++j) {
;         const int e = bt * 16 + j;
;         const float wj = __int_as_float(__builtin_amdgcn_readlane(__float_as_int(e < 64 ? w0 : w1), e & 63));
; #pragma unroll
;         for (int w = 0; w < 4; ++w) {
;           const f32x2 lo = __builtin_amdgcn_cvt_pk_f32_fp8((int)vr[j][w], false);
;           const f32x2 hi = __builtin_amdgcn_cvt_pk_f32_fp8((int)vr[j][w], true);
;           acc[4 * w] += wj * lo[0]; acc[4 * w + 1] += wj * lo[1]; acc[4 * w + 2] += wj * hi[0]; acc[4 * w + 3] += wj * hi[1];
;         }
;       }
;     }
;       float* hp = hbuf + row * DM;
;       float hn[16];
; #pragma unroll
;       for (int q = 0; q < 2; ++q) {
;         const float4 a = *(const float4*)(hp + lane * 16 + q * 8);
;         const float4 bq = *(const float4*)(hp + lane * 16 + q * 8 + 4);
;         hn[q * 8 + 0] = a.x + acc[q * 8 + 0]; hn[q * 8 + 1] = a.y + acc[q * 8 + 1]; hn[q * 8 + 2] = a.z + acc[q * 8 + 2]; hn[q * 8 + 3] = a.w + acc[q * 8 + 3];
;         hn[q * 8 + 4] = bq.x + acc[q * 8 + 4]; hn[q * 8 + 5] = bq.y + acc[q * 8 + 5]; hn[q * 8 + 6] = bq.z + acc[q * 8 + 6]; hn[q * 8 + 7] = bq.w + acc[q * 8 + 7];
;       }
;       float ss = 0.f;
; #pragma unroll
;       for (int i = 0; i < 16; ++i) ss += hn[i] * hn[i];
;       ss = wave_sum(ss);
;       const float rn = rsqrtf(ss * (1.f / 1024.f) + 1e-6f);
;       float y[16];
; #pragma unroll
;       for (int q = 0; q < 2; ++q) {
;         const float4 ga = *(const float4*)(gnext + lane * 16 + q * 8);
;         const float4 gb = *(const float4*)(gnext + lane * 16 + q * 8 + 4);
;         y[q * 8 + 0] = hn[q * 8 + 0] * rn * ga.x; y[q * 8 + 1] = hn[q * 8 + 1] * rn * ga.y; y[q * 8 + 2] = hn[q * 8 + 2] * rn * ga.z; y[q * 8 + 3] = hn[q * 8 + 3] * rn * ga.w;
;         y[q * 8 + 4] = hn[q * 8 + 4] * rn * gb.x; y[q * 8 + 5] = hn[q * 8 + 5] * rn * gb.y; y[q * 8 + 6] = hn[q * 8 + 6] * rn * gb.z; y[q * 8 + 7] = hn[q * 8 + 7] * rn * gb.w;
;       }
;       if (!last) {
; #pragma unroll
;         for (int q = 0; q < 2; ++q) {
;           *(float4*)(hp + lane * 16 + q * 8) = make_float4(hn[q * 8 + 0], hn[q * 8 + 1], hn[q * 8 + 2], hn[q * 8 + 3]);
;           *(float4*)(hp + lane * 16 + q * 8 + 4) = make_float4(hn[q * 8 + 4], hn[q * 8 + 5], hn[q * 8 + 6], hn[q * 8 + 7]);
	v_cvt_pk_f32_fp8_e32 v[144:145], v120
	v_cvt_pk_f32_fp8_sdwa v[146:147], v120 src0_sel:WORD_1
	v_cvt_pk_f32_fp8_e32 v[148:149], v121
	v_cvt_pk_f32_fp8_sdwa v[150:151], v121 src0_sel:WORD_1
	v_cvt_pk_f32_fp8_e32 v[152:153], v122
	v_cvt_pk_f32_fp8_sdwa v[154:155], v122 src0_sel:WORD_1
	v_cvt_pk_f32_fp8_e32 v[156:157], v123
	v_cvt_pk_f32_fp8_sdwa v[158:159], v123 src0_sel:WORD_1
	v_fmac_f32_e32 v0, v74, v144
	v_fmac_f32_e32 v1, v74, v145
	v_fmac_f32_e32 v2, v74, v146
	v_fmac_f32_e32 v3, v74, v147
	v_fmac_f32_e32 v4, v74, v148
	v_fmac_f32_e32 v5, v74, v149
	v_fmac_f32_e32 v6, v74, v150
	v_fmac_f32_e32 v7, v74, v151
	v_fmac_f32_e32 v8, v74, v152
	v_fmac_f32_e32 v9, v74, v153
	v_fmac_f32_e32 v10, v74, v154
	v_fmac_f32_e32 v11, v74, v155
	v_fmac_f32_e32 v12, v74, v156
	v_fmac_f32_e32 v13, v74, v157
	v_fmac_f32_e32 v14, v74, v158
	v_fmac_f32_e32 v15, v74, v159
	v_lshl_add_u32 v161, v26, 7, v160
	global_load_dwordx4 v[120:123], v161, s[14:15]
	s_waitcnt vmcnt(23)
	v_cvt_pk_f32_fp8_e32 v[144:145], v124
	v_cvt_pk_f32_fp8_sdwa v[146:147], v124 src0_sel:WORD_1
	v_cvt_pk_f32_fp8_e32 v[148:149], v125
	v_cvt_pk_f32_fp8_sdwa v[150:151], v125 src0_sel:WORD_1
	v_cvt_pk_f32_fp8_e32 v[152:153], v126
	v_cvt_pk_f32_fp8_sdwa v[154:155], v126 src0_sel:WORD_1
	v_cvt_pk_f32_fp8_e32 v[156:157], v127
	v_cvt_pk_f32_fp8_sdwa v[158:159], v127 src0_sel:WORD_1
	v_fmac_f32_e32 v0, v75, v144
	v_fmac_f32_e32 v1, v75, v145
	v_fmac_f32_e32 v2, v75, v146
	v_fmac_f32_e32 v3, v75, v147
	v_fmac_f32_e32 v4, v75, v148
	v_fmac_f32_e32 v5, v75, v149
	v_fmac_f32_e32 v6, v75, v150
	v_fmac_f32_e32 v7, v75, v151
	v_fmac_f32_e32 v8, v75, v152
	v_fmac_f32_e32 v9, v75, v153
	v_fmac_f32_e32 v10, v75, v154
	v_fmac_f32_e32 v11, v75, v155
	v_fmac_f32_e32 v12, v75, v156
	v_fmac_f32_e32 v13, v75, v157
	v_fmac_f32_e32 v14, v75, v158
	v_fmac_f32_e32 v15, v75, v159
	v_lshl_add_u32 v161, v27, 7, v160
	global_load_dwordx4 v[124:127], v161, s[14:15]
	s_waitcnt vmcnt(23)
	v_cvt_pk_f32_fp8_e32 v[144:145], v128
	v_cvt_pk_f32_fp8_sdwa v[146:147], v128 src0_sel:WORD_1
	v_cvt_pk_f32_fp8_e32 v[148:149], v129
	v_cvt_pk_f32_fp8_sdwa v[150:151], v129 src0_sel:WORD_1
	v_cvt_pk_f32_fp8_e32 v[152:153], v130
	v_cvt_pk_f32_fp8_sdwa v[154:155], v130 src0_sel:WORD_1
	v_cvt_pk_f32_fp8_e32 v[156:157], v131
	v_cvt_pk_f32_fp8_sdwa v[158:159], v131 src0_sel:WORD_1
	v_fmac_f32_e32 v0, v76, v144
	v_fmac_f32_e32 v1, v76, v145
	v_fmac_f32_e32 v2, v76, v146
	v_fmac_f32_e32 v3, v76, v147
	v_fmac_f32_e32 v4, v76, v148
	v_fmac_f32_e32 v5, v76, v149
	v_fmac_f32_e32 v6, v76, v150
	v_fmac_f32_e32 v7, v76, v151
	v_fmac_f32_e32 v8, v76, v152
	v_fmac_f32_e32 v9, v76, v153
	v_fmac_f32_e32 v10, v76, v154
	v_fmac_f32_e32 v11, v76, v155
	v_fmac_f32_e32 v12, v76, v156
	v_fmac_f32_e32 v13, v76, v157
	v_fmac_f32_e32 v14, v76, v158
	v_fmac_f32_e32 v15, v76, v159
	v_lshl_add_u32 v161, v28, 7, v160
	global_load_dwordx4 v[128:131], v161, s[14:15]
	s_waitcnt vmcnt(23)
	v_cvt_pk_f32_fp8_e32 v[144:145], v132
	v_cvt_pk_f32_fp8_sdwa v[146:147], v132 src0_sel:WORD_1
	v_cvt_pk_f32_fp8_e32 v[148:149], v133
	v_cvt_pk_f32_fp8_sdwa v[150:151], v133 src0_sel:WORD_1
	v_cvt_pk_f32_fp8_e32 v[152:153], v134
	v_cvt_pk_f32_fp8_sdwa v[154:155], v134 src0_sel:WORD_1
	v_cvt_pk_f32_fp8_e32 v[156:157], v135
	v_cvt_pk_f32_fp8_sdwa v[158:159], v135 src0_sel:WORD_1
	v_fmac_f32_e32 v0, v77, v144
	v_fmac_f32_e32 v1, v77, v145
	v_fmac_f32_e32 v2, v77, v146
	v_fmac_f32_e32 v3, v77, v147
	v_fmac_f32_e32 v4, v77, v148
	v_fmac_f32_e32 v5, v77, v149
	v_fmac_f32_e32 v6, v77, v150
	v_fmac_f32_e32 v7, v77, v151
	v_fmac_f32_e32 v8, v77, v152
	v_fmac_f32_e32 v9, v77, v153
	v_fmac_f32_e32 v10, v77, v154
	v_fmac_f32_e32 v11, v77, v155
	v_fmac_f32_e32 v12, v77, v156
	v_fmac_f32_e32 v13, v77, v157
	v_fmac_f32_e32 v14, v77, v158
	v_fmac_f32_e32 v15, v77, v159
	v_lshl_add_u32 v161, v29, 7, v160
	global_load_dwordx4 v[132:135], v161, s[14:15]
	s_waitcnt vmcnt(23)
	v_cvt_pk_f32_fp8_e32 v[144:145], v136
	v_cvt_pk_f32_fp8_sdwa v[146:147], v136 src0_sel:WORD_1
	v_cvt_pk_f32_fp8_e32 v[148:149], v137
	v_cvt_pk_f32_fp8_sdwa v[150:151], v137 src0_sel:WORD_1
	v_cvt_pk_f32_fp8_e32 v[152:153], v138
	v_cvt_pk_f32_fp8_sdwa v[154:155], v138 src0_sel:WORD_1
	v_cvt_pk_f32_fp8_e32 v[156:157], v139
	v_cvt_pk_f32_fp8_sdwa v[158:159], v139 src0_sel:WORD_1
	v_fmac_f32_e32 v0, v78, v144
	v_fmac_f32_e32 v1, v78, v145
	v_fmac_f32_e32 v2, v78, v146
	v_fmac_f32_e32 v3, v78, v147
	v_fmac_f32_e32 v4, v78, v148
	v_fmac_f32_e32 v5, v78, v149
	v_fmac_f32_e32 v6, v78, v150
	v_fmac_f32_e32 v7, v78, v151
	v_fmac_f32_e32 v8, v78, v152
	v_fmac_f32_e32 v9, v78, v153
	v_fmac_f32_e32 v10, v78, v154
	v_fmac_f32_e32 v11, v78, v155
	v_fmac_f32_e32 v12, v78, v156
	v_fmac_f32_e32 v13, v78, v157
	v_fmac_f32_e32 v14, v78, v158
	v_fmac_f32_e32 v15, v78, v159
	v_lshl_add_u32 v161, v30, 7, v160
	global_load_dwordx4 v[136:139], v161, s[14:15]
	s_waitcnt vmcnt(23)
	v_cvt_pk_f32_fp8_e32 v[144:145], v140
	v_cvt_pk_f32_fp8_sdwa v[146:147], v140 src0_sel:WORD_1
	v_cvt_pk_f32_fp8_e32 v[148:149], v141
	v_cvt_pk_f32_fp8_sdwa v[150:151], v141 src0_sel:WORD_1
	v_cvt_pk_f32_fp8_e32 v[152:153], v142
	v_cvt_pk_f32_fp8_sdwa v[154:155], v142 src0_sel:WORD_1
	v_cvt_pk_f32_fp8_e32 v[156:157], v143
	v_cvt_pk_f32_fp8_sdwa v[158:159], v143 src0_sel:WORD_1
	v_fmac_f32_e32 v0, v79, v144
	v_fmac_f32_e32 v1, v79, v145
	v_fmac_f32_e32 v2, v79, v146
	v_fmac_f32_e32 v3, v79, v147
	v_fmac_f32_e32 v4, v79, v148
	v_fmac_f32_e32 v5, v79, v149
	v_fmac_f32_e32 v6, v79, v150
	v_fmac_f32_e32 v7, v79, v151
	v_fmac_f32_e32 v8, v79, v152
	v_fmac_f32_e32 v9, v79, v153
	v_fmac_f32_e32 v10, v79, v154
	v_fmac_f32_e32 v11, v79, v155
	v_fmac_f32_e32 v12, v79, v156
	v_fmac_f32_e32 v13, v79, v157
	v_fmac_f32_e32 v14, v79, v158
	v_fmac_f32_e32 v15, v79, v159
	v_lshl_add_u32 v161, v31, 7, v160
	global_load_dwordx4 v[140:143], v161, s[14:15]
	s_waitcnt vmcnt(20)
	v_add_f32_e32 v230, v230, v0
	v_add_f32_e32 v231, v231, v1
	v_add_f32_e32 v232, v232, v2
	v_add_f32_e32 v233, v233, v3
	v_add_f32_e32 v234, v234, v4
	v_add_f32_e32 v235, v235, v5
	v_add_f32_e32 v236, v236, v6
	v_add_f32_e32 v237, v237, v7
	v_add_f32_e32 v238, v238, v8
	v_add_f32_e32 v239, v239, v9
	v_add_f32_e32 v240, v240, v10
	v_add_f32_e32 v241, v241, v11
	v_add_f32_e32 v242, v242, v12
	v_add_f32_e32 v243, v243, v13
	v_add_f32_e32 v244, v244, v14
	v_add_f32_e32 v245, v245, v15
	global_store_dwordx4 v164, v[230:233], s[20:21]
	global_store_dwordx4 v164, v[234:237], s[20:21] offset:16
	global_store_dwordx4 v164, v[238:241], s[20:21] offset:32
	global_store_dwordx4 v164, v[242:245], s[20:21] offset:48
	s_add_u32 s22, s22, s23
	s_cmpk_lt_u32 s22, 0x2010
	s_cbranch_scc1 .Lpv0_item

; DI void phase_peer_b(const Params& p, int layer, const float* gnext, bool last) {
;   const int tid = threadIdx.x, lane = tid & 63, wave = tid >> 6;
;   const float* wbuf = (const float*)(p.ws + OFF_R + R_WBUF);
;   const int* ibuf = (const int*)(p.ws + OFF_R + R_IBUF);
;   u16* xnw = (u16*)(p.ws + OFF_XN);
;   float* hbuf = (float*)(p.ws + OFF_H);
;   const unsigned char* EV = (const unsigned char*)(p.ws + OFF_EXP) + (size_t)(layer * 2 + 1) * NEXP * DM;
; #pragma unroll 1
;   for (size_t row = (size_t)blockIdx.x * 4 + wave; row < (size_t)T; row += (size_t)gridDim.x * 4) {
;     const int i0 = ibuf[row * 128 + lane], i1 = ibuf[row * 128 + 64 + lane];
;     const float w0 = wbuf[row * 128 + lane], w1 = wbuf[row * 128 + 64 + lane];
;     float acc[16];
; #pragma unroll
;     for (int i = 0; i < 16; ++i) acc[i] = 0.f;
; #pragma unroll 1
;     for (int bt = 0; bt < 8; ++bt) {
;       u32x4 vr[16];
; #pragma unroll
;       for (int j = 0; j < 16; ++j) {
;         const int e = bt * 16 + j;
;         const int eidx = __builtin_amdgcn_readlane(e < 64 ? i0 : i1, e & 63);
;         vr[j] = *(const u32x4*)(EV + (size_t)eidx * DM + lane * 16);
.LBB0_722:
	s_or_b64 exec, exec, s[2:3]
	s_barrier
	s_mov_b64 exec, -1
	v_mbcnt_lo_u32_b32 v165, -1, 0
	v_mbcnt_hi_u32_b32 v165, -1, v165
	v_and_b32_e32 v160, 7, v165
	v_lshlrev_b32_e32 v167, 6, v160
	v_lshlrev_b32_e32 v160, 4, v160
	v_lshrrev_b32_e32 v166, 3, v165
	s_and_b32 s24, s95, 7
	s_lshr_b32 s22, s95, 3
	s_lshr_b32 s23, s70, 3
	s_cmp_ge_u32 s22, s23
	s_cbranch_scc1 .Lpv1_end
	s_lshl_b32 s22, s22, 2
	s_add_u32 s22, s22, s94
	s_lshl_b32 s23, s23, 2
	s_lshl_b32 s25, s24, 21
	s_add_u32 s25, s25, 0x1b0c0000
	s_add_u32 s14, s68, s25
	s_addc_u32 s15, s69, 0
	s_add_u32 s16, s68, 0x2b4b0800
	s_addc_u32 s17, s69, 0
	s_add_u32 s18, s68, 0x294a0800
	s_addc_u32 s19, s69, 0
	s_lshl_b32 s25, s24, 9
	s_add_u32 s20, s68, s25
	s_addc_u32 s21, s69, 0
	s_mul_i32 s25, s94, 8448
	v_lshrrev_b32_e32 v162, 5, v165
	v_mul_u32_u24_e32 v162, 528, v162
	v_and_b32_e32 v161, 31, v165
	v_lshl_add_u32 v162, v161, 4, v162
	v_add_u32_e32 v162, s25, v162
	v_mul_u32_u24_e32 v163, 528, v166
	v_add_u32_e32 v163, s25, v163
	v_lshlrev_b32_e32 v168, 4, v165
	s_cmpk_ge_u32 s22, 0x2010
	s_cbranch_scc1 .Lpv1_end
	s_lshl_b32 s24, s22, 12
	v_add_u32_e32 v172, s24, v168
	global_load_dwordx4 v[200:203], v172, s[16:17]
	global_load_dwordx4 v[204:207], v172, s[16:17] offset:1024
	global_load_dwordx4 v[208:211], v172, s[16:17] offset:2048
	global_load_dwordx4 v[246:249], v172, s[16:17] offset:3072
	s_waitcnt vmcnt(0)
	ds_write_b128 v162, v[200:203]
	ds_write_b128 v162, v[204:207] offset:1056
	ds_write_b128 v162, v[208:211] offset:2112
	ds_write_b128 v162, v[246:249] offset:3168
	s_waitcnt lgkmcnt(0)
	ds_read_b128 v[16:19], v163
	ds_read_b128 v[20:23], v163 offset:16
	ds_read_b128 v[24:27], v163 offset:32
	ds_read_b128 v[28:31], v163 offset:48
	ds_read_b128 v[32:35], v163 offset:64
	ds_read_b128 v[36:39], v163 offset:80
	ds_read_b128 v[40:43], v163 offset:96
	ds_read_b128 v[44:47], v163 offset:112
	global_load_dwordx4 v[48:51], v172, s[18:19]
	global_load_dwordx4 v[52:55], v172, s[18:19] offset:1024
	global_load_dwordx4 v[56:59], v172, s[18:19] offset:2048
	global_load_dwordx4 v[60:63], v172, s[18:19] offset:3072
	s_waitcnt lgkmcnt(0)
	v_lshl_add_u32 v161, v16, 7, v160
	global_load_dwordx4 v[80:83], v161, s[14:15]
	v_lshl_add_u32 v161, v17, 7, v160
	global_load_dwordx4 v[84:87], v161, s[14:15]
	v_lshl_add_u32 v161, v18, 7, v160
	global_load_dwordx4 v[88:91], v161, s[14:15]
	v_lshl_add_u32 v161, v19, 7, v160
	global_load_dwordx4 v[92:95], v161, s[14:15]
	v_lshl_add_u32 v161, v20, 7, v160
	global_load_dwordx4 v[96:99], v161, s[14:15]
	v_lshl_add_u32 v161, v21, 7, v160
	global_load_dwordx4 v[100:103], v161, s[14:15]
	v_lshl_add_u32 v161, v22, 7, v160
	global_load_dwordx4 v[104:107], v161, s[14:15]
	v_lshl_add_u32 v161, v23, 7, v160
	global_load_dwordx4 v[108:111], v161, s[14:15]
	v_lshl_add_u32 v161, v24, 7, v160
	global_load_dwordx4 v[112:115], v161, s[14:15]
	v_lshl_add_u32 v161, v25, 7, v160
	global_load_dwordx4 v[116:119], v161, s[14:15]
	v_lshl_add_u32 v161, v26, 7, v160
	global_load_dwordx4 v[120:123], v161, s[14:15]
	v_lshl_add_u32 v161, v27, 7, v160
	global_load_dwordx4 v[124:127], v161, s[14:15]
	v_lshl_add_u32 v161, v28, 7, v160
	global_load_dwordx4 v[128:131], v161, s[14:15]
	v_lshl_add_u32 v161, v29, 7, v160
	global_load_dwordx4 v[132:135], v161, s[14:15]
	v_lshl_add_u32 v161, v30, 7, v160
	global_load_dwordx4 v[136:139], v161, s[14:15]
	v_lshl_add_u32 v161, v31, 7, v160
	global_load_dwordx4 v[140:143], v161, s[14:15]
